# s_setprio flips removed from the eight GEMM K-loops (loader wave has no VALU left to arbitrate against)
# speedup vs baseline: 1.0318x; 1.0029x over previous
.LBB0_279:
	s_add_u32 s12, s10, 0xfffc0080
	s_addc_u32 s13, s11, -1
	s_add_i32 s19, 0, 0x10000
	v_add_u32_e32 v140, s19, v188
	ds_read_b128 v[120:123], v140
	ds_read_b128 v[124:127], v140 offset:1024
	ds_read_b128 v[136:139], v140 offset:2048
	ds_read_b128 v[140:143], v140 offset:3072
	s_cmp_eq_u32 s18, 12
	s_cselect_b32 s15, s0, s13
	s_cselect_b32 s14, s1, s12
	s_cselect_b32 s13, s7, s17
	s_cselect_b32 s12, s9, s16
	s_add_i32 m0, s68, 0xc000
	ds_read_b128 v[144:147], v189
	ds_read_b128 v[148:151], v189 offset:1024
	ds_read_b128 v[152:155], v189 offset:2048
	ds_read_b128 v[156:159], v189 offset:3072
	ds_read_b128 v[168:171], v189 offset:4096
	ds_read_b128 v[172:175], v189 offset:5120
	ds_read_b128 v[176:179], v189 offset:6144
	ds_read_b128 v[180:183], v189 offset:7168
	global_load_lds_dwordx4 v166, s[10:11]
	s_add_i32 m0, s68, 0xe000
	s_nop 0
	global_load_lds_dwordx4 v164, s[10:11]
	s_waitcnt lgkmcnt(8)
	s_barrier
	s_waitcnt lgkmcnt(0)
	v_mfma_f32_16x16x32_bf16 v[132:135], v[120:123], v[144:147], v[132:135]
	v_mfma_f32_16x16x32_bf16 v[128:131], v[136:139], v[144:147], v[128:131]
	v_mfma_f32_16x16x32_bf16 v[108:111], v[120:123], v[152:155], v[108:111]
	v_mfma_f32_16x16x32_bf16 v[104:107], v[136:139], v[152:155], v[104:107]
	v_mfma_f32_16x16x32_bf16 v[92:95], v[120:123], v[168:171], v[92:95]
	v_mfma_f32_16x16x32_bf16 v[88:91], v[136:139], v[168:171], v[88:91]
	v_mfma_f32_16x16x32_bf16 v[76:79], v[120:123], v[176:179], v[76:79]
	v_mfma_f32_16x16x32_bf16 v[72:75], v[136:139], v[176:179], v[72:75]
	v_mfma_f32_16x16x32_bf16 v[132:135], v[124:127], v[148:151], v[132:135]
	v_mfma_f32_16x16x32_bf16 v[128:131], v[140:143], v[148:151], v[128:131]
	v_mfma_f32_16x16x32_bf16 v[108:111], v[124:127], v[156:159], v[108:111]
	v_mfma_f32_16x16x32_bf16 v[104:107], v[140:143], v[156:159], v[104:107]
	v_mfma_f32_16x16x32_bf16 v[92:95], v[124:127], v[172:175], v[92:95]
	v_mfma_f32_16x16x32_bf16 v[88:91], v[140:143], v[172:175], v[88:91]
	v_mfma_f32_16x16x32_bf16 v[76:79], v[124:127], v[180:183], v[76:79]
	v_mfma_f32_16x16x32_bf16 v[72:75], v[140:143], v[180:183], v[72:75]
	s_barrier
	s_add_i32 s33, 0, 0x14000
	v_add_u32_e32 v190, s33, v188
	s_add_i32 s19, s19, s67
	ds_read_b128 v[184:187], v190
	ds_read_b128 v[198:201], v190 offset:1024
	ds_read_b128 v[206:209], v190 offset:2048
	ds_read_b128 v[210:213], v190 offset:3072
	s_mov_b32 m0, s19
	s_nop 0
	global_load_lds_dwordx4 v160, s[12:13]
	s_add_i32 m0, s19, 0x2000
	s_nop 0
	global_load_lds_dwordx4 v162, s[12:13]
	s_barrier
	s_waitcnt lgkmcnt(0)
	v_mfma_f32_16x16x32_bf16 v[116:119], v[184:187], v[144:147], v[116:119]
	v_mfma_f32_16x16x32_bf16 v[112:115], v[206:209], v[144:147], v[112:115]
	v_mfma_f32_16x16x32_bf16 v[100:103], v[184:187], v[152:155], v[100:103]
	v_mfma_f32_16x16x32_bf16 v[96:99], v[206:209], v[152:155], v[96:99]
	v_mfma_f32_16x16x32_bf16 v[84:87], v[184:187], v[168:171], v[84:87]
	v_mfma_f32_16x16x32_bf16 v[80:83], v[206:209], v[168:171], v[80:83]
	v_mfma_f32_16x16x32_bf16 v[68:71], v[184:187], v[176:179], v[68:71]
	v_mfma_f32_16x16x32_bf16 v[64:67], v[206:209], v[176:179], v[64:67]
	v_mfma_f32_16x16x32_bf16 v[116:119], v[198:201], v[148:151], v[116:119]
	v_mfma_f32_16x16x32_bf16 v[112:115], v[210:213], v[148:151], v[112:115]
	v_mfma_f32_16x16x32_bf16 v[100:103], v[198:201], v[156:159], v[100:103]
	v_mfma_f32_16x16x32_bf16 v[96:99], v[210:213], v[156:159], v[96:99]
	v_mfma_f32_16x16x32_bf16 v[84:87], v[198:201], v[172:175], v[84:87]
	v_mfma_f32_16x16x32_bf16 v[80:83], v[210:213], v[172:175], v[80:83]
	v_mfma_f32_16x16x32_bf16 v[68:71], v[198:201], v[180:183], v[68:71]
	v_mfma_f32_16x16x32_bf16 v[64:67], v[210:213], v[180:183], v[64:67]
	s_mov_b32 m0, s68
	s_add_u32 vcc_lo, s14, 0x80
	s_addc_u32 vcc_hi, s15, 0
	s_barrier
	ds_read_b128 v[144:147], v189 offset:16384
	ds_read_b128 v[148:151], v189 offset:17408
	ds_read_b128 v[152:155], v189 offset:18432
	ds_read_b128 v[156:159], v189 offset:19456
	ds_read_b128 v[168:171], v189 offset:20480
	ds_read_b128 v[172:175], v189 offset:21504
	ds_read_b128 v[176:179], v189 offset:22528
	ds_read_b128 v[180:183], v189 offset:23552
	global_load_lds_dwordx4 v160, s[14:15]
	s_mov_b32 m0, s69
	s_nop 0
	global_load_lds_dwordx4 v162, s[14:15]
	s_barrier
	s_waitcnt lgkmcnt(0)
	v_mfma_f32_16x16x32_bf16 v[60:63], v[120:123], v[144:147], v[60:63]
	v_mfma_f32_16x16x32_bf16 v[56:59], v[136:139], v[144:147], v[56:59]
	v_mfma_f32_16x16x32_bf16 v[44:47], v[120:123], v[152:155], v[44:47]
	v_mfma_f32_16x16x32_bf16 v[40:43], v[136:139], v[152:155], v[40:43]
	v_mfma_f32_16x16x32_bf16 v[28:31], v[120:123], v[168:171], v[28:31]
	v_mfma_f32_16x16x32_bf16 v[24:27], v[136:139], v[168:171], v[24:27]
	v_mfma_f32_16x16x32_bf16 v[12:15], v[120:123], v[176:179], v[12:15]
	v_mfma_f32_16x16x32_bf16 v[8:11], v[136:139], v[176:179], v[8:11]
	v_mfma_f32_16x16x32_bf16 v[60:63], v[124:127], v[148:151], v[60:63]
	v_mfma_f32_16x16x32_bf16 v[56:59], v[140:143], v[148:151], v[56:59]
	v_mfma_f32_16x16x32_bf16 v[44:47], v[124:127], v[156:159], v[44:47]
	v_mfma_f32_16x16x32_bf16 v[40:43], v[140:143], v[156:159], v[40:43]
	v_mfma_f32_16x16x32_bf16 v[28:31], v[124:127], v[172:175], v[28:31]
	v_mfma_f32_16x16x32_bf16 v[24:27], v[140:143], v[172:175], v[24:27]
	v_mfma_f32_16x16x32_bf16 v[12:15], v[124:127], v[180:183], v[12:15]
	v_mfma_f32_16x16x32_bf16 v[8:11], v[140:143], v[180:183], v[8:11]
	s_barrier
	s_add_u32 s44, s12, 0x40000
	s_addc_u32 s45, s13, 0
	s_add_i32 s19, s33, s67
	s_mov_b32 m0, s19
	s_nop 0
	global_load_lds_dwordx4 v160, s[44:45]
	s_add_i32 m0, s19, 0x2000
	s_nop 0
	global_load_lds_dwordx4 v162, s[44:45]
	s_waitcnt vmcnt(6)
	s_barrier
	v_mfma_f32_16x16x32_bf16 v[52:55], v[184:187], v[144:147], v[52:55]
	v_mfma_f32_16x16x32_bf16 v[48:51], v[206:209], v[144:147], v[48:51]
	v_mfma_f32_16x16x32_bf16 v[36:39], v[184:187], v[152:155], v[36:39]
	v_mfma_f32_16x16x32_bf16 v[32:35], v[206:209], v[152:155], v[32:35]
	v_mfma_f32_16x16x32_bf16 v[20:23], v[184:187], v[168:171], v[20:23]
	v_mfma_f32_16x16x32_bf16 v[16:19], v[206:209], v[168:171], v[16:19]
	v_mfma_f32_16x16x32_bf16 v[4:7], v[184:187], v[176:179], v[4:7]
	v_mfma_f32_16x16x32_bf16 v[0:3], v[206:209], v[176:179], v[0:3]
	v_mfma_f32_16x16x32_bf16 v[52:55], v[198:201], v[148:151], v[52:55]
	v_mfma_f32_16x16x32_bf16 v[48:51], v[210:213], v[148:151], v[48:51]
	v_mfma_f32_16x16x32_bf16 v[36:39], v[198:201], v[156:159], v[36:39]
	v_mfma_f32_16x16x32_bf16 v[32:35], v[210:213], v[156:159], v[32:35]
	v_mfma_f32_16x16x32_bf16 v[20:23], v[198:201], v[172:175], v[20:23]
	v_mfma_f32_16x16x32_bf16 v[16:19], v[210:213], v[172:175], v[16:19]
	v_mfma_f32_16x16x32_bf16 v[4:7], v[198:201], v[180:183], v[4:7]
	v_mfma_f32_16x16x32_bf16 v[0:3], v[210:213], v[180:183], v[0:3]
	s_add_i32 s19, 0, 0x18000
	v_add_u32_e32 v140, s19, v188
	s_barrier
	ds_read_b128 v[120:123], v140
	ds_read_b128 v[124:127], v140 offset:1024
	ds_read_b128 v[136:139], v140 offset:2048
	ds_read_b128 v[140:143], v140 offset:3072
	s_add_u32 s14, s14, 0x40000
	s_addc_u32 s15, s15, 0
	s_mov_b32 m0, s72
	ds_read_b128 v[144:147], v189 offset:32768
	ds_read_b128 v[148:151], v189 offset:33792
	ds_read_b128 v[152:155], v189 offset:34816
	ds_read_b128 v[156:159], v189 offset:35840
	ds_read_b128 v[168:171], v189 offset:36864
	ds_read_b128 v[172:175], v189 offset:37888
	ds_read_b128 v[176:179], v189 offset:38912
	ds_read_b128 v[180:183], v189 offset:39936
	global_load_lds_dwordx4 v160, s[14:15]
	s_mov_b32 m0, s73
	s_nop 0
	global_load_lds_dwordx4 v162, s[14:15]
	s_waitcnt lgkmcnt(8)
	s_barrier
	s_waitcnt lgkmcnt(0)
	v_mfma_f32_16x16x32_bf16 v[132:135], v[120:123], v[144:147], v[132:135]
	v_mfma_f32_16x16x32_bf16 v[128:131], v[136:139], v[144:147], v[128:131]
	v_mfma_f32_16x16x32_bf16 v[108:111], v[120:123], v[152:155], v[108:111]
	v_mfma_f32_16x16x32_bf16 v[104:107], v[136:139], v[152:155], v[104:107]
	v_mfma_f32_16x16x32_bf16 v[92:95], v[120:123], v[168:171], v[92:95]
	v_mfma_f32_16x16x32_bf16 v[88:91], v[136:139], v[168:171], v[88:91]
	v_mfma_f32_16x16x32_bf16 v[76:79], v[120:123], v[176:179], v[76:79]
	v_mfma_f32_16x16x32_bf16 v[72:75], v[136:139], v[176:179], v[72:75]
	v_mfma_f32_16x16x32_bf16 v[132:135], v[124:127], v[148:151], v[132:135]
	v_mfma_f32_16x16x32_bf16 v[128:131], v[140:143], v[148:151], v[128:131]
	v_mfma_f32_16x16x32_bf16 v[108:111], v[124:127], v[156:159], v[108:111]
	v_mfma_f32_16x16x32_bf16 v[104:107], v[140:143], v[156:159], v[104:107]
	v_mfma_f32_16x16x32_bf16 v[92:95], v[124:127], v[172:175], v[92:95]
	v_mfma_f32_16x16x32_bf16 v[88:91], v[140:143], v[172:175], v[88:91]
	v_mfma_f32_16x16x32_bf16 v[76:79], v[124:127], v[180:183], v[76:79]
	v_mfma_f32_16x16x32_bf16 v[72:75], v[140:143], v[180:183], v[72:75]
	s_barrier
	s_add_i32 s14, 0, 0x1c000
	s_add_i32 s15, s19, s67
	v_add_u32_e32 v192, s14, v188
	s_add_u32 s100, s12, 0x80
	s_addc_u32 s101, s13, 0
	s_mov_b32 m0, s15
	ds_read_b128 v[184:187], v192
	ds_read_b128 v[198:201], v192 offset:1024
	ds_read_b128 v[206:209], v192 offset:2048
	ds_read_b128 v[210:213], v192 offset:3072
	global_load_lds_dwordx4 v160, s[100:101]
	s_add_i32 m0, s15, 0x2000
	s_nop 0
	global_load_lds_dwordx4 v162, s[100:101]
	s_barrier
	s_waitcnt lgkmcnt(0)
	v_mfma_f32_16x16x32_bf16 v[116:119], v[184:187], v[144:147], v[116:119]
	v_mfma_f32_16x16x32_bf16 v[112:115], v[206:209], v[144:147], v[112:115]
	v_mfma_f32_16x16x32_bf16 v[100:103], v[184:187], v[152:155], v[100:103]
	v_mfma_f32_16x16x32_bf16 v[96:99], v[206:209], v[152:155], v[96:99]
	v_mfma_f32_16x16x32_bf16 v[84:87], v[184:187], v[168:171], v[84:87]
	v_mfma_f32_16x16x32_bf16 v[80:83], v[206:209], v[168:171], v[80:83]
	v_mfma_f32_16x16x32_bf16 v[68:71], v[184:187], v[176:179], v[68:71]
	v_mfma_f32_16x16x32_bf16 v[64:67], v[206:209], v[176:179], v[64:67]
	v_mfma_f32_16x16x32_bf16 v[116:119], v[198:201], v[148:151], v[116:119]
	v_mfma_f32_16x16x32_bf16 v[112:115], v[210:213], v[148:151], v[112:115]
	v_mfma_f32_16x16x32_bf16 v[100:103], v[198:201], v[156:159], v[100:103]
	v_mfma_f32_16x16x32_bf16 v[96:99], v[210:213], v[156:159], v[96:99]
	v_mfma_f32_16x16x32_bf16 v[84:87], v[198:201], v[172:175], v[84:87]
	v_mfma_f32_16x16x32_bf16 v[80:83], v[210:213], v[172:175], v[80:83]
	v_mfma_f32_16x16x32_bf16 v[68:71], v[198:201], v[180:183], v[68:71]
	v_mfma_f32_16x16x32_bf16 v[64:67], v[210:213], v[180:183], v[64:67]
	s_mov_b32 m0, s74
	s_barrier
	ds_read_b128 v[144:147], v189 offset:49152
	ds_read_b128 v[148:151], v189 offset:50176
	ds_read_b128 v[152:155], v189 offset:51200
	ds_read_b128 v[156:159], v189 offset:52224
	ds_read_b128 v[168:171], v189 offset:53248
	ds_read_b128 v[172:175], v189 offset:54272
	ds_read_b128 v[176:179], v189 offset:55296
	ds_read_b128 v[180:183], v189 offset:56320
	global_load_lds_dwordx4 v160, vcc
	s_mov_b32 m0, s75
	s_nop 0
	global_load_lds_dwordx4 v162, vcc
	s_barrier
	s_waitcnt lgkmcnt(0)
	v_mfma_f32_16x16x32_bf16 v[60:63], v[120:123], v[144:147], v[60:63]
	v_mfma_f32_16x16x32_bf16 v[56:59], v[136:139], v[144:147], v[56:59]
	v_mfma_f32_16x16x32_bf16 v[44:47], v[120:123], v[152:155], v[44:47]
	v_mfma_f32_16x16x32_bf16 v[40:43], v[136:139], v[152:155], v[40:43]
	v_mfma_f32_16x16x32_bf16 v[28:31], v[120:123], v[168:171], v[28:31]
	v_mfma_f32_16x16x32_bf16 v[24:27], v[136:139], v[168:171], v[24:27]
	v_mfma_f32_16x16x32_bf16 v[12:15], v[120:123], v[176:179], v[12:15]
	v_mfma_f32_16x16x32_bf16 v[8:11], v[136:139], v[176:179], v[8:11]
	v_mfma_f32_16x16x32_bf16 v[60:63], v[124:127], v[148:151], v[60:63]
	v_mfma_f32_16x16x32_bf16 v[56:59], v[140:143], v[148:151], v[56:59]
	v_mfma_f32_16x16x32_bf16 v[44:47], v[124:127], v[156:159], v[44:47]
	v_mfma_f32_16x16x32_bf16 v[40:43], v[140:143], v[156:159], v[40:43]
	v_mfma_f32_16x16x32_bf16 v[28:31], v[124:127], v[172:175], v[28:31]
	v_mfma_f32_16x16x32_bf16 v[24:27], v[140:143], v[172:175], v[24:27]
	v_mfma_f32_16x16x32_bf16 v[12:15], v[124:127], v[180:183], v[12:15]
	v_mfma_f32_16x16x32_bf16 v[8:11], v[140:143], v[180:183], v[8:11]
	s_barrier
	s_add_u32 s12, s12, 0x40080
	s_addc_u32 s13, s13, 0
	s_add_i32 s14, s14, s67
	s_mov_b32 m0, s14
	s_nop 0
	global_load_lds_dwordx4 v160, s[12:13]
	s_add_i32 m0, s14, 0x2000
	s_nop 0
	global_load_lds_dwordx4 v162, s[12:13]
	s_waitcnt vmcnt(6)
	s_barrier
	v_mfma_f32_16x16x32_bf16 v[52:55], v[184:187], v[144:147], v[52:55]
	v_mfma_f32_16x16x32_bf16 v[48:51], v[206:209], v[144:147], v[48:51]
	v_mfma_f32_16x16x32_bf16 v[36:39], v[184:187], v[152:155], v[36:39]
	v_mfma_f32_16x16x32_bf16 v[32:35], v[206:209], v[152:155], v[32:35]
	v_mfma_f32_16x16x32_bf16 v[20:23], v[184:187], v[168:171], v[20:23]
	v_mfma_f32_16x16x32_bf16 v[16:19], v[206:209], v[168:171], v[16:19]
	v_mfma_f32_16x16x32_bf16 v[4:7], v[184:187], v[176:179], v[4:7]
	v_mfma_f32_16x16x32_bf16 v[0:3], v[206:209], v[176:179], v[0:3]
	v_mfma_f32_16x16x32_bf16 v[52:55], v[198:201], v[148:151], v[52:55]
	v_mfma_f32_16x16x32_bf16 v[48:51], v[210:213], v[148:151], v[48:51]
	v_mfma_f32_16x16x32_bf16 v[36:39], v[198:201], v[156:159], v[36:39]
	v_mfma_f32_16x16x32_bf16 v[32:35], v[210:213], v[156:159], v[32:35]
	v_mfma_f32_16x16x32_bf16 v[20:23], v[198:201], v[172:175], v[20:23]
	v_mfma_f32_16x16x32_bf16 v[16:19], v[210:213], v[172:175], v[16:19]
	v_mfma_f32_16x16x32_bf16 v[4:7], v[198:201], v[180:183], v[4:7]
	v_mfma_f32_16x16x32_bf16 v[0:3], v[210:213], v[180:183], v[0:3]
	s_add_i32 s18, s18, 2
	s_add_u32 s16, s16, 0x100
	s_addc_u32 s17, s17, 0
	s_add_u32 s10, s10, 0x100
	s_addc_u32 s11, s11, 0
	s_cmp_gt_u32 s18, 13
	s_barrier
	s_cbranch_scc0 .LBB0_279
	v_mov_b32_e32 v120, v252
	s_lshl_b32 s0, s8, 8
	v_readfirstlane_b32 s1, v120
	s_ashr_i32 s7, s1, 2
	s_andn2_b32 s7, s7, 63
	v_and_b32_e32 v121, 15, v120
	s_add_i32 s0, s7, s0
	v_or_b32_e32 v172, s0, v121
	v_ashrrev_i32_e32 v173, 31, v172
	v_lshl_add_u64 v[174:175], v[172:173], 2, s[34:35]
	global_load_dword v171, v[174:175], off
	s_lshr_b32 s1, s1, 1
	s_and_b32 s1, s1, 0x60
	s_lshl_b32 s6, s6, 8
	s_or_b32 s1, s1, s6
	v_lshrrev_b32_e32 v120, 2, v120
	s_cmpk_eq_i32 s1, 0x100
	v_and_b32_e32 v170, 12, v120
	s_movk_i32 s6, 0x4000
	v_mov_b32_e32 v120, 0x1fcf
	s_cselect_b64 s[8:9], -1, 0
	v_lshlrev_b32_e32 v168, 1, v170
	v_cmp_gt_i32_e64 s[10:11], s6, v172
	v_bitop3_b32 v169, s0, v120, v121 bitop3:0xc8
	v_mov_b32_e32 v144, 0
	s_and_b64 vcc, exec, s[8:9]
	v_mov_b32_e32 v152, 0
	v_mov_b32_e32 v153, 0
	v_mov_b32_e32 v154, 0
	v_mov_b32_e32 v155, 0
	v_mov_b32_e32 v156, 0
	v_mov_b32_e32 v157, 0
	v_mov_b32_e32 v158, 0
	v_mov_b32_e32 v159, 0
	s_cbranch_vccz .LBB0_282
	v_or_b32_e32 v120, 16, v169
	v_add_u32_e32 v121, 0x7ffc000, v172
	v_cndmask_b32_e64 v120, v121, v120, s[10:11]
	v_lshl_or_b32 v192, v120, 5, v168
	v_lshl_add_u64 v[120:121], v[192:193], 2, s[30:31]
	global_load_dwordx4 v[152:155], v[120:121], off
	global_load_dwordx4 v[156:159], v[120:121], off offset:16

.LBB0_402:
	s_add_u32 s20, s18, 0xfffc0080
	s_addc_u32 s21, s19, -1
	s_add_i32 s41, 0, 0x10000
	ds_read_b128 v[138:141], v218
	ds_read_b128 v[148:151], v218 offset:1024
	ds_read_b128 v[152:155], v218 offset:2048
	ds_read_b128 v[156:159], v218 offset:3072
	s_cmp_eq_u32 s40, 12
	s_cselect_b32 s23, s1, s21
	s_cselect_b32 s22, s9, s20
	s_cselect_b32 s21, s11, s39
	s_cselect_b32 s20, s33, s38
	s_add_i32 m0, s17, 0xc000
	ds_read_b128 v[160:163], v146
	ds_read_b128 v[164:167], v146 offset:1024
	ds_read_b128 v[168:171], v146 offset:2048
	ds_read_b128 v[172:175], v146 offset:3072
	ds_read_b128 v[176:179], v146 offset:4096
	ds_read_b128 v[180:183], v146 offset:5120
	ds_read_b128 v[184:187], v146 offset:6144
	ds_read_b128 v[188:191], v146 offset:7168
	global_load_lds_dwordx4 v136, s[18:19]
	s_add_i32 m0, s17, 0xe000
	s_nop 0
	global_load_lds_dwordx4 v134, s[18:19]
	s_waitcnt lgkmcnt(8)
	s_barrier
	s_waitcnt lgkmcnt(0)
	v_mfma_f32_16x16x32_bf16 v[124:127], v[138:141], v[160:163], v[124:127]
	v_mfma_f32_16x16x32_bf16 v[116:119], v[152:155], v[160:163], v[116:119]
	v_mfma_f32_16x16x32_bf16 v[108:111], v[138:141], v[168:171], v[108:111]
	v_mfma_f32_16x16x32_bf16 v[100:103], v[152:155], v[168:171], v[100:103]
	v_mfma_f32_16x16x32_bf16 v[92:95], v[138:141], v[176:179], v[92:95]
	v_mfma_f32_16x16x32_bf16 v[84:87], v[152:155], v[176:179], v[84:87]
	v_mfma_f32_16x16x32_bf16 v[76:79], v[138:141], v[184:187], v[76:79]
	v_mfma_f32_16x16x32_bf16 v[68:71], v[152:155], v[184:187], v[68:71]
	v_mfma_f32_16x16x32_bf16 v[124:127], v[148:151], v[164:167], v[124:127]
	v_mfma_f32_16x16x32_bf16 v[116:119], v[156:159], v[164:167], v[116:119]
	v_mfma_f32_16x16x32_bf16 v[108:111], v[148:151], v[172:175], v[108:111]
	v_mfma_f32_16x16x32_bf16 v[100:103], v[156:159], v[172:175], v[100:103]
	v_mfma_f32_16x16x32_bf16 v[92:95], v[148:151], v[180:183], v[92:95]
	v_mfma_f32_16x16x32_bf16 v[84:87], v[156:159], v[180:183], v[84:87]
	v_mfma_f32_16x16x32_bf16 v[76:79], v[148:151], v[188:191], v[76:79]
	v_mfma_f32_16x16x32_bf16 v[68:71], v[156:159], v[188:191], v[68:71]
	s_barrier
	s_add_i32 s44, 0, 0x14000
	s_add_i32 s41, s41, s28
	ds_read_b128 v[198:201], v219
	ds_read_b128 v[206:209], v219 offset:1024
	ds_read_b128 v[210:213], v219 offset:2048
	ds_read_b128 v[214:217], v219 offset:3072
	s_mov_b32 m0, s41
	s_nop 0
	global_load_lds_dwordx4 v192, s[20:21]
	s_add_i32 m0, s41, 0x2000
	s_nop 0
	global_load_lds_dwordx4 v128, s[20:21]
	s_barrier
	s_waitcnt lgkmcnt(0)
	v_mfma_f32_16x16x32_bf16 v[120:123], v[198:201], v[160:163], v[120:123]
	v_mfma_f32_16x16x32_bf16 v[112:115], v[210:213], v[160:163], v[112:115]
	v_mfma_f32_16x16x32_bf16 v[104:107], v[198:201], v[168:171], v[104:107]
	v_mfma_f32_16x16x32_bf16 v[96:99], v[210:213], v[168:171], v[96:99]
	v_mfma_f32_16x16x32_bf16 v[88:91], v[198:201], v[176:179], v[88:91]
	v_mfma_f32_16x16x32_bf16 v[80:83], v[210:213], v[176:179], v[80:83]
	v_mfma_f32_16x16x32_bf16 v[72:75], v[198:201], v[184:187], v[72:75]
	v_mfma_f32_16x16x32_bf16 v[64:67], v[210:213], v[184:187], v[64:67]
	v_mfma_f32_16x16x32_bf16 v[120:123], v[206:209], v[164:167], v[120:123]
	v_mfma_f32_16x16x32_bf16 v[112:115], v[214:217], v[164:167], v[112:115]
	v_mfma_f32_16x16x32_bf16 v[104:107], v[206:209], v[172:175], v[104:107]
	v_mfma_f32_16x16x32_bf16 v[96:99], v[214:217], v[172:175], v[96:99]
	v_mfma_f32_16x16x32_bf16 v[88:91], v[206:209], v[180:183], v[88:91]
	v_mfma_f32_16x16x32_bf16 v[80:83], v[214:217], v[180:183], v[80:83]
	v_mfma_f32_16x16x32_bf16 v[72:75], v[206:209], v[188:191], v[72:75]
	v_mfma_f32_16x16x32_bf16 v[64:67], v[214:217], v[188:191], v[64:67]
	s_mov_b32 m0, s17
	s_add_u32 vcc_lo, s22, 0x80
	s_addc_u32 vcc_hi, s23, 0
	s_barrier
	ds_read_b128 v[160:163], v146 offset:16384
	ds_read_b128 v[164:167], v146 offset:17408
	ds_read_b128 v[168:171], v146 offset:18432
	ds_read_b128 v[172:175], v146 offset:19456
	ds_read_b128 v[176:179], v146 offset:20480
	ds_read_b128 v[180:183], v146 offset:21504
	ds_read_b128 v[184:187], v146 offset:22528
	ds_read_b128 v[188:191], v146 offset:23552
	global_load_lds_dwordx4 v132, s[22:23]
	s_mov_b32 m0, s29
	s_nop 0
	global_load_lds_dwordx4 v130, s[22:23]
	s_barrier
	s_waitcnt lgkmcnt(0)
	v_mfma_f32_16x16x32_bf16 v[60:63], v[138:141], v[160:163], v[60:63]
	v_mfma_f32_16x16x32_bf16 v[52:55], v[152:155], v[160:163], v[52:55]
	v_mfma_f32_16x16x32_bf16 v[44:47], v[138:141], v[168:171], v[44:47]
	v_mfma_f32_16x16x32_bf16 v[36:39], v[152:155], v[168:171], v[36:39]
	v_mfma_f32_16x16x32_bf16 v[28:31], v[138:141], v[176:179], v[28:31]
	v_mfma_f32_16x16x32_bf16 v[20:23], v[152:155], v[176:179], v[20:23]
	v_mfma_f32_16x16x32_bf16 v[12:15], v[138:141], v[184:187], v[12:15]
	v_mfma_f32_16x16x32_bf16 v[4:7], v[152:155], v[184:187], v[4:7]
	v_mfma_f32_16x16x32_bf16 v[60:63], v[148:151], v[164:167], v[60:63]
	v_mfma_f32_16x16x32_bf16 v[52:55], v[156:159], v[164:167], v[52:55]
	v_mfma_f32_16x16x32_bf16 v[44:47], v[148:151], v[172:175], v[44:47]
	v_mfma_f32_16x16x32_bf16 v[36:39], v[156:159], v[172:175], v[36:39]
	v_mfma_f32_16x16x32_bf16 v[28:31], v[148:151], v[180:183], v[28:31]
	v_mfma_f32_16x16x32_bf16 v[20:23], v[156:159], v[180:183], v[20:23]
	v_mfma_f32_16x16x32_bf16 v[12:15], v[148:151], v[188:191], v[12:15]
	v_mfma_f32_16x16x32_bf16 v[4:7], v[156:159], v[188:191], v[4:7]
	s_barrier
	s_add_u32 s42, s20, 0x40000
	s_addc_u32 s43, s21, 0
	s_add_i32 s41, s44, s28
	s_mov_b32 m0, s41
	s_nop 0
	global_load_lds_dwordx4 v192, s[42:43]
	s_add_i32 m0, s41, 0x2000
	s_nop 0
	global_load_lds_dwordx4 v128, s[42:43]
	s_waitcnt vmcnt(6)
	s_barrier
	v_mfma_f32_16x16x32_bf16 v[56:59], v[198:201], v[160:163], v[56:59]
	v_mfma_f32_16x16x32_bf16 v[48:51], v[210:213], v[160:163], v[48:51]
	v_mfma_f32_16x16x32_bf16 v[40:43], v[198:201], v[168:171], v[40:43]
	v_mfma_f32_16x16x32_bf16 v[32:35], v[210:213], v[168:171], v[32:35]
	v_mfma_f32_16x16x32_bf16 v[24:27], v[198:201], v[176:179], v[24:27]
	v_mfma_f32_16x16x32_bf16 v[16:19], v[210:213], v[176:179], v[16:19]
	v_mfma_f32_16x16x32_bf16 v[8:11], v[198:201], v[184:187], v[8:11]
	v_mfma_f32_16x16x32_bf16 v[0:3], v[210:213], v[184:187], v[0:3]
	v_mfma_f32_16x16x32_bf16 v[56:59], v[206:209], v[164:167], v[56:59]
	v_mfma_f32_16x16x32_bf16 v[48:51], v[214:217], v[164:167], v[48:51]
	v_mfma_f32_16x16x32_bf16 v[40:43], v[206:209], v[172:175], v[40:43]
	v_mfma_f32_16x16x32_bf16 v[32:35], v[214:217], v[172:175], v[32:35]
	v_mfma_f32_16x16x32_bf16 v[24:27], v[206:209], v[180:183], v[24:27]
	v_mfma_f32_16x16x32_bf16 v[16:19], v[214:217], v[180:183], v[16:19]
	v_mfma_f32_16x16x32_bf16 v[8:11], v[206:209], v[188:191], v[8:11]
	v_mfma_f32_16x16x32_bf16 v[0:3], v[214:217], v[188:191], v[0:3]
	s_add_i32 s41, 0, 0x18000
	s_barrier
	ds_read_b128 v[138:141], v220
	ds_read_b128 v[148:151], v220 offset:1024
	ds_read_b128 v[152:155], v220 offset:2048
	ds_read_b128 v[156:159], v220 offset:3072
	s_add_u32 s22, s22, 0x40000
	s_addc_u32 s23, s23, 0
	s_mov_b32 m0, s30
	ds_read_b128 v[160:163], v146 offset:32768
	ds_read_b128 v[164:167], v146 offset:33792
	ds_read_b128 v[168:171], v146 offset:34816
	ds_read_b128 v[172:175], v146 offset:35840
	ds_read_b128 v[176:179], v146 offset:36864
	ds_read_b128 v[180:183], v146 offset:37888
	ds_read_b128 v[184:187], v146 offset:38912
	ds_read_b128 v[188:191], v146 offset:39936
	global_load_lds_dwordx4 v132, s[22:23]
	s_mov_b32 m0, s31
	s_nop 0
	global_load_lds_dwordx4 v130, s[22:23]
	s_waitcnt lgkmcnt(8)
	s_barrier
	s_waitcnt lgkmcnt(0)
	v_mfma_f32_16x16x32_bf16 v[124:127], v[138:141], v[160:163], v[124:127]
	v_mfma_f32_16x16x32_bf16 v[116:119], v[152:155], v[160:163], v[116:119]
	v_mfma_f32_16x16x32_bf16 v[108:111], v[138:141], v[168:171], v[108:111]
	v_mfma_f32_16x16x32_bf16 v[100:103], v[152:155], v[168:171], v[100:103]
	v_mfma_f32_16x16x32_bf16 v[92:95], v[138:141], v[176:179], v[92:95]
	v_mfma_f32_16x16x32_bf16 v[84:87], v[152:155], v[176:179], v[84:87]
	v_mfma_f32_16x16x32_bf16 v[76:79], v[138:141], v[184:187], v[76:79]
	v_mfma_f32_16x16x32_bf16 v[68:71], v[152:155], v[184:187], v[68:71]
	v_mfma_f32_16x16x32_bf16 v[124:127], v[148:151], v[164:167], v[124:127]
	v_mfma_f32_16x16x32_bf16 v[116:119], v[156:159], v[164:167], v[116:119]
	v_mfma_f32_16x16x32_bf16 v[108:111], v[148:151], v[172:175], v[108:111]
	v_mfma_f32_16x16x32_bf16 v[100:103], v[156:159], v[172:175], v[100:103]
	v_mfma_f32_16x16x32_bf16 v[92:95], v[148:151], v[180:183], v[92:95]
	v_mfma_f32_16x16x32_bf16 v[84:87], v[156:159], v[180:183], v[84:87]
	v_mfma_f32_16x16x32_bf16 v[76:79], v[148:151], v[188:191], v[76:79]
	v_mfma_f32_16x16x32_bf16 v[68:71], v[156:159], v[188:191], v[68:71]
	s_barrier
	s_add_i32 s22, 0, 0x1c000
	s_add_i32 s23, s41, s28
	s_add_u32 s100, s20, 0x80
	s_addc_u32 s101, s21, 0
	s_mov_b32 m0, s23
	ds_read_b128 v[198:201], v221
	ds_read_b128 v[206:209], v221 offset:1024
	ds_read_b128 v[210:213], v221 offset:2048
	ds_read_b128 v[214:217], v221 offset:3072
	global_load_lds_dwordx4 v192, s[100:101]
	s_add_i32 m0, s23, 0x2000
	s_nop 0
	global_load_lds_dwordx4 v128, s[100:101]
	s_barrier
	s_waitcnt lgkmcnt(0)
	v_mfma_f32_16x16x32_bf16 v[120:123], v[198:201], v[160:163], v[120:123]
	v_mfma_f32_16x16x32_bf16 v[112:115], v[210:213], v[160:163], v[112:115]
	v_mfma_f32_16x16x32_bf16 v[104:107], v[198:201], v[168:171], v[104:107]
	v_mfma_f32_16x16x32_bf16 v[96:99], v[210:213], v[168:171], v[96:99]
	v_mfma_f32_16x16x32_bf16 v[88:91], v[198:201], v[176:179], v[88:91]
	v_mfma_f32_16x16x32_bf16 v[80:83], v[210:213], v[176:179], v[80:83]
	v_mfma_f32_16x16x32_bf16 v[72:75], v[198:201], v[184:187], v[72:75]
	v_mfma_f32_16x16x32_bf16 v[64:67], v[210:213], v[184:187], v[64:67]
	v_mfma_f32_16x16x32_bf16 v[120:123], v[206:209], v[164:167], v[120:123]
	v_mfma_f32_16x16x32_bf16 v[112:115], v[214:217], v[164:167], v[112:115]
	v_mfma_f32_16x16x32_bf16 v[104:107], v[206:209], v[172:175], v[104:107]
	v_mfma_f32_16x16x32_bf16 v[96:99], v[214:217], v[172:175], v[96:99]
	v_mfma_f32_16x16x32_bf16 v[88:91], v[206:209], v[180:183], v[88:91]
	v_mfma_f32_16x16x32_bf16 v[80:83], v[214:217], v[180:183], v[80:83]
	v_mfma_f32_16x16x32_bf16 v[72:75], v[206:209], v[188:191], v[72:75]
	v_mfma_f32_16x16x32_bf16 v[64:67], v[214:217], v[188:191], v[64:67]
	s_mov_b32 m0, s34
	s_barrier
	ds_read_b128 v[160:163], v146 offset:49152
	ds_read_b128 v[164:167], v146 offset:50176
	ds_read_b128 v[168:171], v146 offset:51200
	ds_read_b128 v[172:175], v146 offset:52224
	ds_read_b128 v[176:179], v146 offset:53248
	ds_read_b128 v[180:183], v146 offset:54272
	ds_read_b128 v[184:187], v146 offset:55296
	ds_read_b128 v[188:191], v146 offset:56320
	global_load_lds_dwordx4 v132, vcc
	s_mov_b32 m0, s35
	s_nop 0
	global_load_lds_dwordx4 v130, vcc
	s_barrier
	s_waitcnt lgkmcnt(0)
	v_mfma_f32_16x16x32_bf16 v[60:63], v[138:141], v[160:163], v[60:63]
	v_mfma_f32_16x16x32_bf16 v[52:55], v[152:155], v[160:163], v[52:55]
	v_mfma_f32_16x16x32_bf16 v[44:47], v[138:141], v[168:171], v[44:47]
	v_mfma_f32_16x16x32_bf16 v[36:39], v[152:155], v[168:171], v[36:39]
	v_mfma_f32_16x16x32_bf16 v[28:31], v[138:141], v[176:179], v[28:31]
	v_mfma_f32_16x16x32_bf16 v[20:23], v[152:155], v[176:179], v[20:23]
	v_mfma_f32_16x16x32_bf16 v[12:15], v[138:141], v[184:187], v[12:15]
	v_mfma_f32_16x16x32_bf16 v[4:7], v[152:155], v[184:187], v[4:7]
	v_mfma_f32_16x16x32_bf16 v[60:63], v[148:151], v[164:167], v[60:63]
	v_mfma_f32_16x16x32_bf16 v[52:55], v[156:159], v[164:167], v[52:55]
	v_mfma_f32_16x16x32_bf16 v[44:47], v[148:151], v[172:175], v[44:47]
	v_mfma_f32_16x16x32_bf16 v[36:39], v[156:159], v[172:175], v[36:39]
	v_mfma_f32_16x16x32_bf16 v[28:31], v[148:151], v[180:183], v[28:31]
	v_mfma_f32_16x16x32_bf16 v[20:23], v[156:159], v[180:183], v[20:23]
	v_mfma_f32_16x16x32_bf16 v[12:15], v[148:151], v[188:191], v[12:15]
	v_mfma_f32_16x16x32_bf16 v[4:7], v[156:159], v[188:191], v[4:7]
	s_barrier
	s_add_u32 s20, s20, 0x40080
	s_addc_u32 s21, s21, 0
	s_add_i32 s22, s22, s28
	s_mov_b32 m0, s22
	s_nop 0
	global_load_lds_dwordx4 v192, s[20:21]
	s_add_i32 m0, s22, 0x2000
	s_nop 0
	global_load_lds_dwordx4 v128, s[20:21]
	s_waitcnt vmcnt(6)
	s_barrier
	v_mfma_f32_16x16x32_bf16 v[56:59], v[198:201], v[160:163], v[56:59]
	v_mfma_f32_16x16x32_bf16 v[48:51], v[210:213], v[160:163], v[48:51]
	v_mfma_f32_16x16x32_bf16 v[40:43], v[198:201], v[168:171], v[40:43]
	v_mfma_f32_16x16x32_bf16 v[32:35], v[210:213], v[168:171], v[32:35]
	v_mfma_f32_16x16x32_bf16 v[24:27], v[198:201], v[176:179], v[24:27]
	v_mfma_f32_16x16x32_bf16 v[16:19], v[210:213], v[176:179], v[16:19]
	v_mfma_f32_16x16x32_bf16 v[8:11], v[198:201], v[184:187], v[8:11]
	v_mfma_f32_16x16x32_bf16 v[0:3], v[210:213], v[184:187], v[0:3]
	v_mfma_f32_16x16x32_bf16 v[56:59], v[206:209], v[164:167], v[56:59]
	v_mfma_f32_16x16x32_bf16 v[48:51], v[214:217], v[164:167], v[48:51]
	v_mfma_f32_16x16x32_bf16 v[40:43], v[206:209], v[172:175], v[40:43]
	v_mfma_f32_16x16x32_bf16 v[32:35], v[214:217], v[172:175], v[32:35]
	v_mfma_f32_16x16x32_bf16 v[24:27], v[206:209], v[180:183], v[24:27]
	v_mfma_f32_16x16x32_bf16 v[16:19], v[214:217], v[180:183], v[16:19]
	v_mfma_f32_16x16x32_bf16 v[8:11], v[206:209], v[188:191], v[8:11]
	v_mfma_f32_16x16x32_bf16 v[0:3], v[214:217], v[188:191], v[0:3]
	s_add_i32 s40, s40, 2
	s_add_u32 s38, s38, 0x100
	s_addc_u32 s39, s39, 0
	s_add_u32 s18, s18, 0x100
	s_addc_u32 s19, s19, 0
	s_cmp_gt_u32 s40, 13
	s_barrier
	s_cbranch_scc0 .LBB0_402
	v_mov_b32_e32 v139, v252
	s_lshl_b32 s9, s16, 8
	v_readfirstlane_b32 s1, v139
	s_ashr_i32 s11, s1, 2
	s_andn2_b32 s11, s11, 63
	s_lshr_b32 s1, s1, 1
	s_add_i32 s11, s11, s9
	s_lshl_b32 s0, s0, 7
	s_and_b32 s1, s1, 0x60
	v_and_or_b32 v138, v139, 15, s11
	s_or_b32 s0, s1, s0
	v_lshrrev_b32_e32 v139, 1, v139
	v_and_or_b32 v142, v139, 24, s0
	v_ashrrev_i32_e32 v139, 31, v138
	v_lshl_add_u64 v[140:141], v[138:139], 2, s[6:7]
	v_pk_mul_f32 v[120:121], v[124:125], v[120:121]
	v_pk_mul_f32 v[122:123], v[126:127], v[122:123]
	v_pk_mul_f32 v[112:113], v[116:117], v[112:113]
	v_pk_mul_f32 v[114:115], v[118:119], v[114:115]
	v_ashrrev_i32_e32 v143, 31, v142
	s_movk_i32 s9, 0x1600
	v_pk_mul_f32 v[104:105], v[108:109], v[104:105]
	v_pk_mul_f32 v[106:107], v[110:111], v[106:107]
	v_pk_mul_f32 v[96:97], v[100:101], v[96:97]
	v_or_b32_e32 v150, 16, v138
	v_pk_mul_f32 v[98:99], v[102:103], v[98:99]
	v_pk_mul_f32 v[88:89], v[92:93], v[88:89]
	v_pk_mul_f32 v[90:91], v[94:95], v[90:91]
	v_pk_mul_f32 v[80:81], v[84:85], v[80:81]
	v_or_b32_e32 v148, 32, v138
	v_pk_mul_f32 v[82:83], v[86:87], v[82:83]
	v_pk_mul_f32 v[72:73], v[76:77], v[72:73]
	v_pk_mul_f32 v[74:75], v[78:79], v[74:75]
	v_pk_mul_f32 v[64:65], v[68:69], v[64:65]
	v_or_b32_e32 v139, 48, v138
	v_pk_mul_f32 v[66:67], v[70:71], v[66:67]
	v_pk_mul_f32 v[56:57], v[60:61], v[56:57]
	v_pk_mul_f32 v[58:59], v[62:63], v[58:59]
	v_pk_mul_f32 v[48:49], v[52:53], v[48:49]
	v_pk_mul_f32 v[50:51], v[54:55], v[50:51]
	v_pk_mul_f32 v[40:41], v[44:45], v[40:41]
	v_pk_mul_f32 v[42:43], v[46:47], v[42:43]
	v_pk_mul_f32 v[32:33], v[36:37], v[32:33]
	v_pk_mul_f32 v[34:35], v[38:39], v[34:35]
	v_pk_mul_f32 v[24:25], v[28:29], v[24:25]
	v_pk_mul_f32 v[26:27], v[30:31], v[26:27]
	v_pk_mul_f32 v[16:17], v[20:21], v[16:17]
	v_pk_mul_f32 v[18:19], v[22:23], v[18:19]
	v_pk_mul_f32 v[8:9], v[12:13], v[8:9]
	v_pk_mul_f32 v[10:11], v[14:15], v[10:11]
	v_pk_mul_f32 v[0:1], v[4:5], v[0:1]
	v_pk_mul_f32 v[2:3], v[6:7], v[2:3]
	s_mov_b32 s16, s8
	s_mov_b64 s[18:19], s[14:15]
	s_mov_b64 s[20:21], s[12:13]
	v_fmamk_f32 v144, v231, 0x3a800000, v194
	s_nop 0
	v_rsq_f32_e32 v144, v144
	s_nop 0
	v_mul_f32_e32 v152, 0xbfb8aa3b, v144
	v_pk_mul_f32 v[156:157], v[124:125], v[152:153] op_sel_hi:[1,0]
	v_pk_mul_f32 v[154:155], v[126:127], v[152:153] op_sel_hi:[1,0]
	v_exp_f32_e32 v153, v156
	v_mul_f32_e32 v144, v144, v144
	v_add_f32_e32 v153, 1.0, v153
	v_rcp_f32_e32 v156, v153
	v_exp_f32_e32 v153, v157
	s_nop 0
	v_add_f32_e32 v153, 1.0, v153
	v_rcp_f32_e32 v157, v153
	v_exp_f32_e32 v153, v154
	v_pk_mul_f32 v[124:125], v[144:145], v[156:157] op_sel_hi:[0,1]
	v_add_f32_e32 v153, 1.0, v153
	v_rcp_f32_e32 v154, v153
	v_exp_f32_e32 v153, v155
	v_pk_mul_f32 v[120:121], v[120:121], v[124:125]
	v_add_f32_e32 v153, 1.0, v153
	v_rcp_f32_e32 v155, v153
	v_cvt_pk_bf16_f32 v124, v121, s0
	v_cvt_pk_bf16_f32 v120, v120, s0
	v_readlane_b32 s0, v254, 29
	v_pk_mul_f32 v[126:127], v[144:145], v[154:155] op_sel_hi:[0,1]
	v_pk_mul_f32 v[122:123], v[122:123], v[126:127]
	v_readlane_b32 s1, v254, 30
	v_cvt_pk_bf16_f32 v121, v122, v123
	v_lshlrev_b32_e32 v122, 16, v124
	v_pk_mul_f32 v[124:125], v[116:117], v[152:153] op_sel_hi:[1,0]
	v_or_b32_sdwa v120, v122, v120 dst_sel:DWORD dst_unused:UNUSED_PAD src0_sel:DWORD src1_sel:WORD_0
	v_pk_mul_f32 v[122:123], v[118:119], v[152:153] op_sel_hi:[1,0]
	v_exp_f32_e32 v124, v124
	v_exp_f32_e32 v125, v125
	v_exp_f32_e32 v122, v122
	v_exp_f32_e32 v123, v123
	v_add_f32_e32 v124, 1.0, v124
	v_add_f32_e32 v125, 1.0, v125
	v_rcp_f32_e32 v124, v124
	v_rcp_f32_e32 v125, v125
	v_add_f32_e32 v122, 1.0, v122
	v_add_f32_e32 v123, 1.0, v123
	v_rcp_f32_e32 v122, v122
	v_rcp_f32_e32 v123, v123
	v_pk_mul_f32 v[116:117], v[144:145], v[124:125] op_sel_hi:[0,1]
	v_pk_mul_f32 v[112:113], v[112:113], v[116:117]
	v_pk_mul_f32 v[118:119], v[144:145], v[122:123] op_sel_hi:[0,1]
	v_pk_mul_f32 v[114:115], v[114:115], v[118:119]
	v_cvt_pk_bf16_f32 v122, v112, v113
	v_mov_b64_e32 v[112:113], s[0:1]
	v_cvt_pk_bf16_f32 v123, v114, v115
	v_mad_i64_i32 v[116:117], s[0:1], v138, s9, v[112:113]
	v_lshlrev_b64 v[114:115], 1, v[142:143]
	v_lshl_add_u64 v[116:117], v[116:117], 0, v[114:115]
	global_store_dwordx4 v[116:117], v[120:123], off
	v_fmamk_f32 v116, v232, 0x3a800000, v194
	s_nop 0
	v_rsq_f32_e32 v116, v116
	s_nop 0
	v_mul_f32_e32 v118, 0xbfb8aa3b, v116
	v_pk_mul_f32 v[120:121], v[108:109], v[118:119] op_sel_hi:[1,0]
	v_pk_mul_f32 v[122:123], v[110:111], v[118:119] op_sel_hi:[1,0]
	v_exp_f32_e32 v117, v120
	v_mul_f32_e32 v116, v116, v116
	v_add_f32_e32 v117, 1.0, v117
	v_rcp_f32_e32 v120, v117
	v_exp_f32_e32 v117, v121
	s_nop 0
	v_add_f32_e32 v117, 1.0, v117
	v_rcp_f32_e32 v121, v117
	v_exp_f32_e32 v117, v122
	s_nop 0
	v_add_f32_e32 v117, 1.0, v117
	v_rcp_f32_e32 v122, v117
	v_exp_f32_e32 v117, v123
	s_nop 0
	v_add_f32_e32 v117, 1.0, v117
	v_rcp_f32_e32 v123, v117
	v_pk_mul_f32 v[108:109], v[116:117], v[120:121] op_sel_hi:[0,1]
	v_pk_mul_f32 v[104:105], v[104:105], v[108:109]
	v_pk_mul_f32 v[110:111], v[116:117], v[122:123] op_sel_hi:[0,1]
	v_pk_mul_f32 v[106:107], v[106:107], v[110:111]
	v_cvt_pk_bf16_f32 v108, v105, s0
	v_cvt_pk_bf16_f32 v104, v104, s0
	v_cvt_pk_bf16_f32 v105, v106, v107
	v_lshlrev_b32_e32 v106, 16, v108
	v_pk_mul_f32 v[108:109], v[100:101], v[118:119] op_sel_hi:[1,0]
	v_or_b32_sdwa v104, v106, v104 dst_sel:DWORD dst_unused:UNUSED_PAD src0_sel:DWORD src1_sel:WORD_0
	v_pk_mul_f32 v[106:107], v[102:103], v[118:119] op_sel_hi:[1,0]
	v_exp_f32_e32 v108, v108
	v_exp_f32_e32 v109, v109
	v_exp_f32_e32 v106, v106
	v_exp_f32_e32 v107, v107
	v_add_f32_e32 v108, 1.0, v108
	v_add_f32_e32 v109, 1.0, v109
	v_rcp_f32_e32 v108, v108
	v_rcp_f32_e32 v109, v109
	v_add_f32_e32 v106, 1.0, v106
	v_add_f32_e32 v107, 1.0, v107
	v_rcp_f32_e32 v106, v106
	v_rcp_f32_e32 v107, v107
	v_pk_mul_f32 v[100:101], v[116:117], v[108:109] op_sel_hi:[0,1]
	v_pk_mul_f32 v[96:97], v[96:97], v[100:101]
	v_pk_mul_f32 v[102:103], v[116:117], v[106:107] op_sel_hi:[0,1]
	v_pk_mul_f32 v[98:99], v[98:99], v[102:103]
	v_cvt_pk_bf16_f32 v106, v96, v97
	v_mad_i64_i32 v[96:97], s[0:1], v150, s9, v[112:113]
	v_cvt_pk_bf16_f32 v107, v98, v99
	v_lshl_add_u64 v[96:97], v[96:97], 0, v[114:115]
	global_store_dwordx4 v[96:97], v[104:107], off
	v_fmamk_f32 v96, v233, 0x3a800000, v194
	s_nop 0
	v_rsq_f32_e32 v96, v96
	s_nop 0
	v_mov_b32_e32 v97, v96
	v_mul_f32_e32 v96, 0xbfb8aa3b, v97
	v_pk_mul_f32 v[102:103], v[92:93], v[96:97] op_sel_hi:[1,0]
	v_mul_f32_e32 v98, v97, v97
	v_pk_mul_f32 v[100:101], v[94:95], v[96:97] op_sel_hi:[1,0]
	v_exp_f32_e32 v97, v102
	s_nop 0
	v_add_f32_e32 v97, 1.0, v97
	v_rcp_f32_e32 v102, v97
	v_exp_f32_e32 v97, v103
	s_nop 0
	v_add_f32_e32 v97, 1.0, v97
	v_rcp_f32_e32 v103, v97
	v_exp_f32_e32 v97, v100
	v_pk_mul_f32 v[92:93], v[98:99], v[102:103] op_sel_hi:[0,1]
	v_add_f32_e32 v97, 1.0, v97
	v_rcp_f32_e32 v100, v97
	v_exp_f32_e32 v97, v101
	v_pk_mul_f32 v[88:89], v[88:89], v[92:93]
	v_add_f32_e32 v97, 1.0, v97
	v_rcp_f32_e32 v101, v97
	v_cvt_pk_bf16_f32 v92, v89, s0
	v_cvt_pk_bf16_f32 v88, v88, s0
	v_pk_mul_f32 v[94:95], v[98:99], v[100:101] op_sel_hi:[0,1]
	v_pk_mul_f32 v[90:91], v[90:91], v[94:95]
	s_nop 0
	v_cvt_pk_bf16_f32 v89, v90, v91
	v_lshlrev_b32_e32 v90, 16, v92
	v_pk_mul_f32 v[92:93], v[84:85], v[96:97] op_sel_hi:[1,0]
	v_or_b32_sdwa v88, v90, v88 dst_sel:DWORD dst_unused:UNUSED_PAD src0_sel:DWORD src1_sel:WORD_0
	v_pk_mul_f32 v[90:91], v[86:87], v[96:97] op_sel_hi:[1,0]
	v_exp_f32_e32 v92, v92
	v_exp_f32_e32 v93, v93
	v_exp_f32_e32 v90, v90
	v_exp_f32_e32 v91, v91
	v_add_f32_e32 v92, 1.0, v92
	v_add_f32_e32 v93, 1.0, v93
	v_rcp_f32_e32 v92, v92
	v_rcp_f32_e32 v93, v93
	v_add_f32_e32 v90, 1.0, v90
	v_add_f32_e32 v91, 1.0, v91
	v_rcp_f32_e32 v90, v90
	v_rcp_f32_e32 v91, v91
	v_pk_mul_f32 v[84:85], v[98:99], v[92:93] op_sel_hi:[0,1]
	v_pk_mul_f32 v[80:81], v[80:81], v[84:85]
	v_pk_mul_f32 v[86:87], v[98:99], v[90:91] op_sel_hi:[0,1]
	v_pk_mul_f32 v[82:83], v[82:83], v[86:87]
	v_cvt_pk_bf16_f32 v90, v80, v81
	v_mad_i64_i32 v[80:81], s[0:1], v148, s9, v[112:113]
	v_cvt_pk_bf16_f32 v91, v82, v83
	v_lshl_add_u64 v[80:81], v[80:81], 0, v[114:115]
	global_store_dwordx4 v[80:81], v[88:91], off
	v_fmamk_f32 v80, v234, 0x3a800000, v194
	s_nop 0
	v_rsq_f32_e32 v80, v80
	s_nop 0
	v_mov_b32_e32 v81, v80
	v_mul_f32_e32 v80, 0xbfb8aa3b, v81
	v_pk_mul_f32 v[86:87], v[76:77], v[80:81] op_sel_hi:[1,0]
	v_mul_f32_e32 v82, v81, v81
	v_pk_mul_f32 v[84:85], v[78:79], v[80:81] op_sel_hi:[1,0]
	v_exp_f32_e32 v81, v86
	s_nop 0
	v_add_f32_e32 v81, 1.0, v81
	v_rcp_f32_e32 v86, v81
	v_exp_f32_e32 v81, v87
	s_nop 0
	v_add_f32_e32 v81, 1.0, v81
	v_rcp_f32_e32 v87, v81
	v_exp_f32_e32 v81, v84
	v_pk_mul_f32 v[76:77], v[82:83], v[86:87] op_sel_hi:[0,1]
	v_add_f32_e32 v81, 1.0, v81
	v_rcp_f32_e32 v84, v81
	v_exp_f32_e32 v81, v85
	v_pk_mul_f32 v[72:73], v[72:73], v[76:77]
	v_add_f32_e32 v81, 1.0, v81
	v_rcp_f32_e32 v85, v81
	v_cvt_pk_bf16_f32 v76, v73, s0
	v_cvt_pk_bf16_f32 v72, v72, s0
	v_pk_mul_f32 v[78:79], v[82:83], v[84:85] op_sel_hi:[0,1]
	v_pk_mul_f32 v[74:75], v[74:75], v[78:79]
	s_nop 0
	v_cvt_pk_bf16_f32 v73, v74, v75
	v_lshlrev_b32_e32 v74, 16, v76
	v_pk_mul_f32 v[76:77], v[68:69], v[80:81] op_sel_hi:[1,0]
	v_or_b32_sdwa v72, v74, v72 dst_sel:DWORD dst_unused:UNUSED_PAD src0_sel:DWORD src1_sel:WORD_0
	v_pk_mul_f32 v[74:75], v[70:71], v[80:81] op_sel_hi:[1,0]
	v_exp_f32_e32 v76, v76
	v_exp_f32_e32 v77, v77
	v_exp_f32_e32 v74, v74
	v_exp_f32_e32 v75, v75
	v_add_f32_e32 v76, 1.0, v76
	v_add_f32_e32 v77, 1.0, v77
	v_rcp_f32_e32 v76, v76
	v_rcp_f32_e32 v77, v77
	v_add_f32_e32 v74, 1.0, v74
	v_add_f32_e32 v75, 1.0, v75
	v_rcp_f32_e32 v74, v74
	v_rcp_f32_e32 v75, v75
	v_pk_mul_f32 v[68:69], v[82:83], v[76:77] op_sel_hi:[0,1]
	v_pk_mul_f32 v[64:65], v[64:65], v[68:69]
	v_add_u32_e32 v69, 0x90, v138
	v_pk_mul_f32 v[70:71], v[82:83], v[74:75] op_sel_hi:[0,1]
	v_pk_mul_f32 v[66:67], v[66:67], v[70:71]
	v_cvt_pk_bf16_f32 v74, v64, v65
	v_mad_i64_i32 v[64:65], s[0:1], v139, s9, v[112:113]
	v_cvt_pk_bf16_f32 v75, v66, v67
	v_lshl_add_u64 v[64:65], v[64:65], 0, v[114:115]
	global_store_dwordx4 v[64:65], v[72:75], off
	v_add_u32_e32 v67, 0x80, v138
	v_add_u32_e32 v66, 0xa0, v138
	v_add_u32_e32 v64, 0xb0, v138
	v_fmamk_f32 v68, v235, 0x3a800000, v194
	s_nop 0
	v_rsq_f32_e32 v68, v68
	s_nop 0
	v_mov_b32_e32 v70, v68
	v_mul_f32_e32 v68, 0xbfb8aa3b, v70
	v_pk_mul_f32 v[74:75], v[60:61], v[68:69] op_sel_hi:[1,0]
	v_pk_mul_f32 v[72:73], v[62:63], v[68:69] op_sel_hi:[1,0]
	v_exp_f32_e32 v74, v74
	v_exp_f32_e32 v75, v75
	v_exp_f32_e32 v72, v72
	v_exp_f32_e32 v73, v73
	v_add_f32_e32 v74, 1.0, v74
	v_add_f32_e32 v75, 1.0, v75
	v_rcp_f32_e32 v74, v74
	v_rcp_f32_e32 v75, v75
	v_add_f32_e32 v72, 1.0, v72
	v_add_f32_e32 v73, 1.0, v73
	v_rcp_f32_e32 v72, v72
	v_rcp_f32_e32 v73, v73
	v_mul_f32_e32 v70, v70, v70
	v_pk_mul_f32 v[60:61], v[70:71], v[74:75] op_sel_hi:[0,1]
	v_pk_mul_f32 v[56:57], v[56:57], v[60:61]
	v_pk_mul_f32 v[62:63], v[70:71], v[72:73] op_sel_hi:[0,1]
	v_pk_mul_f32 v[58:59], v[58:59], v[62:63]
	v_cvt_pk_bf16_f32 v60, v57, s0
	v_cvt_pk_bf16_f32 v56, v56, s0
	v_cvt_pk_bf16_f32 v57, v58, v59
	v_lshlrev_b32_e32 v58, 16, v60
	v_pk_mul_f32 v[60:61], v[52:53], v[68:69] op_sel_hi:[1,0]
	v_or_b32_sdwa v56, v58, v56 dst_sel:DWORD dst_unused:UNUSED_PAD src0_sel:DWORD src1_sel:WORD_0
	v_pk_mul_f32 v[58:59], v[54:55], v[68:69] op_sel_hi:[1,0]
	v_exp_f32_e32 v60, v60
	v_exp_f32_e32 v61, v61
	v_exp_f32_e32 v58, v58
	v_exp_f32_e32 v59, v59
	v_add_f32_e32 v60, 1.0, v60
	v_add_f32_e32 v61, 1.0, v61
	v_rcp_f32_e32 v60, v60
	v_rcp_f32_e32 v61, v61
	v_add_f32_e32 v58, 1.0, v58
	v_add_f32_e32 v59, 1.0, v59
	v_rcp_f32_e32 v58, v58
	v_rcp_f32_e32 v59, v59
	v_pk_mul_f32 v[52:53], v[70:71], v[60:61] op_sel_hi:[0,1]
	v_pk_mul_f32 v[48:49], v[48:49], v[52:53]
	v_pk_mul_f32 v[54:55], v[70:71], v[58:59] op_sel_hi:[0,1]
	v_pk_mul_f32 v[50:51], v[50:51], v[54:55]
	v_cvt_pk_bf16_f32 v58, v48, v49
	v_mad_i64_i32 v[48:49], s[0:1], v67, s9, v[112:113]
	v_cvt_pk_bf16_f32 v59, v50, v51
	v_lshl_add_u64 v[48:49], v[48:49], 0, v[114:115]
	global_store_dwordx4 v[48:49], v[56:59], off
	v_fmamk_f32 v48, v236, 0x3a800000, v194
	s_nop 0
	v_rsq_f32_e32 v48, v48
	s_nop 0
	v_mov_b32_e32 v49, v48
	v_mul_f32_e32 v48, 0xbfb8aa3b, v49
	v_pk_mul_f32 v[54:55], v[44:45], v[48:49] op_sel_hi:[1,0]
	v_mul_f32_e32 v50, v49, v49
	v_pk_mul_f32 v[52:53], v[46:47], v[48:49] op_sel_hi:[1,0]
	v_exp_f32_e32 v49, v54
	s_nop 0
	v_add_f32_e32 v49, 1.0, v49
	v_rcp_f32_e32 v54, v49
	v_exp_f32_e32 v49, v55
	s_nop 0
	v_add_f32_e32 v49, 1.0, v49
	v_rcp_f32_e32 v55, v49
	v_exp_f32_e32 v49, v52
	v_pk_mul_f32 v[44:45], v[50:51], v[54:55] op_sel_hi:[0,1]
	v_add_f32_e32 v49, 1.0, v49
	v_rcp_f32_e32 v52, v49
	v_exp_f32_e32 v49, v53
	v_pk_mul_f32 v[40:41], v[40:41], v[44:45]
	v_add_f32_e32 v49, 1.0, v49
	v_rcp_f32_e32 v53, v49
	v_cvt_pk_bf16_f32 v44, v41, s0
	v_cvt_pk_bf16_f32 v40, v40, s0
	v_pk_mul_f32 v[46:47], v[50:51], v[52:53] op_sel_hi:[0,1]
	v_pk_mul_f32 v[42:43], v[42:43], v[46:47]
	s_nop 0
	v_cvt_pk_bf16_f32 v41, v42, v43
	v_lshlrev_b32_e32 v42, 16, v44
	v_pk_mul_f32 v[44:45], v[36:37], v[48:49] op_sel_hi:[1,0]
	v_or_b32_sdwa v40, v42, v40 dst_sel:DWORD dst_unused:UNUSED_PAD src0_sel:DWORD src1_sel:WORD_0
	v_pk_mul_f32 v[42:43], v[38:39], v[48:49] op_sel_hi:[1,0]
	v_exp_f32_e32 v44, v44
	v_exp_f32_e32 v45, v45
	v_exp_f32_e32 v42, v42
	v_exp_f32_e32 v43, v43
	v_add_f32_e32 v44, 1.0, v44
	v_add_f32_e32 v45, 1.0, v45
	v_rcp_f32_e32 v44, v44
	v_rcp_f32_e32 v45, v45
	v_add_f32_e32 v42, 1.0, v42
	v_add_f32_e32 v43, 1.0, v43
	v_rcp_f32_e32 v42, v42
	v_rcp_f32_e32 v43, v43
	v_pk_mul_f32 v[36:37], v[50:51], v[44:45] op_sel_hi:[0,1]
	v_pk_mul_f32 v[32:33], v[32:33], v[36:37]
	v_pk_mul_f32 v[38:39], v[50:51], v[42:43] op_sel_hi:[0,1]
	v_pk_mul_f32 v[34:35], v[34:35], v[38:39]
	v_cvt_pk_bf16_f32 v42, v32, v33
	v_mad_i64_i32 v[32:33], s[0:1], v69, s9, v[112:113]
	v_cvt_pk_bf16_f32 v43, v34, v35
	v_lshl_add_u64 v[32:33], v[32:33], 0, v[114:115]
	global_store_dwordx4 v[32:33], v[40:43], off
	v_fmamk_f32 v32, v237, 0x3a800000, v194
	s_nop 0
	v_rsq_f32_e32 v32, v32
	s_nop 0
	v_mov_b32_e32 v33, v32
	v_mul_f32_e32 v32, 0xbfb8aa3b, v33
	v_pk_mul_f32 v[38:39], v[28:29], v[32:33] op_sel_hi:[1,0]
	v_mul_f32_e32 v34, v33, v33
	v_pk_mul_f32 v[36:37], v[30:31], v[32:33] op_sel_hi:[1,0]
	v_exp_f32_e32 v33, v38
	s_nop 0
	v_add_f32_e32 v33, 1.0, v33
	v_rcp_f32_e32 v38, v33
	v_exp_f32_e32 v33, v39
	s_nop 0
	v_add_f32_e32 v33, 1.0, v33
	v_rcp_f32_e32 v39, v33
	v_exp_f32_e32 v33, v36
	v_pk_mul_f32 v[28:29], v[34:35], v[38:39] op_sel_hi:[0,1]
	v_add_f32_e32 v33, 1.0, v33
	v_rcp_f32_e32 v36, v33
	v_exp_f32_e32 v33, v37
	v_pk_mul_f32 v[24:25], v[24:25], v[28:29]
	v_add_f32_e32 v33, 1.0, v33
	v_rcp_f32_e32 v37, v33
	v_cvt_pk_bf16_f32 v28, v25, s0
	v_cvt_pk_bf16_f32 v24, v24, s0
	v_pk_mul_f32 v[30:31], v[34:35], v[36:37] op_sel_hi:[0,1]
	v_pk_mul_f32 v[26:27], v[26:27], v[30:31]
	s_nop 0
	v_cvt_pk_bf16_f32 v25, v26, v27
	v_lshlrev_b32_e32 v26, 16, v28
	v_pk_mul_f32 v[28:29], v[20:21], v[32:33] op_sel_hi:[1,0]
	v_or_b32_sdwa v24, v26, v24 dst_sel:DWORD dst_unused:UNUSED_PAD src0_sel:DWORD src1_sel:WORD_0
	v_pk_mul_f32 v[26:27], v[22:23], v[32:33] op_sel_hi:[1,0]
	v_exp_f32_e32 v28, v28
	v_exp_f32_e32 v29, v29
	v_exp_f32_e32 v26, v26
	v_exp_f32_e32 v27, v27
	v_add_f32_e32 v28, 1.0, v28
	v_add_f32_e32 v29, 1.0, v29
	v_rcp_f32_e32 v28, v28
	v_rcp_f32_e32 v29, v29
	v_add_f32_e32 v26, 1.0, v26
	v_add_f32_e32 v27, 1.0, v27
	v_rcp_f32_e32 v26, v26
	v_rcp_f32_e32 v27, v27
	v_pk_mul_f32 v[20:21], v[34:35], v[28:29] op_sel_hi:[0,1]
	v_pk_mul_f32 v[16:17], v[16:17], v[20:21]
	v_pk_mul_f32 v[22:23], v[34:35], v[26:27] op_sel_hi:[0,1]
	v_pk_mul_f32 v[18:19], v[18:19], v[22:23]
	v_cvt_pk_bf16_f32 v26, v16, v17
	v_mad_i64_i32 v[16:17], s[0:1], v66, s9, v[112:113]
	v_cvt_pk_bf16_f32 v27, v18, v19
	v_lshl_add_u64 v[16:17], v[16:17], 0, v[114:115]
	global_store_dwordx4 v[16:17], v[24:27], off
	v_fmamk_f32 v16, v238, 0x3a800000, v194
	s_nop 0
	v_rsq_f32_e32 v16, v16
	s_nop 0
	v_mov_b32_e32 v17, v16
	v_mul_f32_e32 v16, 0xbfb8aa3b, v17
	v_pk_mul_f32 v[22:23], v[12:13], v[16:17] op_sel_hi:[1,0]
	v_mul_f32_e32 v18, v17, v17
	v_pk_mul_f32 v[20:21], v[14:15], v[16:17] op_sel_hi:[1,0]
	v_exp_f32_e32 v17, v22
	s_and_b64 vcc, exec, s[4:5]
	v_add_f32_e32 v17, 1.0, v17
	v_rcp_f32_e32 v22, v17
	v_exp_f32_e32 v17, v23
	s_nop 0
	v_add_f32_e32 v17, 1.0, v17
	v_rcp_f32_e32 v23, v17
	v_exp_f32_e32 v17, v20
	v_pk_mul_f32 v[12:13], v[18:19], v[22:23] op_sel_hi:[0,1]
	v_add_f32_e32 v17, 1.0, v17
	v_rcp_f32_e32 v20, v17
	v_exp_f32_e32 v17, v21
	v_pk_mul_f32 v[8:9], v[8:9], v[12:13]
	v_add_f32_e32 v17, 1.0, v17
	v_rcp_f32_e32 v21, v17
	v_cvt_pk_bf16_f32 v12, v9, s0
	v_cvt_pk_bf16_f32 v8, v8, s0
	v_pk_mul_f32 v[14:15], v[18:19], v[20:21] op_sel_hi:[0,1]
	v_pk_mul_f32 v[10:11], v[10:11], v[14:15]
	s_nop 0
	v_cvt_pk_bf16_f32 v9, v10, v11
	v_lshlrev_b32_e32 v10, 16, v12
	v_pk_mul_f32 v[12:13], v[4:5], v[16:17] op_sel_hi:[1,0]
	v_or_b32_sdwa v8, v10, v8 dst_sel:DWORD dst_unused:UNUSED_PAD src0_sel:DWORD src1_sel:WORD_0
	v_pk_mul_f32 v[10:11], v[6:7], v[16:17] op_sel_hi:[1,0]
	v_exp_f32_e32 v12, v12
	v_exp_f32_e32 v13, v13
	v_exp_f32_e32 v10, v10
	v_exp_f32_e32 v11, v11
	v_add_f32_e32 v12, 1.0, v12
	v_add_f32_e32 v13, 1.0, v13
	v_rcp_f32_e32 v12, v12
	v_rcp_f32_e32 v13, v13
	v_add_f32_e32 v10, 1.0, v10
	v_add_f32_e32 v11, 1.0, v11
	v_rcp_f32_e32 v10, v10
	v_rcp_f32_e32 v11, v11
	v_pk_mul_f32 v[4:5], v[18:19], v[12:13] op_sel_hi:[0,1]
	v_pk_mul_f32 v[0:1], v[0:1], v[4:5]
	v_pk_mul_f32 v[6:7], v[18:19], v[10:11] op_sel_hi:[0,1]
	v_pk_mul_f32 v[2:3], v[2:3], v[6:7]
	v_cvt_pk_bf16_f32 v10, v0, v1
	v_mad_i64_i32 v[0:1], s[0:1], v64, s9, v[112:113]
	v_cvt_pk_bf16_f32 v11, v2, v3
	v_lshl_add_u64 v[0:1], v[0:1], 0, v[114:115]
	s_mov_b32 s0, s10
	global_store_dwordx4 v[0:1], v[8:11], off
	s_cbranch_vccz .LBB0_399
	s_waitcnt vmcnt(0)
	s_cmpk_gt_u32 s25, 0xff
	s_cbranch_scc1 .LBB0_406
	s_barrier

.LBB0_1623:
	s_add_u32 s22, s20, 0x100
	s_addc_u32 s23, s21, 0
	s_add_i32 s46, 0, 0x10000
	ds_read_b128 v[128:131], v216
	ds_read_b128 v[132:135], v216 offset:1024
	ds_read_b128 v[136:139], v216 offset:2048
	ds_read_b128 v[140:143], v216 offset:3072
	s_cmp_eq_u32 s45, 40
	s_cselect_b32 s27, s7, s23
	s_cselect_b32 s26, s6, s22
	s_cselect_b32 s25, s9, s44
	s_cselect_b32 s24, s8, s33
	s_add_i32 m0, s34, 0xc000
	ds_read_b128 v[144:147], v198
	ds_read_b128 v[148:151], v198 offset:1024
	ds_read_b128 v[152:155], v198 offset:2048
	ds_read_b128 v[156:159], v198 offset:3072
	ds_read_b128 v[160:163], v198 offset:4096
	ds_read_b128 v[164:167], v198 offset:5120
	ds_read_b128 v[168:171], v198 offset:6144
	ds_read_b128 v[172:175], v198 offset:7168
	global_load_lds_dwordx4 v214, s[20:21]
	s_add_i32 m0, s34, 0xe000
	s_nop 0
	global_load_lds_dwordx4 v212, s[20:21]
	s_waitcnt lgkmcnt(8)
	s_barrier
	s_waitcnt lgkmcnt(0)
	v_mfma_f32_16x16x32_bf16 v[124:127], v[128:131], v[144:147], v[124:127]
	v_mfma_f32_16x16x32_bf16 v[120:123], v[136:139], v[144:147], v[120:123]
	v_mfma_f32_16x16x32_bf16 v[108:111], v[128:131], v[152:155], v[108:111]
	v_mfma_f32_16x16x32_bf16 v[104:107], v[136:139], v[152:155], v[104:107]
	v_mfma_f32_16x16x32_bf16 v[92:95], v[128:131], v[160:163], v[92:95]
	v_mfma_f32_16x16x32_bf16 v[88:91], v[136:139], v[160:163], v[88:91]
	v_mfma_f32_16x16x32_bf16 v[76:79], v[128:131], v[168:171], v[76:79]
	v_mfma_f32_16x16x32_bf16 v[72:75], v[136:139], v[168:171], v[72:75]
	v_mfma_f32_16x16x32_bf16 v[124:127], v[132:135], v[148:151], v[124:127]
	v_mfma_f32_16x16x32_bf16 v[120:123], v[140:143], v[148:151], v[120:123]
	v_mfma_f32_16x16x32_bf16 v[108:111], v[132:135], v[156:159], v[108:111]
	v_mfma_f32_16x16x32_bf16 v[104:107], v[140:143], v[156:159], v[104:107]
	v_mfma_f32_16x16x32_bf16 v[92:95], v[132:135], v[164:167], v[92:95]
	v_mfma_f32_16x16x32_bf16 v[88:91], v[140:143], v[164:167], v[88:91]
	v_mfma_f32_16x16x32_bf16 v[76:79], v[132:135], v[172:175], v[76:79]
	v_mfma_f32_16x16x32_bf16 v[72:75], v[140:143], v[172:175], v[72:75]
	s_barrier
	s_add_i32 s47, 0, 0x14000
	s_add_i32 s20, s46, s31
	s_mov_b32 m0, s20
	ds_read_b128 v[176:179], v217
	ds_read_b128 v[180:183], v217 offset:1024
	ds_read_b128 v[184:187], v217 offset:2048
	ds_read_b128 v[188:191], v217 offset:3072
	global_load_lds_dwordx4 v192, s[24:25]
	s_add_i32 m0, s20, 0x2000
	s_nop 0
	global_load_lds_dwordx4 v210, s[24:25]
	s_barrier
	s_waitcnt lgkmcnt(0)
	v_mfma_f32_16x16x32_bf16 v[116:119], v[176:179], v[144:147], v[116:119]
	v_mfma_f32_16x16x32_bf16 v[112:115], v[184:187], v[144:147], v[112:115]
	v_mfma_f32_16x16x32_bf16 v[100:103], v[176:179], v[152:155], v[100:103]
	v_mfma_f32_16x16x32_bf16 v[96:99], v[184:187], v[152:155], v[96:99]
	v_mfma_f32_16x16x32_bf16 v[84:87], v[176:179], v[160:163], v[84:87]
	v_mfma_f32_16x16x32_bf16 v[80:83], v[184:187], v[160:163], v[80:83]
	v_mfma_f32_16x16x32_bf16 v[68:71], v[176:179], v[168:171], v[68:71]
	v_mfma_f32_16x16x32_bf16 v[64:67], v[184:187], v[168:171], v[64:67]
	v_mfma_f32_16x16x32_bf16 v[116:119], v[180:183], v[148:151], v[116:119]
	v_mfma_f32_16x16x32_bf16 v[112:115], v[188:191], v[148:151], v[112:115]
	v_mfma_f32_16x16x32_bf16 v[100:103], v[180:183], v[156:159], v[100:103]
	v_mfma_f32_16x16x32_bf16 v[96:99], v[188:191], v[156:159], v[96:99]
	v_mfma_f32_16x16x32_bf16 v[84:87], v[180:183], v[164:167], v[84:87]
	v_mfma_f32_16x16x32_bf16 v[80:83], v[188:191], v[164:167], v[80:83]
	v_mfma_f32_16x16x32_bf16 v[68:71], v[180:183], v[172:175], v[68:71]
	v_mfma_f32_16x16x32_bf16 v[64:67], v[188:191], v[172:175], v[64:67]
	s_mov_b32 m0, s34
	s_add_u32 vcc_lo, s26, 0x80
	s_addc_u32 vcc_hi, s27, 0
	s_barrier
	ds_read_b128 v[144:147], v198 offset:16384
	ds_read_b128 v[148:151], v198 offset:17408
	ds_read_b128 v[152:155], v198 offset:18432
	ds_read_b128 v[156:159], v198 offset:19456
	ds_read_b128 v[160:163], v198 offset:20480
	ds_read_b128 v[164:167], v198 offset:21504
	ds_read_b128 v[168:171], v198 offset:22528
	ds_read_b128 v[172:175], v198 offset:23552
	global_load_lds_dwordx4 v206, s[26:27]
	s_mov_b32 m0, s35
	s_nop 0
	global_load_lds_dwordx4 v208, s[26:27]
	s_barrier
	s_waitcnt lgkmcnt(0)
	v_mfma_f32_16x16x32_bf16 v[60:63], v[128:131], v[144:147], v[60:63]
	v_mfma_f32_16x16x32_bf16 v[56:59], v[136:139], v[144:147], v[56:59]
	v_mfma_f32_16x16x32_bf16 v[44:47], v[128:131], v[152:155], v[44:47]
	v_mfma_f32_16x16x32_bf16 v[40:43], v[136:139], v[152:155], v[40:43]
	v_mfma_f32_16x16x32_bf16 v[28:31], v[128:131], v[160:163], v[28:31]
	v_mfma_f32_16x16x32_bf16 v[24:27], v[136:139], v[160:163], v[24:27]
	v_mfma_f32_16x16x32_bf16 v[12:15], v[128:131], v[168:171], v[12:15]
	v_mfma_f32_16x16x32_bf16 v[8:11], v[136:139], v[168:171], v[8:11]
	v_mfma_f32_16x16x32_bf16 v[60:63], v[132:135], v[148:151], v[60:63]
	v_mfma_f32_16x16x32_bf16 v[56:59], v[140:143], v[148:151], v[56:59]
	v_mfma_f32_16x16x32_bf16 v[44:47], v[132:135], v[156:159], v[44:47]
	v_mfma_f32_16x16x32_bf16 v[40:43], v[140:143], v[156:159], v[40:43]
	v_mfma_f32_16x16x32_bf16 v[28:31], v[132:135], v[164:167], v[28:31]
	v_mfma_f32_16x16x32_bf16 v[24:27], v[140:143], v[164:167], v[24:27]
	v_mfma_f32_16x16x32_bf16 v[12:15], v[132:135], v[172:175], v[12:15]
	v_mfma_f32_16x16x32_bf16 v[8:11], v[140:143], v[172:175], v[8:11]
	s_barrier
	s_add_u32 s20, s24, 0xb0000
	s_addc_u32 s21, s25, 0
	s_add_i32 s46, s47, s31
	s_mov_b32 m0, s46
	s_nop 0
	global_load_lds_dwordx4 v192, s[20:21]
	s_add_i32 m0, s46, 0x2000
	s_nop 0
	global_load_lds_dwordx4 v210, s[20:21]
	s_waitcnt vmcnt(6)
	s_barrier
	v_mfma_f32_16x16x32_bf16 v[52:55], v[176:179], v[144:147], v[52:55]
	v_mfma_f32_16x16x32_bf16 v[48:51], v[184:187], v[144:147], v[48:51]
	v_mfma_f32_16x16x32_bf16 v[36:39], v[176:179], v[152:155], v[36:39]
	v_mfma_f32_16x16x32_bf16 v[32:35], v[184:187], v[152:155], v[32:35]
	v_mfma_f32_16x16x32_bf16 v[20:23], v[176:179], v[160:163], v[20:23]
	v_mfma_f32_16x16x32_bf16 v[16:19], v[184:187], v[160:163], v[16:19]
	v_mfma_f32_16x16x32_bf16 v[4:7], v[176:179], v[168:171], v[4:7]
	v_mfma_f32_16x16x32_bf16 v[0:3], v[184:187], v[168:171], v[0:3]
	v_mfma_f32_16x16x32_bf16 v[52:55], v[180:183], v[148:151], v[52:55]
	v_mfma_f32_16x16x32_bf16 v[48:51], v[188:191], v[148:151], v[48:51]
	v_mfma_f32_16x16x32_bf16 v[36:39], v[180:183], v[156:159], v[36:39]
	v_mfma_f32_16x16x32_bf16 v[32:35], v[188:191], v[156:159], v[32:35]
	v_mfma_f32_16x16x32_bf16 v[20:23], v[180:183], v[164:167], v[20:23]
	v_mfma_f32_16x16x32_bf16 v[16:19], v[188:191], v[164:167], v[16:19]
	v_mfma_f32_16x16x32_bf16 v[4:7], v[180:183], v[172:175], v[4:7]
	v_mfma_f32_16x16x32_bf16 v[0:3], v[188:191], v[172:175], v[0:3]
	s_add_i32 s46, 0, 0x18000
	s_barrier
	ds_read_b128 v[128:131], v218
	ds_read_b128 v[132:135], v218 offset:1024
	ds_read_b128 v[136:139], v218 offset:2048
	ds_read_b128 v[140:143], v218 offset:3072
	s_add_u32 s20, s26, 0xb0000
	s_addc_u32 s21, s27, 0
	s_mov_b32 m0, s36
	ds_read_b128 v[144:147], v198 offset:32768
	ds_read_b128 v[148:151], v198 offset:33792
	ds_read_b128 v[152:155], v198 offset:34816
	ds_read_b128 v[156:159], v198 offset:35840
	ds_read_b128 v[160:163], v198 offset:36864
	ds_read_b128 v[164:167], v198 offset:37888
	ds_read_b128 v[168:171], v198 offset:38912
	ds_read_b128 v[172:175], v198 offset:39936
	global_load_lds_dwordx4 v206, s[20:21]
	s_mov_b32 m0, s37
	s_nop 0
	global_load_lds_dwordx4 v208, s[20:21]
	s_waitcnt lgkmcnt(8)
	s_barrier
	s_waitcnt lgkmcnt(0)
	v_mfma_f32_16x16x32_bf16 v[124:127], v[128:131], v[144:147], v[124:127]
	v_mfma_f32_16x16x32_bf16 v[120:123], v[136:139], v[144:147], v[120:123]
	v_mfma_f32_16x16x32_bf16 v[108:111], v[128:131], v[152:155], v[108:111]
	v_mfma_f32_16x16x32_bf16 v[104:107], v[136:139], v[152:155], v[104:107]
	v_mfma_f32_16x16x32_bf16 v[92:95], v[128:131], v[160:163], v[92:95]
	v_mfma_f32_16x16x32_bf16 v[88:91], v[136:139], v[160:163], v[88:91]
	v_mfma_f32_16x16x32_bf16 v[76:79], v[128:131], v[168:171], v[76:79]
	v_mfma_f32_16x16x32_bf16 v[72:75], v[136:139], v[168:171], v[72:75]
	v_mfma_f32_16x16x32_bf16 v[124:127], v[132:135], v[148:151], v[124:127]
	v_mfma_f32_16x16x32_bf16 v[120:123], v[140:143], v[148:151], v[120:123]
	v_mfma_f32_16x16x32_bf16 v[108:111], v[132:135], v[156:159], v[108:111]
	v_mfma_f32_16x16x32_bf16 v[104:107], v[140:143], v[156:159], v[104:107]
	v_mfma_f32_16x16x32_bf16 v[92:95], v[132:135], v[164:167], v[92:95]
	v_mfma_f32_16x16x32_bf16 v[88:91], v[140:143], v[164:167], v[88:91]
	v_mfma_f32_16x16x32_bf16 v[76:79], v[132:135], v[172:175], v[76:79]
	v_mfma_f32_16x16x32_bf16 v[72:75], v[140:143], v[172:175], v[72:75]
	s_barrier
	s_add_i32 s26, 0, 0x1c000
	s_add_i32 s20, s46, s31
	s_add_u32 s100, s24, 0x80
	s_addc_u32 s101, s25, 0
	s_mov_b32 m0, s20
	ds_read_b128 v[176:179], v219
	ds_read_b128 v[180:183], v219 offset:1024
	ds_read_b128 v[184:187], v219 offset:2048
	ds_read_b128 v[188:191], v219 offset:3072
	global_load_lds_dwordx4 v192, s[100:101]
	s_add_i32 m0, s20, 0x2000
	s_nop 0
	global_load_lds_dwordx4 v210, s[100:101]
	s_barrier
	s_waitcnt lgkmcnt(0)
	v_mfma_f32_16x16x32_bf16 v[116:119], v[176:179], v[144:147], v[116:119]
	v_mfma_f32_16x16x32_bf16 v[112:115], v[184:187], v[144:147], v[112:115]
	v_mfma_f32_16x16x32_bf16 v[100:103], v[176:179], v[152:155], v[100:103]
	v_mfma_f32_16x16x32_bf16 v[96:99], v[184:187], v[152:155], v[96:99]
	v_mfma_f32_16x16x32_bf16 v[84:87], v[176:179], v[160:163], v[84:87]
	v_mfma_f32_16x16x32_bf16 v[80:83], v[184:187], v[160:163], v[80:83]
	v_mfma_f32_16x16x32_bf16 v[68:71], v[176:179], v[168:171], v[68:71]
	v_mfma_f32_16x16x32_bf16 v[64:67], v[184:187], v[168:171], v[64:67]
	v_mfma_f32_16x16x32_bf16 v[116:119], v[180:183], v[148:151], v[116:119]
	v_mfma_f32_16x16x32_bf16 v[112:115], v[188:191], v[148:151], v[112:115]
	v_mfma_f32_16x16x32_bf16 v[100:103], v[180:183], v[156:159], v[100:103]
	v_mfma_f32_16x16x32_bf16 v[96:99], v[188:191], v[156:159], v[96:99]
	v_mfma_f32_16x16x32_bf16 v[84:87], v[180:183], v[164:167], v[84:87]
	v_mfma_f32_16x16x32_bf16 v[80:83], v[188:191], v[164:167], v[80:83]
	v_mfma_f32_16x16x32_bf16 v[68:71], v[180:183], v[172:175], v[68:71]
	v_mfma_f32_16x16x32_bf16 v[64:67], v[188:191], v[172:175], v[64:67]
	s_mov_b32 m0, s38
	s_barrier
	ds_read_b128 v[144:147], v198 offset:49152
	ds_read_b128 v[148:151], v198 offset:50176
	ds_read_b128 v[152:155], v198 offset:51200
	ds_read_b128 v[156:159], v198 offset:52224
	ds_read_b128 v[160:163], v198 offset:53248
	ds_read_b128 v[164:167], v198 offset:54272
	ds_read_b128 v[168:171], v198 offset:55296
	ds_read_b128 v[172:175], v198 offset:56320
	global_load_lds_dwordx4 v206, vcc
	s_mov_b32 m0, s39
	s_nop 0
	global_load_lds_dwordx4 v208, vcc
	s_barrier
	s_waitcnt lgkmcnt(0)
	v_mfma_f32_16x16x32_bf16 v[60:63], v[128:131], v[144:147], v[60:63]
	v_mfma_f32_16x16x32_bf16 v[56:59], v[136:139], v[144:147], v[56:59]
	v_mfma_f32_16x16x32_bf16 v[44:47], v[128:131], v[152:155], v[44:47]
	v_mfma_f32_16x16x32_bf16 v[40:43], v[136:139], v[152:155], v[40:43]
	v_mfma_f32_16x16x32_bf16 v[28:31], v[128:131], v[160:163], v[28:31]
	v_mfma_f32_16x16x32_bf16 v[24:27], v[136:139], v[160:163], v[24:27]
	v_mfma_f32_16x16x32_bf16 v[12:15], v[128:131], v[168:171], v[12:15]
	v_mfma_f32_16x16x32_bf16 v[8:11], v[136:139], v[168:171], v[8:11]
	v_mfma_f32_16x16x32_bf16 v[60:63], v[132:135], v[148:151], v[60:63]
	v_mfma_f32_16x16x32_bf16 v[56:59], v[140:143], v[148:151], v[56:59]
	v_mfma_f32_16x16x32_bf16 v[44:47], v[132:135], v[156:159], v[44:47]
	v_mfma_f32_16x16x32_bf16 v[40:43], v[140:143], v[156:159], v[40:43]
	v_mfma_f32_16x16x32_bf16 v[28:31], v[132:135], v[164:167], v[28:31]
	v_mfma_f32_16x16x32_bf16 v[24:27], v[140:143], v[164:167], v[24:27]
	v_mfma_f32_16x16x32_bf16 v[12:15], v[132:135], v[172:175], v[12:15]
	v_mfma_f32_16x16x32_bf16 v[8:11], v[140:143], v[172:175], v[8:11]
	s_barrier
	s_add_u32 s20, s24, 0xb0080
	s_addc_u32 s21, s25, 0
	s_add_i32 s24, s26, s31
	s_mov_b32 m0, s24
	s_nop 0
	global_load_lds_dwordx4 v192, s[20:21]
	s_add_i32 m0, s24, 0x2000
	s_nop 0
	global_load_lds_dwordx4 v210, s[20:21]
	s_waitcnt vmcnt(6)
	s_barrier
	v_mfma_f32_16x16x32_bf16 v[52:55], v[176:179], v[144:147], v[52:55]
	v_mfma_f32_16x16x32_bf16 v[48:51], v[184:187], v[144:147], v[48:51]
	v_mfma_f32_16x16x32_bf16 v[36:39], v[176:179], v[152:155], v[36:39]
	v_mfma_f32_16x16x32_bf16 v[32:35], v[184:187], v[152:155], v[32:35]
	v_mfma_f32_16x16x32_bf16 v[20:23], v[176:179], v[160:163], v[20:23]
	v_mfma_f32_16x16x32_bf16 v[16:19], v[184:187], v[160:163], v[16:19]
	v_mfma_f32_16x16x32_bf16 v[4:7], v[176:179], v[168:171], v[4:7]
	v_mfma_f32_16x16x32_bf16 v[0:3], v[184:187], v[168:171], v[0:3]
	v_mfma_f32_16x16x32_bf16 v[52:55], v[180:183], v[148:151], v[52:55]
	v_mfma_f32_16x16x32_bf16 v[48:51], v[188:191], v[148:151], v[48:51]
	v_mfma_f32_16x16x32_bf16 v[36:39], v[180:183], v[156:159], v[36:39]
	v_mfma_f32_16x16x32_bf16 v[32:35], v[188:191], v[156:159], v[32:35]
	v_mfma_f32_16x16x32_bf16 v[20:23], v[180:183], v[164:167], v[20:23]
	v_mfma_f32_16x16x32_bf16 v[16:19], v[188:191], v[164:167], v[16:19]
	v_mfma_f32_16x16x32_bf16 v[4:7], v[180:183], v[172:175], v[4:7]
	v_mfma_f32_16x16x32_bf16 v[0:3], v[188:191], v[172:175], v[0:3]
	s_add_i32 s45, s45, 2
	s_add_u32 s33, s33, 0x100
	s_addc_u32 s44, s44, 0
	s_cmp_gt_u32 s45, 41
	s_mov_b64 s[20:21], s[22:23]
	s_barrier
	s_cbranch_scc0 .LBB0_1623
	v_mov_b32_e32 v128, v252
	s_lshl_b32 s1, s1, 8
	v_readfirstlane_b32 s20, v128
	s_ashr_i32 s21, s20, 2
	s_andn2_b32 s21, s21, 63
	s_add_i32 s21, s21, s1
	s_lshr_b32 s1, s20, 1
	s_and_b32 s1, s1, 0x60
	s_lshl_b32 s0, s0, 8
	v_and_or_b32 v244, v128, 15, s21
	v_lshrrev_b32_e32 v128, 1, v128
	s_or_b32 s0, s1, s0
	v_and_b32_e32 v129, 64, v195
	v_and_or_b32 v216, v128, 24, s0
	v_xor_b32_e32 v128, 16, v195
	v_add_u32_e32 v129, 64, v129
	v_cmp_lt_i32_e32 vcc, v128, v129
	v_ashrrev_i32_e32 v245, 31, v244
	v_lshlrev_b64 v[220:221], 10, v[244:245]
	v_cndmask_b32_e32 v128, v195, v128, vcc
	v_lshlrev_b32_e32 v200, 2, v128
	v_xor_b32_e32 v128, 32, v195
	v_cmp_lt_i32_e32 vcc, v128, v129
	v_ashrrev_i32_e32 v217, 31, v216
	v_or_b32_e32 v218, 0x80, v216
	v_cndmask_b32_e32 v128, v195, v128, vcc
	v_lshlrev_b32_e32 v199, 2, v128
	v_lshl_add_u64 v[128:129], v[220:221], 0, v[216:217]
	v_lshlrev_b64 v[128:129], 1, v[128:129]
	v_lshl_add_u64 v[240:241], s[18:19], 0, v[128:129]
	v_lshl_add_u64 v[246:247], s[10:11], 0, v[128:129]
	global_load_dwordx4 v[188:191], v[240:241], off
	global_load_dwordx4 v[180:183], v[240:241], off offset:256
	global_load_dwordx4 v[184:187], v[246:247], off
	v_ashrrev_i32_e32 v219, 31, v218
	v_lshl_add_u64 v[128:129], v[220:221], 0, v[218:219]
	v_lshl_add_u64 v[242:243], v[128:129], 1, s[10:11]
	v_or_b32_e32 v128, 16, v244
	v_ashrrev_i32_e32 v129, 31, v128
	v_lshlrev_b64 v[128:129], 10, v[128:129]
	v_lshl_add_u64 v[130:131], v[128:129], 0, v[216:217]
	v_lshl_add_u64 v[128:129], v[128:129], 0, v[218:219]
	v_lshl_add_u64 v[236:237], v[128:129], 1, s[10:11]
	v_or_b32_e32 v128, 32, v244
	v_ashrrev_i32_e32 v129, 31, v128
	v_lshlrev_b64 v[130:131], 1, v[130:131]
	v_lshlrev_b64 v[128:129], 10, v[128:129]
	v_lshl_add_u64 v[234:235], s[18:19], 0, v[130:131]
	v_lshl_add_u64 v[238:239], s[10:11], 0, v[130:131]
	v_lshl_add_u64 v[130:131], v[128:129], 0, v[216:217]
	v_lshl_add_u64 v[128:129], v[128:129], 0, v[218:219]
	v_lshl_add_u64 v[230:231], v[128:129], 1, s[10:11]
	v_or_b32_e32 v128, 48, v244
	v_ashrrev_i32_e32 v129, 31, v128
	v_lshlrev_b64 v[130:131], 1, v[130:131]
	v_lshlrev_b64 v[128:129], 10, v[128:129]
	v_lshl_add_u64 v[226:227], s[18:19], 0, v[130:131]
	v_lshl_add_u64 v[232:233], s[10:11], 0, v[130:131]
	v_lshl_add_u64 v[130:131], v[128:129], 0, v[216:217]
	v_lshlrev_b64 v[130:131], 1, v[130:131]
	v_lshl_add_u64 v[132:133], v[128:129], 0, v[218:219]
	v_lshl_add_u64 v[222:223], s[18:19], 0, v[130:131]
	v_lshl_add_u64 v[228:229], s[10:11], 0, v[130:131]
	v_lshl_add_u64 v[224:225], v[132:133], 1, s[10:11]
	global_load_dwordx4 v[176:179], v[242:243], off
	global_load_dwordx4 v[172:175], v[234:235], off
	global_load_dwordx4 v[164:167], v[234:235], off offset:256
	global_load_dwordx4 v[168:171], v[238:239], off
	global_load_dwordx4 v[160:163], v[236:237], off
	global_load_dwordx4 v[156:159], v[226:227], off
	global_load_dwordx4 v[132:135], v[224:225], off
	global_load_dwordx4 v[152:155], v[232:233], off
	global_load_dwordx4 v[144:147], v[230:231], off
	global_load_dwordx4 v[148:151], v[226:227], off offset:256
	global_load_dwordx4 v[136:139], v[228:229], off
	global_load_dwordx4 v[140:143], v[222:223], off
	global_load_dwordx4 v[128:131], v[222:223], off offset:256
	v_cmp_gt_u32_e32 vcc, 16, v195
	s_waitcnt vmcnt(0)
	v_lshlrev_b32_e32 v248, 16, v188
	v_and_b32_e32 v249, 0xffff0000, v188
	v_lshlrev_b32_e32 v250, 16, v184
	v_and_b32_e32 v251, 0xffff0000, v184
	v_lshlrev_b32_e32 v188, 16, v189
	v_and_b32_e32 v189, 0xffff0000, v189
	v_lshlrev_b32_e32 v184, 16, v185
	v_and_b32_e32 v185, 0xffff0000, v185
	v_pk_add_f32 v[248:249], v[248:249], v[250:251]
	v_pk_add_f32 v[184:185], v[188:189], v[184:185]
	v_pk_fma_f32 v[188:189], v[124:125], 0.5, v[248:249] op_sel_hi:[1,0,1]
	v_pk_fma_f32 v[184:185], v[126:127], 0.5, v[184:185] op_sel_hi:[1,0,1]
	v_lshlrev_b32_e32 v124, 16, v190
	v_and_b32_e32 v125, 0xffff0000, v190
	v_lshlrev_b32_e32 v126, 16, v186
	v_and_b32_e32 v127, 0xffff0000, v186
	v_pk_add_f32 v[124:125], v[124:125], v[126:127]
	v_lshlrev_b32_e32 v126, 16, v191
	v_and_b32_e32 v127, 0xffff0000, v191
	v_lshlrev_b32_e32 v186, 16, v187
	v_and_b32_e32 v187, 0xffff0000, v187
	v_pk_add_f32 v[126:127], v[126:127], v[186:187]
	v_pk_fma_f32 v[190:191], v[120:121], 0.5, v[124:125] op_sel_hi:[1,0,1]
	v_cvt_pk_bf16_f32 v120, v188, v189
	v_pk_fma_f32 v[186:187], v[122:123], 0.5, v[126:127] op_sel_hi:[1,0,1]
	v_and_b32_e32 v123, 0xffff0000, v120
	v_lshlrev_b32_e32 v122, 16, v120
	v_pk_add_f32 v[122:123], v[188:189], v[122:123] neg_lo:[0,1] neg_hi:[0,1]
	v_cvt_pk_bf16_f32 v121, v184, v185
	v_cvt_pk_bf16_f32 v124, v122, v123
	v_and_b32_e32 v123, 0xffff0000, v121
	v_lshlrev_b32_e32 v122, 16, v121
	v_pk_add_f32 v[122:123], v[184:185], v[122:123] neg_lo:[0,1] neg_hi:[0,1]
	s_nop 0
	v_cvt_pk_bf16_f32 v125, v122, v123
	v_cvt_pk_bf16_f32 v122, v190, v191
	v_cvt_pk_bf16_f32 v123, v186, v187
	v_and_b32_e32 v127, 0xffff0000, v122
	v_lshlrev_b32_e32 v126, 16, v122
	v_and_b32_e32 v249, 0xffff0000, v123
	v_lshlrev_b32_e32 v248, 16, v123
	v_pk_add_f32 v[126:127], v[190:191], v[126:127] neg_lo:[0,1] neg_hi:[0,1]
	v_pk_add_f32 v[248:249], v[186:187], v[248:249] neg_lo:[0,1] neg_hi:[0,1]
	v_cvt_pk_bf16_f32 v126, v126, v127
	v_cvt_pk_bf16_f32 v127, v248, v249
	global_store_dwordx4 v[240:241], v[120:123], off
	global_store_dwordx4 v[246:247], v[124:127], off
	s_nop 0
	v_pk_mul_f32 v[122:123], v[190:191], v[190:191]
	v_pk_mul_f32 v[120:121], v[186:187], v[186:187]
	v_pk_fma_f32 v[122:123], v[188:189], v[188:189], v[122:123]
	v_pk_fma_f32 v[120:121], v[184:185], v[184:185], v[120:121]
	v_add_f32_e32 v122, v122, v123
	v_add_f32_e32 v120, v120, v122
	v_add_f32_e32 v120, v121, v120
	ds_bpermute_b32 v121, v200, v120
	v_lshl_add_u64 v[184:185], v[244:245], 2, s[14:15]
	s_waitcnt lgkmcnt(0)
	v_add_f32_e32 v120, v120, v121
	ds_bpermute_b32 v121, v199, v120
	s_and_saveexec_b64 s[20:21], vcc
	s_cbranch_execz .LBB0_1626
	s_waitcnt lgkmcnt(0)
	v_add_f32_e32 v120, v120, v121
	global_atomic_add_f32 v[184:185], v120, off

.LBB0_2148:
	s_add_u32 s34, s30, 0xfffc0080
	s_addc_u32 s35, s31, -1
	s_add_i32 s51, 0, 0x10000
	v_add_u32_e32 v146, s51, v148
	ds_read_b128 v[138:141], v146
	ds_read_b128 v[142:145], v146 offset:1024
	ds_read_b128 v[150:153], v146 offset:2048
	ds_read_b128 v[154:157], v146 offset:3072
	s_cmp_eq_u32 s33, 12
	s_cselect_b32 s37, s0, s35
	s_cselect_b32 s36, s1, s34
	s_cselect_b32 s35, s7, s25
	s_cselect_b32 s34, s9, s19
	s_add_i32 m0, s44, 0xc000
	ds_read_b128 v[158:161], v149
	ds_read_b128 v[162:165], v149 offset:1024
	ds_read_b128 v[166:169], v149 offset:2048
	ds_read_b128 v[170:173], v149 offset:3072
	ds_read_b128 v[174:177], v149 offset:4096
	ds_read_b128 v[178:181], v149 offset:5120
	ds_read_b128 v[182:185], v149 offset:6144
	ds_read_b128 v[186:189], v149 offset:7168
	global_load_lds_dwordx4 v134, s[30:31]
	s_add_i32 m0, s44, 0xe000
	s_nop 0
	global_load_lds_dwordx4 v136, s[30:31]
	s_waitcnt lgkmcnt(8)
	s_barrier
	s_waitcnt lgkmcnt(0)
	v_mfma_f32_16x16x32_bf16 v[124:127], v[138:141], v[158:161], v[124:127]
	v_mfma_f32_16x16x32_bf16 v[120:123], v[150:153], v[158:161], v[120:123]
	v_mfma_f32_16x16x32_bf16 v[108:111], v[138:141], v[166:169], v[108:111]
	v_mfma_f32_16x16x32_bf16 v[104:107], v[150:153], v[166:169], v[104:107]
	v_mfma_f32_16x16x32_bf16 v[92:95], v[138:141], v[174:177], v[92:95]
	v_mfma_f32_16x16x32_bf16 v[88:91], v[150:153], v[174:177], v[88:91]
	v_mfma_f32_16x16x32_bf16 v[76:79], v[138:141], v[182:185], v[76:79]
	v_mfma_f32_16x16x32_bf16 v[72:75], v[150:153], v[182:185], v[72:75]
	v_mfma_f32_16x16x32_bf16 v[124:127], v[142:145], v[162:165], v[124:127]
	v_mfma_f32_16x16x32_bf16 v[120:123], v[154:157], v[162:165], v[120:123]
	v_mfma_f32_16x16x32_bf16 v[108:111], v[142:145], v[170:173], v[108:111]
	v_mfma_f32_16x16x32_bf16 v[104:107], v[154:157], v[170:173], v[104:107]
	v_mfma_f32_16x16x32_bf16 v[92:95], v[142:145], v[178:181], v[92:95]
	v_mfma_f32_16x16x32_bf16 v[88:91], v[154:157], v[178:181], v[88:91]
	v_mfma_f32_16x16x32_bf16 v[76:79], v[142:145], v[186:189], v[76:79]
	v_mfma_f32_16x16x32_bf16 v[72:75], v[154:157], v[186:189], v[72:75]
	s_barrier
	s_add_i32 s54, 0, 0x14000
	v_add_u32_e32 v146, s54, v148
	s_add_i32 s51, s51, s43
	ds_read_b128 v[198:201], v146
	ds_read_b128 v[206:209], v146 offset:1024
	ds_read_b128 v[210:213], v146 offset:2048
	ds_read_b128 v[214:217], v146 offset:3072
	s_mov_b32 m0, s51
	s_nop 0
	global_load_lds_dwordx4 v192, s[34:35]
	s_add_i32 m0, s51, 0x2000
	s_nop 0
	global_load_lds_dwordx4 v132, s[34:35]
	s_barrier
	s_waitcnt lgkmcnt(0)
	v_mfma_f32_16x16x32_bf16 v[116:119], v[198:201], v[158:161], v[116:119]
	v_mfma_f32_16x16x32_bf16 v[112:115], v[210:213], v[158:161], v[112:115]
	v_mfma_f32_16x16x32_bf16 v[100:103], v[198:201], v[166:169], v[100:103]
	v_mfma_f32_16x16x32_bf16 v[96:99], v[210:213], v[166:169], v[96:99]
	v_mfma_f32_16x16x32_bf16 v[84:87], v[198:201], v[174:177], v[84:87]
	v_mfma_f32_16x16x32_bf16 v[80:83], v[210:213], v[174:177], v[80:83]
	v_mfma_f32_16x16x32_bf16 v[68:71], v[198:201], v[182:185], v[68:71]
	v_mfma_f32_16x16x32_bf16 v[64:67], v[210:213], v[182:185], v[64:67]
	v_mfma_f32_16x16x32_bf16 v[116:119], v[206:209], v[162:165], v[116:119]
	v_mfma_f32_16x16x32_bf16 v[112:115], v[214:217], v[162:165], v[112:115]
	v_mfma_f32_16x16x32_bf16 v[100:103], v[206:209], v[170:173], v[100:103]
	v_mfma_f32_16x16x32_bf16 v[96:99], v[214:217], v[170:173], v[96:99]
	v_mfma_f32_16x16x32_bf16 v[84:87], v[206:209], v[178:181], v[84:87]
	v_mfma_f32_16x16x32_bf16 v[80:83], v[214:217], v[178:181], v[80:83]
	v_mfma_f32_16x16x32_bf16 v[68:71], v[206:209], v[186:189], v[68:71]
	v_mfma_f32_16x16x32_bf16 v[64:67], v[214:217], v[186:189], v[64:67]
	s_mov_b32 m0, s44
	s_add_u32 vcc_lo, s36, 0x80
	s_addc_u32 vcc_hi, s37, 0
	s_barrier
	ds_read_b128 v[158:161], v149 offset:16384
	ds_read_b128 v[162:165], v149 offset:17408
	ds_read_b128 v[166:169], v149 offset:18432
	ds_read_b128 v[170:173], v149 offset:19456
	ds_read_b128 v[174:177], v149 offset:20480
	ds_read_b128 v[178:181], v149 offset:21504
	ds_read_b128 v[182:185], v149 offset:22528
	ds_read_b128 v[186:189], v149 offset:23552
	global_load_lds_dwordx4 v128, s[36:37]
	s_mov_b32 m0, s45
	s_nop 0
	global_load_lds_dwordx4 v130, s[36:37]
	s_barrier
	s_waitcnt lgkmcnt(0)
	v_mfma_f32_16x16x32_bf16 v[60:63], v[138:141], v[158:161], v[60:63]
	v_mfma_f32_16x16x32_bf16 v[56:59], v[150:153], v[158:161], v[56:59]
	v_mfma_f32_16x16x32_bf16 v[44:47], v[138:141], v[166:169], v[44:47]
	v_mfma_f32_16x16x32_bf16 v[40:43], v[150:153], v[166:169], v[40:43]
	v_mfma_f32_16x16x32_bf16 v[28:31], v[138:141], v[174:177], v[28:31]
	v_mfma_f32_16x16x32_bf16 v[24:27], v[150:153], v[174:177], v[24:27]
	v_mfma_f32_16x16x32_bf16 v[12:15], v[138:141], v[182:185], v[12:15]
	v_mfma_f32_16x16x32_bf16 v[8:11], v[150:153], v[182:185], v[8:11]
	v_mfma_f32_16x16x32_bf16 v[60:63], v[142:145], v[162:165], v[60:63]
	v_mfma_f32_16x16x32_bf16 v[56:59], v[154:157], v[162:165], v[56:59]
	v_mfma_f32_16x16x32_bf16 v[44:47], v[142:145], v[170:173], v[44:47]
	v_mfma_f32_16x16x32_bf16 v[40:43], v[154:157], v[170:173], v[40:43]
	v_mfma_f32_16x16x32_bf16 v[28:31], v[142:145], v[178:181], v[28:31]
	v_mfma_f32_16x16x32_bf16 v[24:27], v[154:157], v[178:181], v[24:27]
	v_mfma_f32_16x16x32_bf16 v[12:15], v[142:145], v[186:189], v[12:15]
	v_mfma_f32_16x16x32_bf16 v[8:11], v[154:157], v[186:189], v[8:11]
	s_barrier
	s_add_u32 s52, s34, 0x40000
	s_addc_u32 s53, s35, 0
	s_add_i32 s51, s54, s43
	s_mov_b32 m0, s51
	s_nop 0
	global_load_lds_dwordx4 v192, s[52:53]
	s_add_i32 m0, s51, 0x2000
	s_nop 0
	global_load_lds_dwordx4 v132, s[52:53]
	s_waitcnt vmcnt(6)
	s_barrier
	v_mfma_f32_16x16x32_bf16 v[52:55], v[198:201], v[158:161], v[52:55]
	v_mfma_f32_16x16x32_bf16 v[48:51], v[210:213], v[158:161], v[48:51]
	v_mfma_f32_16x16x32_bf16 v[36:39], v[198:201], v[166:169], v[36:39]
	v_mfma_f32_16x16x32_bf16 v[32:35], v[210:213], v[166:169], v[32:35]
	v_mfma_f32_16x16x32_bf16 v[20:23], v[198:201], v[174:177], v[20:23]
	v_mfma_f32_16x16x32_bf16 v[16:19], v[210:213], v[174:177], v[16:19]
	v_mfma_f32_16x16x32_bf16 v[4:7], v[198:201], v[182:185], v[4:7]
	v_mfma_f32_16x16x32_bf16 v[0:3], v[210:213], v[182:185], v[0:3]
	v_mfma_f32_16x16x32_bf16 v[52:55], v[206:209], v[162:165], v[52:55]
	v_mfma_f32_16x16x32_bf16 v[48:51], v[214:217], v[162:165], v[48:51]
	v_mfma_f32_16x16x32_bf16 v[36:39], v[206:209], v[170:173], v[36:39]
	v_mfma_f32_16x16x32_bf16 v[32:35], v[214:217], v[170:173], v[32:35]
	v_mfma_f32_16x16x32_bf16 v[20:23], v[206:209], v[178:181], v[20:23]
	v_mfma_f32_16x16x32_bf16 v[16:19], v[214:217], v[178:181], v[16:19]
	v_mfma_f32_16x16x32_bf16 v[4:7], v[206:209], v[186:189], v[4:7]
	v_mfma_f32_16x16x32_bf16 v[0:3], v[214:217], v[186:189], v[0:3]
	s_add_i32 s51, 0, 0x18000
	v_add_u32_e32 v154, s51, v148
	s_barrier
	ds_read_b128 v[138:141], v154
	ds_read_b128 v[142:145], v154 offset:1024
	ds_read_b128 v[150:153], v154 offset:2048
	ds_read_b128 v[154:157], v154 offset:3072
	s_add_u32 s36, s36, 0x40000
	s_addc_u32 s37, s37, 0
	s_mov_b32 m0, s46
	ds_read_b128 v[158:161], v149 offset:32768
	ds_read_b128 v[162:165], v149 offset:33792
	ds_read_b128 v[166:169], v149 offset:34816
	ds_read_b128 v[170:173], v149 offset:35840
	ds_read_b128 v[174:177], v149 offset:36864
	ds_read_b128 v[178:181], v149 offset:37888
	ds_read_b128 v[182:185], v149 offset:38912
	ds_read_b128 v[186:189], v149 offset:39936
	global_load_lds_dwordx4 v128, s[36:37]
	s_mov_b32 m0, s47
	s_nop 0
	global_load_lds_dwordx4 v130, s[36:37]
	s_waitcnt lgkmcnt(8)
	s_barrier
	s_waitcnt lgkmcnt(0)
	v_mfma_f32_16x16x32_bf16 v[124:127], v[138:141], v[158:161], v[124:127]
	v_mfma_f32_16x16x32_bf16 v[120:123], v[150:153], v[158:161], v[120:123]
	v_mfma_f32_16x16x32_bf16 v[108:111], v[138:141], v[166:169], v[108:111]
	v_mfma_f32_16x16x32_bf16 v[104:107], v[150:153], v[166:169], v[104:107]
	v_mfma_f32_16x16x32_bf16 v[92:95], v[138:141], v[174:177], v[92:95]
	v_mfma_f32_16x16x32_bf16 v[88:91], v[150:153], v[174:177], v[88:91]
	v_mfma_f32_16x16x32_bf16 v[76:79], v[138:141], v[182:185], v[76:79]
	v_mfma_f32_16x16x32_bf16 v[72:75], v[150:153], v[182:185], v[72:75]
	v_mfma_f32_16x16x32_bf16 v[124:127], v[142:145], v[162:165], v[124:127]
	v_mfma_f32_16x16x32_bf16 v[120:123], v[154:157], v[162:165], v[120:123]
	v_mfma_f32_16x16x32_bf16 v[108:111], v[142:145], v[170:173], v[108:111]
	v_mfma_f32_16x16x32_bf16 v[104:107], v[154:157], v[170:173], v[104:107]
	v_mfma_f32_16x16x32_bf16 v[92:95], v[142:145], v[178:181], v[92:95]
	v_mfma_f32_16x16x32_bf16 v[88:91], v[154:157], v[178:181], v[88:91]
	v_mfma_f32_16x16x32_bf16 v[76:79], v[142:145], v[186:189], v[76:79]
	v_mfma_f32_16x16x32_bf16 v[72:75], v[154:157], v[186:189], v[72:75]
	s_barrier
	s_add_i32 s36, 0, 0x1c000
	s_add_i32 s37, s51, s43
	v_add_u32_e32 v196, s36, v148
	s_add_u32 s100, s34, 0x80
	s_addc_u32 s101, s35, 0
	s_mov_b32 m0, s37
	ds_read_b128 v[198:201], v196
	ds_read_b128 v[206:209], v196 offset:1024
	ds_read_b128 v[210:213], v196 offset:2048
	ds_read_b128 v[214:217], v196 offset:3072
	global_load_lds_dwordx4 v192, s[100:101]
	s_add_i32 m0, s37, 0x2000
	s_nop 0
	global_load_lds_dwordx4 v132, s[100:101]
	s_barrier
	s_waitcnt lgkmcnt(0)
	v_mfma_f32_16x16x32_bf16 v[116:119], v[198:201], v[158:161], v[116:119]
	v_mfma_f32_16x16x32_bf16 v[112:115], v[210:213], v[158:161], v[112:115]
	v_mfma_f32_16x16x32_bf16 v[100:103], v[198:201], v[166:169], v[100:103]
	v_mfma_f32_16x16x32_bf16 v[96:99], v[210:213], v[166:169], v[96:99]
	v_mfma_f32_16x16x32_bf16 v[84:87], v[198:201], v[174:177], v[84:87]
	v_mfma_f32_16x16x32_bf16 v[80:83], v[210:213], v[174:177], v[80:83]
	v_mfma_f32_16x16x32_bf16 v[68:71], v[198:201], v[182:185], v[68:71]
	v_mfma_f32_16x16x32_bf16 v[64:67], v[210:213], v[182:185], v[64:67]
	v_mfma_f32_16x16x32_bf16 v[116:119], v[206:209], v[162:165], v[116:119]
	v_mfma_f32_16x16x32_bf16 v[112:115], v[214:217], v[162:165], v[112:115]
	v_mfma_f32_16x16x32_bf16 v[100:103], v[206:209], v[170:173], v[100:103]
	v_mfma_f32_16x16x32_bf16 v[96:99], v[214:217], v[170:173], v[96:99]
	v_mfma_f32_16x16x32_bf16 v[84:87], v[206:209], v[178:181], v[84:87]
	v_mfma_f32_16x16x32_bf16 v[80:83], v[214:217], v[178:181], v[80:83]
	v_mfma_f32_16x16x32_bf16 v[68:71], v[206:209], v[186:189], v[68:71]
	v_mfma_f32_16x16x32_bf16 v[64:67], v[214:217], v[186:189], v[64:67]
	s_mov_b32 m0, s48
	s_barrier
	ds_read_b128 v[158:161], v149 offset:49152
	ds_read_b128 v[162:165], v149 offset:50176
	ds_read_b128 v[166:169], v149 offset:51200
	ds_read_b128 v[170:173], v149 offset:52224
	ds_read_b128 v[174:177], v149 offset:53248
	ds_read_b128 v[178:181], v149 offset:54272
	ds_read_b128 v[182:185], v149 offset:55296
	ds_read_b128 v[186:189], v149 offset:56320
	global_load_lds_dwordx4 v128, vcc
	s_mov_b32 m0, s49
	s_nop 0
	global_load_lds_dwordx4 v130, vcc
	s_barrier
	s_waitcnt lgkmcnt(0)
	v_mfma_f32_16x16x32_bf16 v[60:63], v[138:141], v[158:161], v[60:63]
	v_mfma_f32_16x16x32_bf16 v[56:59], v[150:153], v[158:161], v[56:59]
	v_mfma_f32_16x16x32_bf16 v[44:47], v[138:141], v[166:169], v[44:47]
	v_mfma_f32_16x16x32_bf16 v[40:43], v[150:153], v[166:169], v[40:43]
	v_mfma_f32_16x16x32_bf16 v[28:31], v[138:141], v[174:177], v[28:31]
	v_mfma_f32_16x16x32_bf16 v[24:27], v[150:153], v[174:177], v[24:27]
	v_mfma_f32_16x16x32_bf16 v[12:15], v[138:141], v[182:185], v[12:15]
	v_mfma_f32_16x16x32_bf16 v[8:11], v[150:153], v[182:185], v[8:11]
	v_mfma_f32_16x16x32_bf16 v[60:63], v[142:145], v[162:165], v[60:63]
	v_mfma_f32_16x16x32_bf16 v[56:59], v[154:157], v[162:165], v[56:59]
	v_mfma_f32_16x16x32_bf16 v[44:47], v[142:145], v[170:173], v[44:47]
	v_mfma_f32_16x16x32_bf16 v[40:43], v[154:157], v[170:173], v[40:43]
	v_mfma_f32_16x16x32_bf16 v[28:31], v[142:145], v[178:181], v[28:31]
	v_mfma_f32_16x16x32_bf16 v[24:27], v[154:157], v[178:181], v[24:27]
	v_mfma_f32_16x16x32_bf16 v[12:15], v[142:145], v[186:189], v[12:15]
	v_mfma_f32_16x16x32_bf16 v[8:11], v[154:157], v[186:189], v[8:11]
	s_barrier
	s_add_u32 s34, s34, 0x40080
	s_addc_u32 s35, s35, 0
	s_add_i32 s36, s36, s43
	s_mov_b32 m0, s36
	s_nop 0
	global_load_lds_dwordx4 v192, s[34:35]
	s_add_i32 m0, s36, 0x2000
	s_nop 0
	global_load_lds_dwordx4 v132, s[34:35]
	s_waitcnt vmcnt(6)
	s_barrier
	v_mfma_f32_16x16x32_bf16 v[52:55], v[198:201], v[158:161], v[52:55]
	v_mfma_f32_16x16x32_bf16 v[48:51], v[210:213], v[158:161], v[48:51]
	v_mfma_f32_16x16x32_bf16 v[36:39], v[198:201], v[166:169], v[36:39]
	v_mfma_f32_16x16x32_bf16 v[32:35], v[210:213], v[166:169], v[32:35]
	v_mfma_f32_16x16x32_bf16 v[20:23], v[198:201], v[174:177], v[20:23]
	v_mfma_f32_16x16x32_bf16 v[16:19], v[210:213], v[174:177], v[16:19]
	v_mfma_f32_16x16x32_bf16 v[4:7], v[198:201], v[182:185], v[4:7]
	v_mfma_f32_16x16x32_bf16 v[0:3], v[210:213], v[182:185], v[0:3]
	v_mfma_f32_16x16x32_bf16 v[52:55], v[206:209], v[162:165], v[52:55]
	v_mfma_f32_16x16x32_bf16 v[48:51], v[214:217], v[162:165], v[48:51]
	v_mfma_f32_16x16x32_bf16 v[36:39], v[206:209], v[170:173], v[36:39]
	v_mfma_f32_16x16x32_bf16 v[32:35], v[214:217], v[170:173], v[32:35]
	v_mfma_f32_16x16x32_bf16 v[20:23], v[206:209], v[178:181], v[20:23]
	v_mfma_f32_16x16x32_bf16 v[16:19], v[214:217], v[178:181], v[16:19]
	v_mfma_f32_16x16x32_bf16 v[4:7], v[206:209], v[186:189], v[4:7]
	v_mfma_f32_16x16x32_bf16 v[0:3], v[214:217], v[186:189], v[0:3]
	s_add_i32 s33, s33, 2
	s_add_u32 s30, s30, 0x100
	s_addc_u32 s31, s31, 0
	s_add_u32 s19, s19, 0x100
	s_addc_u32 s25, s25, 0
	s_cmp_gt_u32 s33, 13
	s_barrier
	s_cbranch_scc0 .LBB0_2148
	v_mov_b32_e32 v138, v252
	s_lshl_b32 s1, s8, 8
	v_readfirstlane_b32 s0, v138
	s_ashr_i32 s7, s0, 2
	s_andn2_b32 s7, s7, 63
	s_add_i32 s7, s7, s1
	v_and_or_b32 v140, v138, 15, s7
	v_ashrrev_i32_e32 v141, 31, v140
	v_lshl_add_u64 v[142:143], v[140:141], 2, s[14:15]
	global_load_dword v139, v[142:143], off
	global_load_dword v153, v[142:143], off offset:64
	global_load_dword v152, v[142:143], off offset:128
	global_load_dword v151, v[142:143], off offset:192
	s_lshl_b32 s1, s6, 8
	s_lshr_b32 s0, s0, 1
	s_and_b32 s0, s0, 0x60
	v_lshrrev_b32_e32 v138, 1, v138
	s_or_b32 s0, s0, s1
	v_and_or_b32 v138, v138, 24, s0
	v_mad_i64_i32 v[154:155], s[0:1], v140, s55, 0
	v_cmp_gt_i32_e32 vcc, s55, v138
	s_waitcnt vmcnt(0)
	v_fmamk_f32 v139, v139, 0x3a800000, v194
	v_mul_f32_e32 v144, 0x4b800000, v139
	v_cmp_gt_f32_e64 s[6:7], s2, v139
	s_nop 1
	v_cndmask_b32_e64 v139, v139, v144, s[6:7]
	v_rsq_f32_e32 v144, v139
	v_ashrrev_i32_e32 v139, 31, v138
	v_mul_f32_e32 v145, 0x45800000, v144
	v_cndmask_b32_e64 v144, v144, v145, s[6:7]
	v_pk_mul_f32 v[126:127], v[126:127], v[144:145] op_sel_hi:[1,0]
	v_pk_mul_f32 v[124:125], v[124:125], v[144:145] op_sel_hi:[1,0]
	v_pk_mul_f32 v[146:147], v[122:123], v[144:145] op_sel_hi:[1,0]
	v_pk_mul_f32 v[120:121], v[120:121], v[144:145] op_sel_hi:[1,0]
	v_lshl_add_u64 v[122:123], v[154:155], 1, s[12:13]
	s_and_saveexec_b64 s[6:7], vcc
	s_cbranch_execz .LBB0_2151
	v_cvt_pk_bf16_f32 v150, v125, v127
	v_cvt_pk_bf16_f32 v145, v124, v126
	v_and_b32_e32 v154, 0xffff0000, v150
	v_lshlrev_b32_e32 v150, 16, v150
	v_or_b32_sdwa v155, v154, v145 dst_sel:DWORD dst_unused:UNUSED_PAD src0_sel:DWORD src1_sel:WORD_1
	v_or_b32_sdwa v154, v150, v145 dst_sel:DWORD dst_unused:UNUSED_PAD src0_sel:DWORD src1_sel:WORD_0
	v_cvt_pk_bf16_f32 v150, v121, v147
	v_cvt_pk_bf16_f32 v145, v120, v146
	v_and_b32_e32 v156, 0xffff0000, v150
	v_lshlrev_b32_e32 v150, 16, v150
	v_lshl_add_u64 v[158:159], v[138:139], 1, v[122:123]
	v_or_b32_sdwa v157, v156, v145 dst_sel:DWORD dst_unused:UNUSED_PAD src0_sel:DWORD src1_sel:WORD_1
	v_or_b32_sdwa v156, v150, v145 dst_sel:DWORD dst_unused:UNUSED_PAD src0_sel:DWORD src1_sel:WORD_0
	global_store_dwordx4 v[158:159], v[154:157], off

.LBB0_2292:
	s_add_u32 s8, s12, 0x100
	s_addc_u32 s9, s13, 0
	s_add_i32 s53, 0, 0x10000
	v_add_u32_e32 v140, s53, v196
	ds_read_b128 v[128:131], v140
	ds_read_b128 v[132:135], v140 offset:1024
	ds_read_b128 v[136:139], v140 offset:2048
	ds_read_b128 v[140:143], v140 offset:3072
	s_cmp_eq_u32 s52, 2
	s_cselect_b32 s15, s31, s9
	s_cselect_b32 s14, s30, s8
	s_cselect_b32 s11, s35, s51
	s_cselect_b32 s10, s34, s33
	s_add_i32 m0, s42, 0xc000
	ds_read_b128 v[144:147], v198
	ds_read_b128 v[148:151], v198 offset:1024
	ds_read_b128 v[152:155], v198 offset:2048
	ds_read_b128 v[156:159], v198 offset:3072
	ds_read_b128 v[160:163], v198 offset:4096
	ds_read_b128 v[164:167], v198 offset:5120
	ds_read_b128 v[168:171], v198 offset:6144
	ds_read_b128 v[172:175], v198 offset:7168
	global_load_lds_dwordx4 v190, s[12:13]
	s_add_i32 m0, s42, 0xe000
	s_nop 0
	global_load_lds_dwordx4 v206, s[12:13]
	s_waitcnt lgkmcnt(8)
	s_barrier
	s_waitcnt lgkmcnt(0)
	v_mfma_f32_16x16x32_bf16 v[124:127], v[128:131], v[144:147], v[124:127]
	v_mfma_f32_16x16x32_bf16 v[120:123], v[136:139], v[144:147], v[120:123]
	v_mfma_f32_16x16x32_bf16 v[108:111], v[128:131], v[152:155], v[108:111]
	v_mfma_f32_16x16x32_bf16 v[104:107], v[136:139], v[152:155], v[104:107]
	v_mfma_f32_16x16x32_bf16 v[92:95], v[128:131], v[160:163], v[92:95]
	v_mfma_f32_16x16x32_bf16 v[88:91], v[136:139], v[160:163], v[88:91]
	v_mfma_f32_16x16x32_bf16 v[76:79], v[128:131], v[168:171], v[76:79]
	v_mfma_f32_16x16x32_bf16 v[72:75], v[136:139], v[168:171], v[72:75]
	v_mfma_f32_16x16x32_bf16 v[124:127], v[132:135], v[148:151], v[124:127]
	v_mfma_f32_16x16x32_bf16 v[120:123], v[140:143], v[148:151], v[120:123]
	v_mfma_f32_16x16x32_bf16 v[108:111], v[132:135], v[156:159], v[108:111]
	v_mfma_f32_16x16x32_bf16 v[104:107], v[140:143], v[156:159], v[104:107]
	v_mfma_f32_16x16x32_bf16 v[92:95], v[132:135], v[164:167], v[92:95]
	v_mfma_f32_16x16x32_bf16 v[88:91], v[140:143], v[164:167], v[88:91]
	v_mfma_f32_16x16x32_bf16 v[76:79], v[132:135], v[172:175], v[76:79]
	v_mfma_f32_16x16x32_bf16 v[72:75], v[140:143], v[172:175], v[72:75]
	s_barrier
	s_add_i32 s54, 0, 0x14000
	v_add_u32_e32 v184, s54, v196
	s_add_i32 s12, s53, s41
	ds_read_b128 v[176:179], v184
	ds_read_b128 v[180:183], v184 offset:1024
	ds_read_b128 v[208:211], v184 offset:2048
	ds_read_b128 v[212:215], v184 offset:3072
	s_mov_b32 m0, s12
	s_nop 0
	global_load_lds_dwordx4 v186, s[10:11]
	s_add_i32 m0, s12, 0x2000
	s_nop 0
	global_load_lds_dwordx4 v188, s[10:11]
	s_barrier
	s_waitcnt lgkmcnt(0)
	v_mfma_f32_16x16x32_bf16 v[116:119], v[176:179], v[144:147], v[116:119]
	v_mfma_f32_16x16x32_bf16 v[112:115], v[208:211], v[144:147], v[112:115]
	v_mfma_f32_16x16x32_bf16 v[100:103], v[176:179], v[152:155], v[100:103]
	v_mfma_f32_16x16x32_bf16 v[96:99], v[208:211], v[152:155], v[96:99]
	v_mfma_f32_16x16x32_bf16 v[84:87], v[176:179], v[160:163], v[84:87]
	v_mfma_f32_16x16x32_bf16 v[80:83], v[208:211], v[160:163], v[80:83]
	v_mfma_f32_16x16x32_bf16 v[68:71], v[176:179], v[168:171], v[68:71]
	v_mfma_f32_16x16x32_bf16 v[64:67], v[208:211], v[168:171], v[64:67]
	v_mfma_f32_16x16x32_bf16 v[116:119], v[180:183], v[148:151], v[116:119]
	v_mfma_f32_16x16x32_bf16 v[112:115], v[212:215], v[148:151], v[112:115]
	v_mfma_f32_16x16x32_bf16 v[100:103], v[180:183], v[156:159], v[100:103]
	v_mfma_f32_16x16x32_bf16 v[96:99], v[212:215], v[156:159], v[96:99]
	v_mfma_f32_16x16x32_bf16 v[84:87], v[180:183], v[164:167], v[84:87]
	v_mfma_f32_16x16x32_bf16 v[80:83], v[212:215], v[164:167], v[80:83]
	v_mfma_f32_16x16x32_bf16 v[68:71], v[180:183], v[172:175], v[68:71]
	v_mfma_f32_16x16x32_bf16 v[64:67], v[212:215], v[172:175], v[64:67]
	s_mov_b32 m0, s42
	s_barrier
	ds_read_b128 v[144:147], v198 offset:16384
	ds_read_b128 v[148:151], v198 offset:17408
	ds_read_b128 v[152:155], v198 offset:18432
	ds_read_b128 v[156:159], v198 offset:19456
	ds_read_b128 v[160:163], v198 offset:20480
	ds_read_b128 v[164:167], v198 offset:21504
	ds_read_b128 v[168:171], v198 offset:22528
	ds_read_b128 v[172:175], v198 offset:23552
	global_load_lds_dwordx4 v186, s[14:15]
	s_mov_b32 m0, s43
	s_nop 0
	global_load_lds_dwordx4 v188, s[14:15]
	s_barrier
	s_waitcnt lgkmcnt(0)
	v_mfma_f32_16x16x32_bf16 v[60:63], v[128:131], v[144:147], v[60:63]
	v_mfma_f32_16x16x32_bf16 v[56:59], v[136:139], v[144:147], v[56:59]
	v_mfma_f32_16x16x32_bf16 v[44:47], v[128:131], v[152:155], v[44:47]
	v_mfma_f32_16x16x32_bf16 v[40:43], v[136:139], v[152:155], v[40:43]
	v_mfma_f32_16x16x32_bf16 v[28:31], v[128:131], v[160:163], v[28:31]
	v_mfma_f32_16x16x32_bf16 v[24:27], v[136:139], v[160:163], v[24:27]
	v_mfma_f32_16x16x32_bf16 v[12:15], v[128:131], v[168:171], v[12:15]
	v_mfma_f32_16x16x32_bf16 v[8:11], v[136:139], v[168:171], v[8:11]
	v_mfma_f32_16x16x32_bf16 v[60:63], v[132:135], v[148:151], v[60:63]
	v_mfma_f32_16x16x32_bf16 v[56:59], v[140:143], v[148:151], v[56:59]
	v_mfma_f32_16x16x32_bf16 v[44:47], v[132:135], v[156:159], v[44:47]
	v_mfma_f32_16x16x32_bf16 v[40:43], v[140:143], v[156:159], v[40:43]
	v_mfma_f32_16x16x32_bf16 v[28:31], v[132:135], v[164:167], v[28:31]
	v_mfma_f32_16x16x32_bf16 v[24:27], v[140:143], v[164:167], v[24:27]
	v_mfma_f32_16x16x32_bf16 v[12:15], v[132:135], v[172:175], v[12:15]
	v_mfma_f32_16x16x32_bf16 v[8:11], v[140:143], v[172:175], v[8:11]
	s_barrier
	s_add_u32 s12, s10, 0x18000
	s_addc_u32 s13, s11, 0
	s_add_i32 s53, s54, s41
	s_mov_b32 m0, s53
	s_nop 0
	global_load_lds_dwordx4 v186, s[12:13]
	s_add_i32 m0, s53, 0x2000
	s_nop 0
	global_load_lds_dwordx4 v188, s[12:13]
	s_waitcnt vmcnt(6)
	s_barrier
	v_mfma_f32_16x16x32_bf16 v[52:55], v[176:179], v[144:147], v[52:55]
	v_mfma_f32_16x16x32_bf16 v[48:51], v[208:211], v[144:147], v[48:51]
	v_mfma_f32_16x16x32_bf16 v[36:39], v[176:179], v[152:155], v[36:39]
	v_mfma_f32_16x16x32_bf16 v[32:35], v[208:211], v[152:155], v[32:35]
	v_mfma_f32_16x16x32_bf16 v[20:23], v[176:179], v[160:163], v[20:23]
	v_mfma_f32_16x16x32_bf16 v[16:19], v[208:211], v[160:163], v[16:19]
	v_mfma_f32_16x16x32_bf16 v[4:7], v[176:179], v[168:171], v[4:7]
	v_mfma_f32_16x16x32_bf16 v[0:3], v[208:211], v[168:171], v[0:3]
	v_mfma_f32_16x16x32_bf16 v[52:55], v[180:183], v[148:151], v[52:55]
	v_mfma_f32_16x16x32_bf16 v[48:51], v[212:215], v[148:151], v[48:51]
	v_mfma_f32_16x16x32_bf16 v[36:39], v[180:183], v[156:159], v[36:39]
	v_mfma_f32_16x16x32_bf16 v[32:35], v[212:215], v[156:159], v[32:35]
	v_mfma_f32_16x16x32_bf16 v[20:23], v[180:183], v[164:167], v[20:23]
	v_mfma_f32_16x16x32_bf16 v[16:19], v[212:215], v[164:167], v[16:19]
	v_mfma_f32_16x16x32_bf16 v[4:7], v[180:183], v[172:175], v[4:7]
	v_mfma_f32_16x16x32_bf16 v[0:3], v[212:215], v[172:175], v[0:3]
	s_add_i32 s53, 0, 0x18000
	v_add_u32_e32 v140, s53, v196
	s_barrier
	ds_read_b128 v[128:131], v140
	ds_read_b128 v[132:135], v140 offset:1024
	ds_read_b128 v[136:139], v140 offset:2048
	ds_read_b128 v[140:143], v140 offset:3072
	s_add_u32 s12, s14, 0x18000
	s_addc_u32 s13, s15, 0
	s_mov_b32 m0, s44
	ds_read_b128 v[144:147], v198 offset:32768
	ds_read_b128 v[148:151], v198 offset:33792
	ds_read_b128 v[152:155], v198 offset:34816
	ds_read_b128 v[156:159], v198 offset:35840
	ds_read_b128 v[160:163], v198 offset:36864
	ds_read_b128 v[164:167], v198 offset:37888
	ds_read_b128 v[168:171], v198 offset:38912
	ds_read_b128 v[172:175], v198 offset:39936
	global_load_lds_dwordx4 v186, s[12:13]
	s_mov_b32 m0, s45
	s_nop 0
	global_load_lds_dwordx4 v188, s[12:13]
	s_waitcnt lgkmcnt(8)
	s_barrier
	s_waitcnt lgkmcnt(0)
	v_mfma_f32_16x16x32_bf16 v[124:127], v[128:131], v[144:147], v[124:127]
	v_mfma_f32_16x16x32_bf16 v[120:123], v[136:139], v[144:147], v[120:123]
	v_mfma_f32_16x16x32_bf16 v[108:111], v[128:131], v[152:155], v[108:111]
	v_mfma_f32_16x16x32_bf16 v[104:107], v[136:139], v[152:155], v[104:107]
	v_mfma_f32_16x16x32_bf16 v[92:95], v[128:131], v[160:163], v[92:95]
	v_mfma_f32_16x16x32_bf16 v[88:91], v[136:139], v[160:163], v[88:91]
	v_mfma_f32_16x16x32_bf16 v[76:79], v[128:131], v[168:171], v[76:79]
	v_mfma_f32_16x16x32_bf16 v[72:75], v[136:139], v[168:171], v[72:75]
	v_mfma_f32_16x16x32_bf16 v[124:127], v[132:135], v[148:151], v[124:127]
	v_mfma_f32_16x16x32_bf16 v[120:123], v[140:143], v[148:151], v[120:123]
	v_mfma_f32_16x16x32_bf16 v[108:111], v[132:135], v[156:159], v[108:111]
	v_mfma_f32_16x16x32_bf16 v[104:107], v[140:143], v[156:159], v[104:107]
	v_mfma_f32_16x16x32_bf16 v[92:95], v[132:135], v[164:167], v[92:95]
	v_mfma_f32_16x16x32_bf16 v[88:91], v[140:143], v[164:167], v[88:91]
	v_mfma_f32_16x16x32_bf16 v[76:79], v[132:135], v[172:175], v[76:79]
	v_mfma_f32_16x16x32_bf16 v[72:75], v[140:143], v[172:175], v[72:75]
	s_barrier
	s_add_i32 s12, 0, 0x1c000
	s_add_i32 s13, s53, s41
	v_add_u32_e32 v192, s12, v196
	s_add_u32 s100, s10, 0x80
	s_addc_u32 s101, s11, 0
	s_mov_b32 m0, s13
	ds_read_b128 v[176:179], v192
	ds_read_b128 v[180:183], v192 offset:1024
	ds_read_b128 v[208:211], v192 offset:2048
	ds_read_b128 v[212:215], v192 offset:3072
	global_load_lds_dwordx4 v186, s[100:101]
	s_add_i32 m0, s13, 0x2000
	s_nop 0
	global_load_lds_dwordx4 v188, s[100:101]
	s_barrier
	s_waitcnt lgkmcnt(0)
	v_mfma_f32_16x16x32_bf16 v[116:119], v[176:179], v[144:147], v[116:119]
	v_mfma_f32_16x16x32_bf16 v[112:115], v[208:211], v[144:147], v[112:115]
	v_mfma_f32_16x16x32_bf16 v[100:103], v[176:179], v[152:155], v[100:103]
	v_mfma_f32_16x16x32_bf16 v[96:99], v[208:211], v[152:155], v[96:99]
	v_mfma_f32_16x16x32_bf16 v[84:87], v[176:179], v[160:163], v[84:87]
	v_mfma_f32_16x16x32_bf16 v[80:83], v[208:211], v[160:163], v[80:83]
	v_mfma_f32_16x16x32_bf16 v[68:71], v[176:179], v[168:171], v[68:71]
	v_mfma_f32_16x16x32_bf16 v[64:67], v[208:211], v[168:171], v[64:67]
	v_mfma_f32_16x16x32_bf16 v[116:119], v[180:183], v[148:151], v[116:119]
	v_mfma_f32_16x16x32_bf16 v[112:115], v[212:215], v[148:151], v[112:115]
	v_mfma_f32_16x16x32_bf16 v[100:103], v[180:183], v[156:159], v[100:103]
	v_mfma_f32_16x16x32_bf16 v[96:99], v[212:215], v[156:159], v[96:99]
	v_mfma_f32_16x16x32_bf16 v[84:87], v[180:183], v[164:167], v[84:87]
	v_mfma_f32_16x16x32_bf16 v[80:83], v[212:215], v[164:167], v[80:83]
	v_mfma_f32_16x16x32_bf16 v[68:71], v[180:183], v[172:175], v[68:71]
	v_mfma_f32_16x16x32_bf16 v[64:67], v[212:215], v[172:175], v[64:67]
	s_mov_b32 m0, s46
	s_add_u32 s100, s14, 0x80
	s_addc_u32 s101, s15, 0
	s_barrier
	ds_read_b128 v[144:147], v198 offset:49152
	ds_read_b128 v[148:151], v198 offset:50176
	ds_read_b128 v[152:155], v198 offset:51200
	ds_read_b128 v[156:159], v198 offset:52224
	ds_read_b128 v[160:163], v198 offset:53248
	ds_read_b128 v[164:167], v198 offset:54272
	ds_read_b128 v[168:171], v198 offset:55296
	ds_read_b128 v[172:175], v198 offset:56320
	global_load_lds_dwordx4 v186, s[100:101]
	s_mov_b32 m0, s47
	s_nop 0
	global_load_lds_dwordx4 v188, s[100:101]
	s_barrier
	s_waitcnt lgkmcnt(0)
	v_mfma_f32_16x16x32_bf16 v[60:63], v[128:131], v[144:147], v[60:63]
	v_mfma_f32_16x16x32_bf16 v[56:59], v[136:139], v[144:147], v[56:59]
	v_mfma_f32_16x16x32_bf16 v[44:47], v[128:131], v[152:155], v[44:47]
	v_mfma_f32_16x16x32_bf16 v[40:43], v[136:139], v[152:155], v[40:43]
	v_mfma_f32_16x16x32_bf16 v[28:31], v[128:131], v[160:163], v[28:31]
	v_mfma_f32_16x16x32_bf16 v[24:27], v[136:139], v[160:163], v[24:27]
	v_mfma_f32_16x16x32_bf16 v[12:15], v[128:131], v[168:171], v[12:15]
	v_mfma_f32_16x16x32_bf16 v[8:11], v[136:139], v[168:171], v[8:11]
	v_mfma_f32_16x16x32_bf16 v[60:63], v[132:135], v[148:151], v[60:63]
	v_mfma_f32_16x16x32_bf16 v[56:59], v[140:143], v[148:151], v[56:59]
	v_mfma_f32_16x16x32_bf16 v[44:47], v[132:135], v[156:159], v[44:47]
	v_mfma_f32_16x16x32_bf16 v[40:43], v[140:143], v[156:159], v[40:43]
	v_mfma_f32_16x16x32_bf16 v[28:31], v[132:135], v[164:167], v[28:31]
	v_mfma_f32_16x16x32_bf16 v[24:27], v[140:143], v[164:167], v[24:27]
	v_mfma_f32_16x16x32_bf16 v[12:15], v[132:135], v[172:175], v[12:15]
	v_mfma_f32_16x16x32_bf16 v[8:11], v[140:143], v[172:175], v[8:11]
	s_barrier
	s_add_u32 s10, s10, 0x18080
	s_addc_u32 s11, s11, 0
	s_add_i32 s12, s12, s41
	s_mov_b32 m0, s12
	s_nop 0
	global_load_lds_dwordx4 v186, s[10:11]
	s_add_i32 m0, s12, 0x2000
	s_nop 0
	global_load_lds_dwordx4 v188, s[10:11]
	s_waitcnt vmcnt(6)
	s_barrier
	v_mfma_f32_16x16x32_bf16 v[52:55], v[176:179], v[144:147], v[52:55]
	v_mfma_f32_16x16x32_bf16 v[48:51], v[208:211], v[144:147], v[48:51]
	v_mfma_f32_16x16x32_bf16 v[36:39], v[176:179], v[152:155], v[36:39]
	v_mfma_f32_16x16x32_bf16 v[32:35], v[208:211], v[152:155], v[32:35]
	v_mfma_f32_16x16x32_bf16 v[20:23], v[176:179], v[160:163], v[20:23]
	v_mfma_f32_16x16x32_bf16 v[16:19], v[208:211], v[160:163], v[16:19]
	v_mfma_f32_16x16x32_bf16 v[4:7], v[176:179], v[168:171], v[4:7]
	v_mfma_f32_16x16x32_bf16 v[0:3], v[208:211], v[168:171], v[0:3]
	v_mfma_f32_16x16x32_bf16 v[52:55], v[180:183], v[148:151], v[52:55]
	v_mfma_f32_16x16x32_bf16 v[48:51], v[212:215], v[148:151], v[48:51]
	v_mfma_f32_16x16x32_bf16 v[36:39], v[180:183], v[156:159], v[36:39]
	v_mfma_f32_16x16x32_bf16 v[32:35], v[212:215], v[156:159], v[32:35]
	v_mfma_f32_16x16x32_bf16 v[20:23], v[180:183], v[164:167], v[20:23]
	v_mfma_f32_16x16x32_bf16 v[16:19], v[212:215], v[164:167], v[16:19]
	v_mfma_f32_16x16x32_bf16 v[4:7], v[180:183], v[172:175], v[4:7]
	v_mfma_f32_16x16x32_bf16 v[0:3], v[212:215], v[172:175], v[0:3]
	s_add_i32 s52, s52, 2
	s_add_u32 s33, s33, 0x100
	s_addc_u32 s51, s51, 0
	s_cmp_gt_u32 s52, 3
	s_mov_b64 s[12:13], s[8:9]
	s_barrier
	s_cbranch_scc0 .LBB0_2292
	v_mov_b32_e32 v128, v252
	s_lshl_b32 s1, s1, 8
	v_readfirstlane_b32 s8, v128
	s_ashr_i32 s9, s8, 2
	s_andn2_b32 s9, s9, 63
	s_add_i32 s9, s9, s1
	v_and_or_b32 v208, v128, 15, s9
	v_ashrrev_i32_e32 v209, 31, v208
	v_lshl_add_u64 v[210:211], v[208:209], 2, s[26:27]
	global_load_dword v225, v[210:211], off
	s_lshr_b32 s1, s8, 1
	s_and_b32 s1, s1, 0x60
	s_lshl_b32 s0, s0, 8
	v_lshrrev_b32_e32 v128, 2, v128
	s_or_b32 s0, s1, s0
	s_movk_i32 s1, 0x1fcf
	v_and_b32_e32 v226, 12, v128
	v_and_or_b32 v128, v208, s1, 16
	s_movk_i32 s1, 0x4000
	v_cmp_gt_i32_e32 vcc, s1, v208
	s_mul_hi_i32 s1, s0, 0x2aaaaaab
	s_lshr_b32 s8, s1, 31
	s_lshr_b32 s1, s1, 4
	s_add_i32 s1, s1, s8
	s_mulk_i32 s1, 0x60
	v_add_u32_e32 v129, 0x7ffc000, v208
	s_sub_i32 s1, s0, s1
	v_lshlrev_b32_e32 v199, 1, v226
	v_cndmask_b32_e32 v128, v129, v128, vcc
	s_cmp_eq_u32 s1, 64
	v_lshl_or_b32 v192, v128, 5, v199
	s_cselect_b64 s[10:11], -1, 0
	v_lshl_add_u64 v[128:129], v[192:193], 2, s[28:29]
	v_mov_b32_e32 v160, 0
	s_and_b64 vcc, exec, s[10:11]
	v_mov_b32_e32 v178, 0
	v_mov_b32_e32 v218, 0
	v_mov_b32_e32 v179, 0
	v_mov_b32_e32 v219, 0
	v_mov_b32_e32 v182, 0
	v_mov_b32_e32 v220, 0
	v_mov_b32_e32 v183, 0
	v_mov_b32_e32 v221, 0
	s_cbranch_vccz .LBB0_2295
	global_load_dwordx4 v[178:181], v[128:129], off
	global_load_dwordx4 v[182:185], v[128:129], off offset:16
	s_waitcnt vmcnt(0)
	v_mov_b32_e32 v218, v179
	v_mov_b32_e32 v179, v180
	v_mov_b32_e32 v219, v181
	v_mov_b32_e32 v220, v183
	v_mov_b32_e32 v183, v184
	v_mov_b32_e32 v221, v185

.LBB0_2484:
	s_add_u32 s34, s30, 0xfffe0080
	s_addc_u32 s35, s31, -1
	s_add_i32 s53, 0, 0x10000
	v_add_u32_e32 v140, s53, v196
	ds_read_b128 v[128:131], v140
	ds_read_b128 v[132:135], v140 offset:1024
	ds_read_b128 v[136:139], v140 offset:2048
	ds_read_b128 v[140:143], v140 offset:3072
	s_cmp_eq_u32 s52, 4
	s_cselect_b32 s37, s0, s35
	s_cselect_b32 s36, s1, s34
	s_cselect_b32 s35, s15, s33
	s_cselect_b32 s34, s21, s27
	s_add_i32 m0, s29, 0xc000
	ds_read_b128 v[144:147], v198
	ds_read_b128 v[148:151], v198 offset:1024
	ds_read_b128 v[152:155], v198 offset:2048
	ds_read_b128 v[156:159], v198 offset:3072
	ds_read_b128 v[160:163], v198 offset:4096
	ds_read_b128 v[164:167], v198 offset:5120
	ds_read_b128 v[168:171], v198 offset:6144
	ds_read_b128 v[172:175], v198 offset:7168
	global_load_lds_dwordx4 v212, s[30:31]
	s_add_i32 m0, s29, 0xe000
	s_nop 0
	global_load_lds_dwordx4 v214, s[30:31]
	s_waitcnt lgkmcnt(8)
	s_barrier
	s_waitcnt lgkmcnt(0)
	v_mfma_f32_16x16x32_bf16 v[124:127], v[128:131], v[144:147], v[124:127]
	v_mfma_f32_16x16x32_bf16 v[120:123], v[136:139], v[144:147], v[120:123]
	v_mfma_f32_16x16x32_bf16 v[108:111], v[128:131], v[152:155], v[108:111]
	v_mfma_f32_16x16x32_bf16 v[104:107], v[136:139], v[152:155], v[104:107]
	v_mfma_f32_16x16x32_bf16 v[92:95], v[128:131], v[160:163], v[92:95]
	v_mfma_f32_16x16x32_bf16 v[88:91], v[136:139], v[160:163], v[88:91]
	v_mfma_f32_16x16x32_bf16 v[76:79], v[128:131], v[168:171], v[76:79]
	v_mfma_f32_16x16x32_bf16 v[72:75], v[136:139], v[168:171], v[72:75]
	v_mfma_f32_16x16x32_bf16 v[124:127], v[132:135], v[148:151], v[124:127]
	v_mfma_f32_16x16x32_bf16 v[120:123], v[140:143], v[148:151], v[120:123]
	v_mfma_f32_16x16x32_bf16 v[108:111], v[132:135], v[156:159], v[108:111]
	v_mfma_f32_16x16x32_bf16 v[104:107], v[140:143], v[156:159], v[104:107]
	v_mfma_f32_16x16x32_bf16 v[92:95], v[132:135], v[164:167], v[92:95]
	v_mfma_f32_16x16x32_bf16 v[88:91], v[140:143], v[164:167], v[88:91]
	v_mfma_f32_16x16x32_bf16 v[76:79], v[132:135], v[172:175], v[76:79]
	v_mfma_f32_16x16x32_bf16 v[72:75], v[140:143], v[172:175], v[72:75]
	s_barrier
	s_add_i32 s56, 0, 0x14000
	s_add_i32 s53, s53, s45
	v_add_u32_e32 v188, s56, v196
	s_mov_b32 m0, s53
	ds_read_b128 v[176:179], v188
	ds_read_b128 v[180:183], v188 offset:1024
	ds_read_b128 v[184:187], v188 offset:2048
	ds_read_b128 v[188:191], v188 offset:3072
	global_load_lds_dwordx4 v192, s[34:35]
	s_add_i32 m0, s53, 0x2000
	s_nop 0
	global_load_lds_dwordx4 v210, s[34:35]
	s_barrier
	s_waitcnt lgkmcnt(0)
	v_mfma_f32_16x16x32_bf16 v[116:119], v[176:179], v[144:147], v[116:119]
	v_mfma_f32_16x16x32_bf16 v[112:115], v[184:187], v[144:147], v[112:115]
	v_mfma_f32_16x16x32_bf16 v[100:103], v[176:179], v[152:155], v[100:103]
	v_mfma_f32_16x16x32_bf16 v[96:99], v[184:187], v[152:155], v[96:99]
	v_mfma_f32_16x16x32_bf16 v[84:87], v[176:179], v[160:163], v[84:87]
	v_mfma_f32_16x16x32_bf16 v[80:83], v[184:187], v[160:163], v[80:83]
	v_mfma_f32_16x16x32_bf16 v[68:71], v[176:179], v[168:171], v[68:71]
	v_mfma_f32_16x16x32_bf16 v[64:67], v[184:187], v[168:171], v[64:67]
	v_mfma_f32_16x16x32_bf16 v[116:119], v[180:183], v[148:151], v[116:119]
	v_mfma_f32_16x16x32_bf16 v[112:115], v[188:191], v[148:151], v[112:115]
	v_mfma_f32_16x16x32_bf16 v[100:103], v[180:183], v[156:159], v[100:103]
	v_mfma_f32_16x16x32_bf16 v[96:99], v[188:191], v[156:159], v[96:99]
	v_mfma_f32_16x16x32_bf16 v[84:87], v[180:183], v[164:167], v[84:87]
	v_mfma_f32_16x16x32_bf16 v[80:83], v[188:191], v[164:167], v[80:83]
	v_mfma_f32_16x16x32_bf16 v[68:71], v[180:183], v[172:175], v[68:71]
	v_mfma_f32_16x16x32_bf16 v[64:67], v[188:191], v[172:175], v[64:67]
	s_mov_b32 m0, s29
	s_add_u32 vcc_lo, s36, 0x80
	s_addc_u32 vcc_hi, s37, 0
	s_barrier
	ds_read_b128 v[144:147], v198 offset:16384
	ds_read_b128 v[148:151], v198 offset:17408
	ds_read_b128 v[152:155], v198 offset:18432
	ds_read_b128 v[156:159], v198 offset:19456
	ds_read_b128 v[160:163], v198 offset:20480
	ds_read_b128 v[164:167], v198 offset:21504
	ds_read_b128 v[168:171], v198 offset:22528
	ds_read_b128 v[172:175], v198 offset:23552
	global_load_lds_dwordx4 v206, s[36:37]
	s_mov_b32 m0, s46
	s_nop 0
	global_load_lds_dwordx4 v208, s[36:37]
	s_barrier
	s_waitcnt lgkmcnt(0)
	v_mfma_f32_16x16x32_bf16 v[60:63], v[128:131], v[144:147], v[60:63]
	v_mfma_f32_16x16x32_bf16 v[56:59], v[136:139], v[144:147], v[56:59]
	v_mfma_f32_16x16x32_bf16 v[44:47], v[128:131], v[152:155], v[44:47]
	v_mfma_f32_16x16x32_bf16 v[40:43], v[136:139], v[152:155], v[40:43]
	v_mfma_f32_16x16x32_bf16 v[28:31], v[128:131], v[160:163], v[28:31]
	v_mfma_f32_16x16x32_bf16 v[24:27], v[136:139], v[160:163], v[24:27]
	v_mfma_f32_16x16x32_bf16 v[12:15], v[128:131], v[168:171], v[12:15]
	v_mfma_f32_16x16x32_bf16 v[8:11], v[136:139], v[168:171], v[8:11]
	v_mfma_f32_16x16x32_bf16 v[60:63], v[132:135], v[148:151], v[60:63]
	v_mfma_f32_16x16x32_bf16 v[56:59], v[140:143], v[148:151], v[56:59]
	v_mfma_f32_16x16x32_bf16 v[44:47], v[132:135], v[156:159], v[44:47]
	v_mfma_f32_16x16x32_bf16 v[40:43], v[140:143], v[156:159], v[40:43]
	v_mfma_f32_16x16x32_bf16 v[28:31], v[132:135], v[164:167], v[28:31]
	v_mfma_f32_16x16x32_bf16 v[24:27], v[140:143], v[164:167], v[24:27]
	v_mfma_f32_16x16x32_bf16 v[12:15], v[132:135], v[172:175], v[12:15]
	v_mfma_f32_16x16x32_bf16 v[8:11], v[140:143], v[172:175], v[8:11]
	s_barrier
	s_add_u32 s54, s34, 0x20000
	s_addc_u32 s55, s35, 0
	s_add_i32 s53, s56, s45
	s_mov_b32 m0, s53
	s_nop 0
	global_load_lds_dwordx4 v192, s[54:55]
	s_add_i32 m0, s53, 0x2000
	s_nop 0
	global_load_lds_dwordx4 v210, s[54:55]
	s_waitcnt vmcnt(6)
	s_barrier
	v_mfma_f32_16x16x32_bf16 v[52:55], v[176:179], v[144:147], v[52:55]
	v_mfma_f32_16x16x32_bf16 v[48:51], v[184:187], v[144:147], v[48:51]
	v_mfma_f32_16x16x32_bf16 v[36:39], v[176:179], v[152:155], v[36:39]
	v_mfma_f32_16x16x32_bf16 v[32:35], v[184:187], v[152:155], v[32:35]
	v_mfma_f32_16x16x32_bf16 v[20:23], v[176:179], v[160:163], v[20:23]
	v_mfma_f32_16x16x32_bf16 v[16:19], v[184:187], v[160:163], v[16:19]
	v_mfma_f32_16x16x32_bf16 v[4:7], v[176:179], v[168:171], v[4:7]
	v_mfma_f32_16x16x32_bf16 v[0:3], v[184:187], v[168:171], v[0:3]
	v_mfma_f32_16x16x32_bf16 v[52:55], v[180:183], v[148:151], v[52:55]
	v_mfma_f32_16x16x32_bf16 v[48:51], v[188:191], v[148:151], v[48:51]
	v_mfma_f32_16x16x32_bf16 v[36:39], v[180:183], v[156:159], v[36:39]
	v_mfma_f32_16x16x32_bf16 v[32:35], v[188:191], v[156:159], v[32:35]
	v_mfma_f32_16x16x32_bf16 v[20:23], v[180:183], v[164:167], v[20:23]
	v_mfma_f32_16x16x32_bf16 v[16:19], v[188:191], v[164:167], v[16:19]
	v_mfma_f32_16x16x32_bf16 v[4:7], v[180:183], v[172:175], v[4:7]
	v_mfma_f32_16x16x32_bf16 v[0:3], v[188:191], v[172:175], v[0:3]
	s_add_i32 s53, 0, 0x18000
	v_add_u32_e32 v140, s53, v196
	s_barrier
	ds_read_b128 v[128:131], v140
	ds_read_b128 v[132:135], v140 offset:1024
	ds_read_b128 v[136:139], v140 offset:2048
	ds_read_b128 v[140:143], v140 offset:3072
	s_add_u32 s36, s36, 0x20000
	s_addc_u32 s37, s37, 0
	s_mov_b32 m0, s47
	ds_read_b128 v[144:147], v198 offset:32768
	ds_read_b128 v[148:151], v198 offset:33792
	ds_read_b128 v[152:155], v198 offset:34816
	ds_read_b128 v[156:159], v198 offset:35840
	ds_read_b128 v[160:163], v198 offset:36864
	ds_read_b128 v[164:167], v198 offset:37888
	ds_read_b128 v[168:171], v198 offset:38912
	ds_read_b128 v[172:175], v198 offset:39936
	global_load_lds_dwordx4 v206, s[36:37]
	s_mov_b32 m0, s48
	s_nop 0
	global_load_lds_dwordx4 v208, s[36:37]
	s_waitcnt lgkmcnt(8)
	s_barrier
	s_waitcnt lgkmcnt(0)
	v_mfma_f32_16x16x32_bf16 v[124:127], v[128:131], v[144:147], v[124:127]
	v_mfma_f32_16x16x32_bf16 v[120:123], v[136:139], v[144:147], v[120:123]
	v_mfma_f32_16x16x32_bf16 v[108:111], v[128:131], v[152:155], v[108:111]
	v_mfma_f32_16x16x32_bf16 v[104:107], v[136:139], v[152:155], v[104:107]
	v_mfma_f32_16x16x32_bf16 v[92:95], v[128:131], v[160:163], v[92:95]
	v_mfma_f32_16x16x32_bf16 v[88:91], v[136:139], v[160:163], v[88:91]
	v_mfma_f32_16x16x32_bf16 v[76:79], v[128:131], v[168:171], v[76:79]
	v_mfma_f32_16x16x32_bf16 v[72:75], v[136:139], v[168:171], v[72:75]
	v_mfma_f32_16x16x32_bf16 v[124:127], v[132:135], v[148:151], v[124:127]
	v_mfma_f32_16x16x32_bf16 v[120:123], v[140:143], v[148:151], v[120:123]
	v_mfma_f32_16x16x32_bf16 v[108:111], v[132:135], v[156:159], v[108:111]
	v_mfma_f32_16x16x32_bf16 v[104:107], v[140:143], v[156:159], v[104:107]
	v_mfma_f32_16x16x32_bf16 v[92:95], v[132:135], v[164:167], v[92:95]
	v_mfma_f32_16x16x32_bf16 v[88:91], v[140:143], v[164:167], v[88:91]
	v_mfma_f32_16x16x32_bf16 v[76:79], v[132:135], v[172:175], v[76:79]
	v_mfma_f32_16x16x32_bf16 v[72:75], v[140:143], v[172:175], v[72:75]
	s_barrier
	s_add_i32 s36, 0, 0x1c000
	s_add_i32 s37, s53, s45
	v_add_u32_e32 v188, s36, v196
	s_add_u32 s100, s34, 0x80
	s_addc_u32 s101, s35, 0
	s_mov_b32 m0, s37
	ds_read_b128 v[176:179], v188
	ds_read_b128 v[180:183], v188 offset:1024
	ds_read_b128 v[184:187], v188 offset:2048
	ds_read_b128 v[188:191], v188 offset:3072
	global_load_lds_dwordx4 v192, s[100:101]
	s_add_i32 m0, s37, 0x2000
	s_nop 0
	global_load_lds_dwordx4 v210, s[100:101]
	s_barrier
	s_waitcnt lgkmcnt(0)
	v_mfma_f32_16x16x32_bf16 v[116:119], v[176:179], v[144:147], v[116:119]
	v_mfma_f32_16x16x32_bf16 v[112:115], v[184:187], v[144:147], v[112:115]
	v_mfma_f32_16x16x32_bf16 v[100:103], v[176:179], v[152:155], v[100:103]
	v_mfma_f32_16x16x32_bf16 v[96:99], v[184:187], v[152:155], v[96:99]
	v_mfma_f32_16x16x32_bf16 v[84:87], v[176:179], v[160:163], v[84:87]
	v_mfma_f32_16x16x32_bf16 v[80:83], v[184:187], v[160:163], v[80:83]
	v_mfma_f32_16x16x32_bf16 v[68:71], v[176:179], v[168:171], v[68:71]
	v_mfma_f32_16x16x32_bf16 v[64:67], v[184:187], v[168:171], v[64:67]
	v_mfma_f32_16x16x32_bf16 v[116:119], v[180:183], v[148:151], v[116:119]
	v_mfma_f32_16x16x32_bf16 v[112:115], v[188:191], v[148:151], v[112:115]
	v_mfma_f32_16x16x32_bf16 v[100:103], v[180:183], v[156:159], v[100:103]
	v_mfma_f32_16x16x32_bf16 v[96:99], v[188:191], v[156:159], v[96:99]
	v_mfma_f32_16x16x32_bf16 v[84:87], v[180:183], v[164:167], v[84:87]
	v_mfma_f32_16x16x32_bf16 v[80:83], v[188:191], v[164:167], v[80:83]
	v_mfma_f32_16x16x32_bf16 v[68:71], v[180:183], v[172:175], v[68:71]
	v_mfma_f32_16x16x32_bf16 v[64:67], v[188:191], v[172:175], v[64:67]
	s_mov_b32 m0, s49
	s_barrier
	ds_read_b128 v[144:147], v198 offset:49152
	ds_read_b128 v[148:151], v198 offset:50176
	ds_read_b128 v[152:155], v198 offset:51200
	ds_read_b128 v[156:159], v198 offset:52224
	ds_read_b128 v[160:163], v198 offset:53248
	ds_read_b128 v[164:167], v198 offset:54272
	ds_read_b128 v[168:171], v198 offset:55296
	ds_read_b128 v[172:175], v198 offset:56320
	global_load_lds_dwordx4 v206, vcc
	s_mov_b32 m0, s50
	s_nop 0
	global_load_lds_dwordx4 v208, vcc
	s_barrier
	s_waitcnt lgkmcnt(0)
	v_mfma_f32_16x16x32_bf16 v[60:63], v[128:131], v[144:147], v[60:63]
	v_mfma_f32_16x16x32_bf16 v[56:59], v[136:139], v[144:147], v[56:59]
	v_mfma_f32_16x16x32_bf16 v[44:47], v[128:131], v[152:155], v[44:47]
	v_mfma_f32_16x16x32_bf16 v[40:43], v[136:139], v[152:155], v[40:43]
	v_mfma_f32_16x16x32_bf16 v[28:31], v[128:131], v[160:163], v[28:31]
	v_mfma_f32_16x16x32_bf16 v[24:27], v[136:139], v[160:163], v[24:27]
	v_mfma_f32_16x16x32_bf16 v[12:15], v[128:131], v[168:171], v[12:15]
	v_mfma_f32_16x16x32_bf16 v[8:11], v[136:139], v[168:171], v[8:11]
	v_mfma_f32_16x16x32_bf16 v[60:63], v[132:135], v[148:151], v[60:63]
	v_mfma_f32_16x16x32_bf16 v[56:59], v[140:143], v[148:151], v[56:59]
	v_mfma_f32_16x16x32_bf16 v[44:47], v[132:135], v[156:159], v[44:47]
	v_mfma_f32_16x16x32_bf16 v[40:43], v[140:143], v[156:159], v[40:43]
	v_mfma_f32_16x16x32_bf16 v[28:31], v[132:135], v[164:167], v[28:31]
	v_mfma_f32_16x16x32_bf16 v[24:27], v[140:143], v[164:167], v[24:27]
	v_mfma_f32_16x16x32_bf16 v[12:15], v[132:135], v[172:175], v[12:15]
	v_mfma_f32_16x16x32_bf16 v[8:11], v[140:143], v[172:175], v[8:11]
	s_barrier
	s_add_u32 s34, s34, 0x20080
	s_addc_u32 s35, s35, 0
	s_add_i32 s36, s36, s45
	s_mov_b32 m0, s36
	s_nop 0
	global_load_lds_dwordx4 v192, s[34:35]
	s_add_i32 m0, s36, 0x2000
	s_nop 0
	global_load_lds_dwordx4 v210, s[34:35]
	s_waitcnt vmcnt(6)
	s_barrier
	v_mfma_f32_16x16x32_bf16 v[52:55], v[176:179], v[144:147], v[52:55]
	v_mfma_f32_16x16x32_bf16 v[48:51], v[184:187], v[144:147], v[48:51]
	v_mfma_f32_16x16x32_bf16 v[36:39], v[176:179], v[152:155], v[36:39]
	v_mfma_f32_16x16x32_bf16 v[32:35], v[184:187], v[152:155], v[32:35]
	v_mfma_f32_16x16x32_bf16 v[20:23], v[176:179], v[160:163], v[20:23]
	v_mfma_f32_16x16x32_bf16 v[16:19], v[184:187], v[160:163], v[16:19]
	v_mfma_f32_16x16x32_bf16 v[4:7], v[176:179], v[168:171], v[4:7]
	v_mfma_f32_16x16x32_bf16 v[0:3], v[184:187], v[168:171], v[0:3]
	v_mfma_f32_16x16x32_bf16 v[52:55], v[180:183], v[148:151], v[52:55]
	v_mfma_f32_16x16x32_bf16 v[48:51], v[188:191], v[148:151], v[48:51]
	v_mfma_f32_16x16x32_bf16 v[36:39], v[180:183], v[156:159], v[36:39]
	v_mfma_f32_16x16x32_bf16 v[32:35], v[188:191], v[156:159], v[32:35]
	v_mfma_f32_16x16x32_bf16 v[20:23], v[180:183], v[164:167], v[20:23]
	v_mfma_f32_16x16x32_bf16 v[16:19], v[188:191], v[164:167], v[16:19]
	v_mfma_f32_16x16x32_bf16 v[4:7], v[180:183], v[172:175], v[4:7]
	v_mfma_f32_16x16x32_bf16 v[0:3], v[188:191], v[172:175], v[0:3]
	s_add_i32 s52, s52, 2
	s_add_u32 s30, s30, 0x100
	s_addc_u32 s31, s31, 0
	s_add_u32 s27, s27, 0x100
	s_addc_u32 s33, s33, 0
	s_cmp_gt_u32 s52, 5
	s_barrier
	s_cbranch_scc0 .LBB0_2484
	v_mov_b32_e32 v128, v252
	s_lshl_b32 s1, s28, 8
	v_readfirstlane_b32 s0, v128
	s_ashr_i32 s15, s0, 2
	s_andn2_b32 s15, s15, 63
	s_lshr_b32 s0, s0, 1
	s_add_i32 s15, s15, s1
	s_and_b32 s0, s0, 0x60
	s_lshl_b32 s1, s26, 8
	v_and_or_b32 v218, v128, 15, s15
	v_lshrrev_b32_e32 v128, 1, v128
	s_or_b32 s0, s0, s1
	v_and_b32_e32 v129, 64, v195
	v_and_or_b32 v216, v128, 24, s0
	v_xor_b32_e32 v128, 16, v195
	v_add_u32_e32 v129, 64, v129
	v_cmp_lt_i32_e32 vcc, v128, v129
	v_ashrrev_i32_e32 v219, 31, v218
	v_ashrrev_i32_e32 v217, 31, v216
	v_cndmask_b32_e32 v128, v195, v128, vcc
	v_lshlrev_b32_e32 v200, 2, v128
	v_xor_b32_e32 v128, 32, v195
	v_cmp_lt_i32_e32 vcc, v128, v129
	v_or_b32_e32 v220, 0x80, v216
	v_ashrrev_i32_e32 v221, 31, v220
	v_cndmask_b32_e32 v128, v195, v128, vcc
	v_lshlrev_b32_e32 v199, 2, v128
	v_lshlrev_b64 v[128:129], 10, v[218:219]
	v_lshl_add_u64 v[130:131], v[128:129], 0, v[216:217]
	v_lshlrev_b64 v[130:131], 1, v[130:131]
	v_lshl_add_u64 v[246:247], s[8:9], 0, v[130:131]
	v_lshl_add_u64 v[250:251], s[10:11], 0, v[130:131]
	global_load_dwordx4 v[188:191], v[246:247], off
	global_load_dwordx4 v[180:183], v[246:247], off offset:256
	global_load_dwordx4 v[184:187], v[250:251], off
	v_or_b32_e32 v242, 16, v218
	v_lshl_add_u64 v[128:129], v[128:129], 0, v[220:221]
	v_ashrrev_i32_e32 v243, 31, v242
	v_lshl_add_u64 v[248:249], v[128:129], 1, s[10:11]
	v_lshlrev_b64 v[128:129], 10, v[242:243]
	v_or_b32_e32 v234, 32, v218
	v_lshl_add_u64 v[130:131], v[128:129], 0, v[216:217]
	v_lshl_add_u64 v[128:129], v[128:129], 0, v[220:221]
	v_ashrrev_i32_e32 v235, 31, v234
	v_lshlrev_b64 v[130:131], 1, v[130:131]
	v_lshl_add_u64 v[240:241], v[128:129], 1, s[10:11]
	v_lshlrev_b64 v[128:129], 10, v[234:235]
	v_or_b32_e32 v226, 48, v218
	v_lshl_add_u64 v[238:239], s[8:9], 0, v[130:131]
	v_lshl_add_u64 v[244:245], s[10:11], 0, v[130:131]
	v_lshl_add_u64 v[130:131], v[128:129], 0, v[216:217]
	v_lshl_add_u64 v[128:129], v[128:129], 0, v[220:221]
	v_ashrrev_i32_e32 v227, 31, v226
	v_lshlrev_b64 v[130:131], 1, v[130:131]
	v_lshl_add_u64 v[232:233], v[128:129], 1, s[10:11]
	v_lshlrev_b64 v[128:129], 10, v[226:227]
	v_lshl_add_u64 v[228:229], s[8:9], 0, v[130:131]
	v_lshl_add_u64 v[236:237], s[10:11], 0, v[130:131]
	v_lshl_add_u64 v[130:131], v[128:129], 0, v[216:217]
	v_lshlrev_b64 v[130:131], 1, v[130:131]
	v_lshl_add_u64 v[132:133], v[128:129], 0, v[220:221]
	v_lshl_add_u64 v[222:223], s[8:9], 0, v[130:131]
	v_lshl_add_u64 v[230:231], s[10:11], 0, v[130:131]
	v_lshl_add_u64 v[224:225], v[132:133], 1, s[10:11]
	global_load_dwordx4 v[176:179], v[248:249], off
	global_load_dwordx4 v[172:175], v[238:239], off
	global_load_dwordx4 v[164:167], v[238:239], off offset:256
	global_load_dwordx4 v[168:171], v[244:245], off
	global_load_dwordx4 v[160:163], v[240:241], off
	global_load_dwordx4 v[156:159], v[228:229], off
	global_load_dwordx4 v[132:135], v[224:225], off
	global_load_dwordx4 v[152:155], v[236:237], off
	global_load_dwordx4 v[144:147], v[232:233], off
	global_load_dwordx4 v[148:151], v[228:229], off offset:256
	global_load_dwordx4 v[136:139], v[230:231], off
	global_load_dwordx4 v[140:143], v[222:223], off
	global_load_dwordx4 v[128:131], v[222:223], off offset:256
	v_cmp_gt_u32_e32 vcc, 16, v195
	s_waitcnt vmcnt(0)
	v_lshlrev_b32_e32 v202, 16, v188
	v_and_b32_e32 v203, 0xffff0000, v188
	v_lshlrev_b32_e32 v204, 16, v184
	v_and_b32_e32 v205, 0xffff0000, v184
	v_lshlrev_b32_e32 v188, 16, v189
	v_and_b32_e32 v189, 0xffff0000, v189
	v_lshlrev_b32_e32 v184, 16, v185
	v_and_b32_e32 v185, 0xffff0000, v185
	v_pk_add_f32 v[202:203], v[202:203], v[204:205]
	v_pk_add_f32 v[184:185], v[188:189], v[184:185]
	v_pk_add_f32 v[188:189], v[124:125], v[202:203]
	v_pk_add_f32 v[184:185], v[126:127], v[184:185]
	v_lshlrev_b32_e32 v124, 16, v190
	v_and_b32_e32 v125, 0xffff0000, v190
	v_lshlrev_b32_e32 v126, 16, v186
	v_and_b32_e32 v127, 0xffff0000, v186
	v_pk_add_f32 v[124:125], v[124:125], v[126:127]
	v_lshlrev_b32_e32 v126, 16, v191
	v_and_b32_e32 v127, 0xffff0000, v191
	v_lshlrev_b32_e32 v186, 16, v187
	v_and_b32_e32 v187, 0xffff0000, v187
	v_pk_add_f32 v[126:127], v[126:127], v[186:187]
	v_pk_add_f32 v[190:191], v[120:121], v[124:125]
	v_cvt_pk_bf16_f32 v120, v188, v189
	v_pk_add_f32 v[186:187], v[122:123], v[126:127]
	v_and_b32_e32 v123, 0xffff0000, v120
	v_lshlrev_b32_e32 v122, 16, v120
	v_pk_add_f32 v[122:123], v[188:189], v[122:123] neg_lo:[0,1] neg_hi:[0,1]
	v_cvt_pk_bf16_f32 v121, v184, v185
	v_cvt_pk_bf16_f32 v124, v122, v123
	v_and_b32_e32 v123, 0xffff0000, v121
	v_lshlrev_b32_e32 v122, 16, v121
	v_pk_add_f32 v[122:123], v[184:185], v[122:123] neg_lo:[0,1] neg_hi:[0,1]
	s_nop 0
	v_cvt_pk_bf16_f32 v125, v122, v123
	v_cvt_pk_bf16_f32 v122, v190, v191
	v_cvt_pk_bf16_f32 v123, v186, v187
	v_and_b32_e32 v127, 0xffff0000, v122
	v_lshlrev_b32_e32 v126, 16, v122
	v_and_b32_e32 v203, 0xffff0000, v123
	v_lshlrev_b32_e32 v202, 16, v123
	v_pk_add_f32 v[126:127], v[190:191], v[126:127] neg_lo:[0,1] neg_hi:[0,1]
	v_pk_add_f32 v[202:203], v[186:187], v[202:203] neg_lo:[0,1] neg_hi:[0,1]
	v_cvt_pk_bf16_f32 v126, v126, v127
	v_cvt_pk_bf16_f32 v127, v202, v203
	global_store_dwordx4 v[246:247], v[120:123], off
	global_store_dwordx4 v[250:251], v[124:127], off
	s_nop 0
	v_pk_mul_f32 v[122:123], v[190:191], v[190:191]
	v_pk_mul_f32 v[120:121], v[186:187], v[186:187]
	v_pk_fma_f32 v[122:123], v[188:189], v[188:189], v[122:123]
	v_pk_fma_f32 v[120:121], v[184:185], v[184:185], v[120:121]
	v_add_f32_e32 v122, v122, v123
	v_add_f32_e32 v120, v120, v122
	v_add_f32_e32 v120, v121, v120
	ds_bpermute_b32 v121, v200, v120
	s_waitcnt lgkmcnt(0)
	v_add_f32_e32 v122, v120, v121
	ds_bpermute_b32 v123, v199, v122
	v_lshl_add_u64 v[120:121], v[218:219], 2, s[12:13]
	s_and_saveexec_b64 s[26:27], vcc
	s_cbranch_execz .LBB0_2487
	s_waitcnt lgkmcnt(0)
	v_add_f32_e32 v122, v122, v123
	global_atomic_add_f32 v[120:121], v122, off

.LBB0_2804:
	s_add_u32 s20, s18, 0xfffc0080
	s_addc_u32 s21, s19, -1
	s_add_i32 s42, 0, 0x10000
	ds_read_b128 v[138:141], v202
	ds_read_b128 v[142:145], v202 offset:1024
	ds_read_b128 v[146:149], v202 offset:2048
	ds_read_b128 v[154:157], v202 offset:3072
	s_cmp_eq_u32 s41, 12
	s_cselect_b32 s23, s9, s21
	s_cselect_b32 s22, s33, s20
	s_cselect_b32 s21, s11, s40
	s_cselect_b32 s20, s38, s39
	s_add_i32 m0, s17, 0xc000
	ds_read_b128 v[158:161], v152
	ds_read_b128 v[162:165], v152 offset:1024
	ds_read_b128 v[166:169], v152 offset:2048
	ds_read_b128 v[170:173], v152 offset:3072
	ds_read_b128 v[174:177], v152 offset:4096
	ds_read_b128 v[178:181], v152 offset:5120
	ds_read_b128 v[182:185], v152 offset:6144
	ds_read_b128 v[186:189], v152 offset:7168
	global_load_lds_dwordx4 v136, s[18:19]
	s_add_i32 m0, s17, 0xe000
	s_nop 0
	global_load_lds_dwordx4 v134, s[18:19]
	s_waitcnt lgkmcnt(8)
	s_barrier
	s_waitcnt lgkmcnt(0)
	v_mfma_f32_16x16x32_bf16 v[124:127], v[138:141], v[158:161], v[124:127]
	v_mfma_f32_16x16x32_bf16 v[116:119], v[146:149], v[158:161], v[116:119]
	v_mfma_f32_16x16x32_bf16 v[108:111], v[138:141], v[166:169], v[108:111]
	v_mfma_f32_16x16x32_bf16 v[100:103], v[146:149], v[166:169], v[100:103]
	v_mfma_f32_16x16x32_bf16 v[92:95], v[138:141], v[174:177], v[92:95]
	v_mfma_f32_16x16x32_bf16 v[84:87], v[146:149], v[174:177], v[84:87]
	v_mfma_f32_16x16x32_bf16 v[76:79], v[138:141], v[182:185], v[76:79]
	v_mfma_f32_16x16x32_bf16 v[68:71], v[146:149], v[182:185], v[68:71]
	v_mfma_f32_16x16x32_bf16 v[124:127], v[142:145], v[162:165], v[124:127]
	v_mfma_f32_16x16x32_bf16 v[116:119], v[154:157], v[162:165], v[116:119]
	v_mfma_f32_16x16x32_bf16 v[108:111], v[142:145], v[170:173], v[108:111]
	v_mfma_f32_16x16x32_bf16 v[100:103], v[154:157], v[170:173], v[100:103]
	v_mfma_f32_16x16x32_bf16 v[92:95], v[142:145], v[178:181], v[92:95]
	v_mfma_f32_16x16x32_bf16 v[84:87], v[154:157], v[178:181], v[84:87]
	v_mfma_f32_16x16x32_bf16 v[76:79], v[142:145], v[186:189], v[76:79]
	v_mfma_f32_16x16x32_bf16 v[68:71], v[154:157], v[186:189], v[68:71]
	s_barrier
	s_add_i32 s44, 0, 0x14000
	s_add_i32 s42, s42, s28
	s_mov_b32 m0, s42
	ds_read_b128 v[198:201], v203
	ds_read_b128 v[206:209], v203 offset:1024
	ds_read_b128 v[210:213], v203 offset:2048
	ds_read_b128 v[214:217], v203 offset:3072
	global_load_lds_dwordx4 v192, s[20:21]
	s_add_i32 m0, s42, 0x2000
	s_nop 0
	global_load_lds_dwordx4 v128, s[20:21]
	s_barrier
	s_waitcnt lgkmcnt(0)
	v_mfma_f32_16x16x32_bf16 v[120:123], v[198:201], v[158:161], v[120:123]
	v_mfma_f32_16x16x32_bf16 v[112:115], v[210:213], v[158:161], v[112:115]
	v_mfma_f32_16x16x32_bf16 v[104:107], v[198:201], v[166:169], v[104:107]
	v_mfma_f32_16x16x32_bf16 v[96:99], v[210:213], v[166:169], v[96:99]
	v_mfma_f32_16x16x32_bf16 v[88:91], v[198:201], v[174:177], v[88:91]
	v_mfma_f32_16x16x32_bf16 v[80:83], v[210:213], v[174:177], v[80:83]
	v_mfma_f32_16x16x32_bf16 v[72:75], v[198:201], v[182:185], v[72:75]
	v_mfma_f32_16x16x32_bf16 v[64:67], v[210:213], v[182:185], v[64:67]
	v_mfma_f32_16x16x32_bf16 v[120:123], v[206:209], v[162:165], v[120:123]
	v_mfma_f32_16x16x32_bf16 v[112:115], v[214:217], v[162:165], v[112:115]
	v_mfma_f32_16x16x32_bf16 v[104:107], v[206:209], v[170:173], v[104:107]
	v_mfma_f32_16x16x32_bf16 v[96:99], v[214:217], v[170:173], v[96:99]
	v_mfma_f32_16x16x32_bf16 v[88:91], v[206:209], v[178:181], v[88:91]
	v_mfma_f32_16x16x32_bf16 v[80:83], v[214:217], v[178:181], v[80:83]
	v_mfma_f32_16x16x32_bf16 v[72:75], v[206:209], v[186:189], v[72:75]
	v_mfma_f32_16x16x32_bf16 v[64:67], v[214:217], v[186:189], v[64:67]
	s_mov_b32 m0, s17
	s_add_u32 vcc_lo, s22, 0x80
	s_addc_u32 vcc_hi, s23, 0
	s_barrier
	ds_read_b128 v[158:161], v152 offset:16384
	ds_read_b128 v[162:165], v152 offset:17408
	ds_read_b128 v[166:169], v152 offset:18432
	ds_read_b128 v[170:173], v152 offset:19456
	ds_read_b128 v[174:177], v152 offset:20480
	ds_read_b128 v[178:181], v152 offset:21504
	ds_read_b128 v[182:185], v152 offset:22528
	ds_read_b128 v[186:189], v152 offset:23552
	global_load_lds_dwordx4 v132, s[22:23]
	s_mov_b32 m0, s29
	s_nop 0
	global_load_lds_dwordx4 v130, s[22:23]
	s_barrier
	s_waitcnt lgkmcnt(0)
	v_mfma_f32_16x16x32_bf16 v[60:63], v[138:141], v[158:161], v[60:63]
	v_mfma_f32_16x16x32_bf16 v[52:55], v[146:149], v[158:161], v[52:55]
	v_mfma_f32_16x16x32_bf16 v[44:47], v[138:141], v[166:169], v[44:47]
	v_mfma_f32_16x16x32_bf16 v[36:39], v[146:149], v[166:169], v[36:39]
	v_mfma_f32_16x16x32_bf16 v[28:31], v[138:141], v[174:177], v[28:31]
	v_mfma_f32_16x16x32_bf16 v[20:23], v[146:149], v[174:177], v[20:23]
	v_mfma_f32_16x16x32_bf16 v[12:15], v[138:141], v[182:185], v[12:15]
	v_mfma_f32_16x16x32_bf16 v[4:7], v[146:149], v[182:185], v[4:7]
	v_mfma_f32_16x16x32_bf16 v[60:63], v[142:145], v[162:165], v[60:63]
	v_mfma_f32_16x16x32_bf16 v[52:55], v[154:157], v[162:165], v[52:55]
	v_mfma_f32_16x16x32_bf16 v[44:47], v[142:145], v[170:173], v[44:47]
	v_mfma_f32_16x16x32_bf16 v[36:39], v[154:157], v[170:173], v[36:39]
	v_mfma_f32_16x16x32_bf16 v[28:31], v[142:145], v[178:181], v[28:31]
	v_mfma_f32_16x16x32_bf16 v[20:23], v[154:157], v[178:181], v[20:23]
	v_mfma_f32_16x16x32_bf16 v[12:15], v[142:145], v[186:189], v[12:15]
	v_mfma_f32_16x16x32_bf16 v[4:7], v[154:157], v[186:189], v[4:7]
	s_barrier
	s_add_u32 s42, s20, 0x40000
	s_addc_u32 s43, s21, 0
	s_add_i32 s44, s44, s28
	s_mov_b32 m0, s44
	s_nop 0
	global_load_lds_dwordx4 v192, s[42:43]
	s_add_i32 m0, s44, 0x2000
	s_nop 0
	global_load_lds_dwordx4 v128, s[42:43]
	s_waitcnt vmcnt(6)
	s_barrier
	v_mfma_f32_16x16x32_bf16 v[56:59], v[198:201], v[158:161], v[56:59]
	v_mfma_f32_16x16x32_bf16 v[48:51], v[210:213], v[158:161], v[48:51]
	v_mfma_f32_16x16x32_bf16 v[40:43], v[198:201], v[166:169], v[40:43]
	v_mfma_f32_16x16x32_bf16 v[32:35], v[210:213], v[166:169], v[32:35]
	v_mfma_f32_16x16x32_bf16 v[24:27], v[198:201], v[174:177], v[24:27]
	v_mfma_f32_16x16x32_bf16 v[16:19], v[210:213], v[174:177], v[16:19]
	v_mfma_f32_16x16x32_bf16 v[8:11], v[198:201], v[182:185], v[8:11]
	v_mfma_f32_16x16x32_bf16 v[0:3], v[210:213], v[182:185], v[0:3]
	v_mfma_f32_16x16x32_bf16 v[56:59], v[206:209], v[162:165], v[56:59]
	v_mfma_f32_16x16x32_bf16 v[48:51], v[214:217], v[162:165], v[48:51]
	v_mfma_f32_16x16x32_bf16 v[40:43], v[206:209], v[170:173], v[40:43]
	v_mfma_f32_16x16x32_bf16 v[32:35], v[214:217], v[170:173], v[32:35]
	v_mfma_f32_16x16x32_bf16 v[24:27], v[206:209], v[178:181], v[24:27]
	v_mfma_f32_16x16x32_bf16 v[16:19], v[214:217], v[178:181], v[16:19]
	v_mfma_f32_16x16x32_bf16 v[8:11], v[206:209], v[186:189], v[8:11]
	v_mfma_f32_16x16x32_bf16 v[0:3], v[214:217], v[186:189], v[0:3]
	s_add_i32 s42, 0, 0x18000
	s_barrier
	ds_read_b128 v[138:141], v204
	ds_read_b128 v[142:145], v204 offset:1024
	ds_read_b128 v[146:149], v204 offset:2048
	ds_read_b128 v[154:157], v204 offset:3072
	s_add_u32 s22, s22, 0x40000
	s_addc_u32 s23, s23, 0
	s_mov_b32 m0, s30
	ds_read_b128 v[158:161], v152 offset:32768
	ds_read_b128 v[162:165], v152 offset:33792
	ds_read_b128 v[166:169], v152 offset:34816
	ds_read_b128 v[170:173], v152 offset:35840
	ds_read_b128 v[174:177], v152 offset:36864
	ds_read_b128 v[178:181], v152 offset:37888
	ds_read_b128 v[182:185], v152 offset:38912
	ds_read_b128 v[186:189], v152 offset:39936
	global_load_lds_dwordx4 v132, s[22:23]
	s_mov_b32 m0, s31
	s_nop 0
	global_load_lds_dwordx4 v130, s[22:23]
	s_waitcnt lgkmcnt(8)
	s_barrier
	s_waitcnt lgkmcnt(0)
	v_mfma_f32_16x16x32_bf16 v[124:127], v[138:141], v[158:161], v[124:127]
	v_mfma_f32_16x16x32_bf16 v[116:119], v[146:149], v[158:161], v[116:119]
	v_mfma_f32_16x16x32_bf16 v[108:111], v[138:141], v[166:169], v[108:111]
	v_mfma_f32_16x16x32_bf16 v[100:103], v[146:149], v[166:169], v[100:103]
	v_mfma_f32_16x16x32_bf16 v[92:95], v[138:141], v[174:177], v[92:95]
	v_mfma_f32_16x16x32_bf16 v[84:87], v[146:149], v[174:177], v[84:87]
	v_mfma_f32_16x16x32_bf16 v[76:79], v[138:141], v[182:185], v[76:79]
	v_mfma_f32_16x16x32_bf16 v[68:71], v[146:149], v[182:185], v[68:71]
	v_mfma_f32_16x16x32_bf16 v[124:127], v[142:145], v[162:165], v[124:127]
	v_mfma_f32_16x16x32_bf16 v[116:119], v[154:157], v[162:165], v[116:119]
	v_mfma_f32_16x16x32_bf16 v[108:111], v[142:145], v[170:173], v[108:111]
	v_mfma_f32_16x16x32_bf16 v[100:103], v[154:157], v[170:173], v[100:103]
	v_mfma_f32_16x16x32_bf16 v[92:95], v[142:145], v[178:181], v[92:95]
	v_mfma_f32_16x16x32_bf16 v[84:87], v[154:157], v[178:181], v[84:87]
	v_mfma_f32_16x16x32_bf16 v[76:79], v[142:145], v[186:189], v[76:79]
	v_mfma_f32_16x16x32_bf16 v[68:71], v[154:157], v[186:189], v[68:71]
	s_barrier
	s_add_i32 s22, 0, 0x1c000
	s_add_i32 s23, s42, s28
	s_add_u32 s100, s20, 0x80
	s_addc_u32 s101, s21, 0
	s_mov_b32 m0, s23
	ds_read_b128 v[198:201], v205
	ds_read_b128 v[206:209], v205 offset:1024
	ds_read_b128 v[210:213], v205 offset:2048
	ds_read_b128 v[214:217], v205 offset:3072
	global_load_lds_dwordx4 v192, s[100:101]
	s_add_i32 m0, s23, 0x2000
	s_nop 0
	global_load_lds_dwordx4 v128, s[100:101]
	s_barrier
	s_waitcnt lgkmcnt(0)
	v_mfma_f32_16x16x32_bf16 v[120:123], v[198:201], v[158:161], v[120:123]
	v_mfma_f32_16x16x32_bf16 v[112:115], v[210:213], v[158:161], v[112:115]
	v_mfma_f32_16x16x32_bf16 v[104:107], v[198:201], v[166:169], v[104:107]
	v_mfma_f32_16x16x32_bf16 v[96:99], v[210:213], v[166:169], v[96:99]
	v_mfma_f32_16x16x32_bf16 v[88:91], v[198:201], v[174:177], v[88:91]
	v_mfma_f32_16x16x32_bf16 v[80:83], v[210:213], v[174:177], v[80:83]
	v_mfma_f32_16x16x32_bf16 v[72:75], v[198:201], v[182:185], v[72:75]
	v_mfma_f32_16x16x32_bf16 v[64:67], v[210:213], v[182:185], v[64:67]
	v_mfma_f32_16x16x32_bf16 v[120:123], v[206:209], v[162:165], v[120:123]
	v_mfma_f32_16x16x32_bf16 v[112:115], v[214:217], v[162:165], v[112:115]
	v_mfma_f32_16x16x32_bf16 v[104:107], v[206:209], v[170:173], v[104:107]
	v_mfma_f32_16x16x32_bf16 v[96:99], v[214:217], v[170:173], v[96:99]
	v_mfma_f32_16x16x32_bf16 v[88:91], v[206:209], v[178:181], v[88:91]
	v_mfma_f32_16x16x32_bf16 v[80:83], v[214:217], v[178:181], v[80:83]
	v_mfma_f32_16x16x32_bf16 v[72:75], v[206:209], v[186:189], v[72:75]
	v_mfma_f32_16x16x32_bf16 v[64:67], v[214:217], v[186:189], v[64:67]
	s_mov_b32 m0, s34
	s_barrier
	ds_read_b128 v[158:161], v152 offset:49152
	ds_read_b128 v[162:165], v152 offset:50176
	ds_read_b128 v[166:169], v152 offset:51200
	ds_read_b128 v[170:173], v152 offset:52224
	ds_read_b128 v[174:177], v152 offset:53248
	ds_read_b128 v[178:181], v152 offset:54272
	ds_read_b128 v[182:185], v152 offset:55296
	ds_read_b128 v[186:189], v152 offset:56320
	global_load_lds_dwordx4 v132, vcc
	s_mov_b32 m0, s35
	s_nop 0
	global_load_lds_dwordx4 v130, vcc
	s_barrier
	s_waitcnt lgkmcnt(0)
	v_mfma_f32_16x16x32_bf16 v[60:63], v[138:141], v[158:161], v[60:63]
	v_mfma_f32_16x16x32_bf16 v[52:55], v[146:149], v[158:161], v[52:55]
	v_mfma_f32_16x16x32_bf16 v[44:47], v[138:141], v[166:169], v[44:47]
	v_mfma_f32_16x16x32_bf16 v[36:39], v[146:149], v[166:169], v[36:39]
	v_mfma_f32_16x16x32_bf16 v[28:31], v[138:141], v[174:177], v[28:31]
	v_mfma_f32_16x16x32_bf16 v[20:23], v[146:149], v[174:177], v[20:23]
	v_mfma_f32_16x16x32_bf16 v[12:15], v[138:141], v[182:185], v[12:15]
	v_mfma_f32_16x16x32_bf16 v[4:7], v[146:149], v[182:185], v[4:7]
	v_mfma_f32_16x16x32_bf16 v[60:63], v[142:145], v[162:165], v[60:63]
	v_mfma_f32_16x16x32_bf16 v[52:55], v[154:157], v[162:165], v[52:55]
	v_mfma_f32_16x16x32_bf16 v[44:47], v[142:145], v[170:173], v[44:47]
	v_mfma_f32_16x16x32_bf16 v[36:39], v[154:157], v[170:173], v[36:39]
	v_mfma_f32_16x16x32_bf16 v[28:31], v[142:145], v[178:181], v[28:31]
	v_mfma_f32_16x16x32_bf16 v[20:23], v[154:157], v[178:181], v[20:23]
	v_mfma_f32_16x16x32_bf16 v[12:15], v[142:145], v[186:189], v[12:15]
	v_mfma_f32_16x16x32_bf16 v[4:7], v[154:157], v[186:189], v[4:7]
	s_barrier
	s_add_u32 s20, s20, 0x40080
	s_addc_u32 s21, s21, 0
	s_add_i32 s22, s22, s28
	s_mov_b32 m0, s22
	s_nop 0
	global_load_lds_dwordx4 v192, s[20:21]
	s_add_i32 m0, s22, 0x2000
	s_nop 0
	global_load_lds_dwordx4 v128, s[20:21]
	s_waitcnt vmcnt(6)
	s_barrier
	v_mfma_f32_16x16x32_bf16 v[56:59], v[198:201], v[158:161], v[56:59]
	v_mfma_f32_16x16x32_bf16 v[48:51], v[210:213], v[158:161], v[48:51]
	v_mfma_f32_16x16x32_bf16 v[40:43], v[198:201], v[166:169], v[40:43]
	v_mfma_f32_16x16x32_bf16 v[32:35], v[210:213], v[166:169], v[32:35]
	v_mfma_f32_16x16x32_bf16 v[24:27], v[198:201], v[174:177], v[24:27]
	v_mfma_f32_16x16x32_bf16 v[16:19], v[210:213], v[174:177], v[16:19]
	v_mfma_f32_16x16x32_bf16 v[8:11], v[198:201], v[182:185], v[8:11]
	v_mfma_f32_16x16x32_bf16 v[0:3], v[210:213], v[182:185], v[0:3]
	v_mfma_f32_16x16x32_bf16 v[56:59], v[206:209], v[162:165], v[56:59]
	v_mfma_f32_16x16x32_bf16 v[48:51], v[214:217], v[162:165], v[48:51]
	v_mfma_f32_16x16x32_bf16 v[40:43], v[206:209], v[170:173], v[40:43]
	v_mfma_f32_16x16x32_bf16 v[32:35], v[214:217], v[170:173], v[32:35]
	v_mfma_f32_16x16x32_bf16 v[24:27], v[206:209], v[178:181], v[24:27]
	v_mfma_f32_16x16x32_bf16 v[16:19], v[214:217], v[178:181], v[16:19]
	v_mfma_f32_16x16x32_bf16 v[8:11], v[206:209], v[186:189], v[8:11]
	v_mfma_f32_16x16x32_bf16 v[0:3], v[214:217], v[186:189], v[0:3]
	s_add_i32 s41, s41, 2
	s_add_u32 s39, s39, 0x100
	s_addc_u32 s40, s40, 0
	s_add_u32 s18, s18, 0x100
	s_addc_u32 s19, s19, 0
	s_cmp_gt_u32 s41, 13
	s_barrier
	s_cbranch_scc0 .LBB0_2804
	v_mov_b32_e32 v139, v252
	s_lshl_b32 s11, s16, 8
	v_readfirstlane_b32 s9, v139
	s_ashr_i32 s16, s9, 2
	s_andn2_b32 s16, s16, 63
	s_lshr_b32 s9, s9, 1
	s_add_i32 s16, s16, s11
	s_lshl_b32 s11, s37, 7
	s_and_b32 s9, s9, 0x60
	v_and_or_b32 v138, v139, 15, s16
	s_or_b32 s9, s9, s11
	v_lshrrev_b32_e32 v139, 1, v139
	v_and_or_b32 v148, v139, 24, s9
	v_ashrrev_i32_e32 v139, 31, v138
	v_lshl_add_u64 v[140:141], v[138:139], 2, s[6:7]
	v_or_b32_e32 v146, 16, v138
	v_ashrrev_i32_e32 v147, 31, v146
	v_lshl_add_u64 v[142:143], v[146:147], 2, s[6:7]
	v_or_b32_e32 v144, 32, v138
	v_ashrrev_i32_e32 v145, 31, v144
	v_lshl_add_u64 v[142:143], v[144:145], 2, s[6:7]
	v_or_b32_e32 v142, 48, v138
	v_ashrrev_i32_e32 v143, 31, v142
	v_lshl_add_u64 v[154:155], v[142:143], 2, s[6:7]
	v_pk_mul_f32 v[120:121], v[124:125], v[120:121]
	v_pk_mul_f32 v[122:123], v[126:127], v[122:123]
	v_pk_mul_f32 v[112:113], v[116:117], v[112:113]
	v_pk_mul_f32 v[114:115], v[118:119], v[114:115]
	v_ashrrev_i32_e32 v149, 31, v148
	s_movk_i32 s9, 0x1600
	v_pk_mul_f32 v[104:105], v[108:109], v[104:105]
	v_pk_mul_f32 v[106:107], v[110:111], v[106:107]
	v_pk_mul_f32 v[96:97], v[100:101], v[96:97]
	v_pk_mul_f32 v[98:99], v[102:103], v[98:99]
	v_pk_mul_f32 v[88:89], v[92:93], v[88:89]
	v_pk_mul_f32 v[90:91], v[94:95], v[90:91]
	v_pk_mul_f32 v[80:81], v[84:85], v[80:81]
	v_pk_mul_f32 v[82:83], v[86:87], v[82:83]
	v_pk_mul_f32 v[72:73], v[76:77], v[72:73]
	v_pk_mul_f32 v[74:75], v[78:79], v[74:75]
	v_pk_mul_f32 v[64:65], v[68:69], v[64:65]
	v_pk_mul_f32 v[66:67], v[70:71], v[66:67]
	v_pk_mul_f32 v[56:57], v[60:61], v[56:57]
	v_pk_mul_f32 v[58:59], v[62:63], v[58:59]
	v_pk_mul_f32 v[48:49], v[52:53], v[48:49]
	v_pk_mul_f32 v[50:51], v[54:55], v[50:51]
	v_pk_mul_f32 v[40:41], v[44:45], v[40:41]
	v_pk_mul_f32 v[42:43], v[46:47], v[42:43]
	v_pk_mul_f32 v[32:33], v[36:37], v[32:33]
	v_pk_mul_f32 v[34:35], v[38:39], v[34:35]
	v_pk_mul_f32 v[24:25], v[28:29], v[24:25]
	v_pk_mul_f32 v[26:27], v[30:31], v[26:27]
	v_pk_mul_f32 v[16:17], v[20:21], v[16:17]
	v_pk_mul_f32 v[18:19], v[22:23], v[18:19]
	v_pk_mul_f32 v[8:9], v[12:13], v[8:9]
	v_pk_mul_f32 v[10:11], v[14:15], v[10:11]
	v_pk_mul_f32 v[0:1], v[4:5], v[0:1]
	v_pk_mul_f32 v[2:3], v[6:7], v[2:3]
	s_mov_b32 s37, s10
	s_mov_b32 s16, s8
	s_mov_b64 s[20:21], s[12:13]
	v_fmamk_f32 v143, v231, 0x3a800000, v194
	s_nop 0
	v_rsq_f32_e32 v143, v143
	s_nop 0
	v_mul_f32_e32 v154, 0xbfb8aa3b, v143
	v_pk_mul_f32 v[158:159], v[124:125], v[154:155] op_sel_hi:[1,0]
	v_mul_f32_e32 v150, v143, v143
	v_exp_f32_e32 v143, v158
	v_pk_mul_f32 v[156:157], v[126:127], v[154:155] op_sel_hi:[1,0]
	v_add_f32_e32 v143, 1.0, v143
	v_rcp_f32_e32 v158, v143
	v_exp_f32_e32 v143, v159
	s_nop 0
	v_add_f32_e32 v143, 1.0, v143
	v_rcp_f32_e32 v159, v143
	v_exp_f32_e32 v143, v156
	v_pk_mul_f32 v[124:125], v[150:151], v[158:159] op_sel_hi:[0,1]
	v_add_f32_e32 v143, 1.0, v143
	v_rcp_f32_e32 v156, v143
	v_exp_f32_e32 v143, v157
	v_pk_mul_f32 v[120:121], v[120:121], v[124:125]
	v_add_f32_e32 v143, 1.0, v143
	v_rcp_f32_e32 v157, v143
	v_cvt_pk_bf16_f32 v124, v121, s0
	v_cvt_pk_bf16_f32 v120, v120, s0
	v_pk_mul_f32 v[126:127], v[150:151], v[156:157] op_sel_hi:[0,1]
	v_pk_mul_f32 v[122:123], v[122:123], v[126:127]
	s_nop 0
	v_cvt_pk_bf16_f32 v121, v122, v123
	v_lshlrev_b32_e32 v122, 16, v124
	v_pk_mul_f32 v[124:125], v[116:117], v[154:155] op_sel_hi:[1,0]
	v_or_b32_sdwa v120, v122, v120 dst_sel:DWORD dst_unused:UNUSED_PAD src0_sel:DWORD src1_sel:WORD_0
	v_pk_mul_f32 v[122:123], v[118:119], v[154:155] op_sel_hi:[1,0]
	v_exp_f32_e32 v124, v124
	v_exp_f32_e32 v125, v125
	v_exp_f32_e32 v122, v122
	v_exp_f32_e32 v123, v123
	v_add_f32_e32 v124, 1.0, v124
	v_add_f32_e32 v125, 1.0, v125
	v_rcp_f32_e32 v124, v124
	v_rcp_f32_e32 v125, v125
	v_add_f32_e32 v122, 1.0, v122
	v_add_f32_e32 v123, 1.0, v123
	v_rcp_f32_e32 v122, v122
	v_rcp_f32_e32 v123, v123
	v_pk_mul_f32 v[116:117], v[150:151], v[124:125] op_sel_hi:[0,1]
	v_pk_mul_f32 v[112:113], v[112:113], v[116:117]
	v_pk_mul_f32 v[118:119], v[150:151], v[122:123] op_sel_hi:[0,1]
	v_pk_mul_f32 v[114:115], v[114:115], v[118:119]
	v_cvt_pk_bf16_f32 v122, v112, v113
	v_mov_b64_e32 v[112:113], s[4:5]
	v_cvt_pk_bf16_f32 v123, v114, v115
	v_mad_i64_i32 v[116:117], s[18:19], v138, s9, v[112:113]
	v_lshlrev_b64 v[114:115], 1, v[148:149]
	v_lshl_add_u64 v[116:117], v[116:117], 0, v[114:115]
	global_store_dwordx4 v[116:117], v[120:123], off
	v_fmamk_f32 v116, v232, 0x3a800000, v194
	s_nop 0
	v_rsq_f32_e32 v116, v116
	s_nop 0
	v_mul_f32_e32 v118, 0xbfb8aa3b, v116
	v_pk_mul_f32 v[122:123], v[108:109], v[118:119] op_sel_hi:[1,0]
	v_pk_mul_f32 v[120:121], v[110:111], v[118:119] op_sel_hi:[1,0]
	v_exp_f32_e32 v117, v122
	v_mul_f32_e32 v116, v116, v116
	v_add_f32_e32 v117, 1.0, v117
	v_rcp_f32_e32 v122, v117
	v_exp_f32_e32 v117, v123
	s_nop 0
	v_add_f32_e32 v117, 1.0, v117
	v_rcp_f32_e32 v123, v117
	v_exp_f32_e32 v117, v120
	s_nop 0
	v_add_f32_e32 v117, 1.0, v117
	v_rcp_f32_e32 v120, v117
	v_exp_f32_e32 v117, v121
	s_nop 0
	v_add_f32_e32 v117, 1.0, v117
	v_rcp_f32_e32 v121, v117
	v_pk_mul_f32 v[108:109], v[116:117], v[122:123] op_sel_hi:[0,1]
	v_pk_mul_f32 v[104:105], v[104:105], v[108:109]
	v_pk_mul_f32 v[110:111], v[116:117], v[120:121] op_sel_hi:[0,1]
	v_pk_mul_f32 v[106:107], v[106:107], v[110:111]
	v_cvt_pk_bf16_f32 v108, v105, s0
	v_cvt_pk_bf16_f32 v104, v104, s0
	v_cvt_pk_bf16_f32 v105, v106, v107
	v_lshlrev_b32_e32 v106, 16, v108
	v_pk_mul_f32 v[108:109], v[100:101], v[118:119] op_sel_hi:[1,0]
	v_or_b32_sdwa v104, v106, v104 dst_sel:DWORD dst_unused:UNUSED_PAD src0_sel:DWORD src1_sel:WORD_0
	v_pk_mul_f32 v[106:107], v[102:103], v[118:119] op_sel_hi:[1,0]
	v_exp_f32_e32 v108, v108
	v_exp_f32_e32 v109, v109
	v_exp_f32_e32 v106, v106
	v_exp_f32_e32 v107, v107
	v_add_f32_e32 v108, 1.0, v108
	v_add_f32_e32 v109, 1.0, v109
	v_rcp_f32_e32 v108, v108
	v_rcp_f32_e32 v109, v109
	v_add_f32_e32 v106, 1.0, v106
	v_add_f32_e32 v107, 1.0, v107
	v_rcp_f32_e32 v106, v106
	v_rcp_f32_e32 v107, v107
	v_pk_mul_f32 v[100:101], v[116:117], v[108:109] op_sel_hi:[0,1]
	v_pk_mul_f32 v[96:97], v[96:97], v[100:101]
	v_pk_mul_f32 v[102:103], v[116:117], v[106:107] op_sel_hi:[0,1]
	v_pk_mul_f32 v[98:99], v[98:99], v[102:103]
	v_cvt_pk_bf16_f32 v106, v96, v97
	v_mad_i64_i32 v[96:97], s[18:19], v146, s9, v[112:113]
	v_cvt_pk_bf16_f32 v107, v98, v99
	v_lshl_add_u64 v[96:97], v[96:97], 0, v[114:115]
	global_store_dwordx4 v[96:97], v[104:107], off
	v_fmamk_f32 v96, v233, 0x3a800000, v194
	s_nop 0
	v_rsq_f32_e32 v96, v96
	s_nop 0
	v_mov_b32_e32 v97, v96
	v_mul_f32_e32 v96, 0xbfb8aa3b, v97
	v_pk_mul_f32 v[102:103], v[92:93], v[96:97] op_sel_hi:[1,0]
	v_mul_f32_e32 v98, v97, v97
	v_pk_mul_f32 v[100:101], v[94:95], v[96:97] op_sel_hi:[1,0]
	v_exp_f32_e32 v97, v102
	s_nop 0
	v_add_f32_e32 v97, 1.0, v97
	v_rcp_f32_e32 v102, v97
	v_exp_f32_e32 v97, v103
	s_nop 0
	v_add_f32_e32 v97, 1.0, v97
	v_rcp_f32_e32 v103, v97
	v_exp_f32_e32 v97, v100
	v_pk_mul_f32 v[92:93], v[98:99], v[102:103] op_sel_hi:[0,1]
	v_add_f32_e32 v97, 1.0, v97
	v_rcp_f32_e32 v100, v97
	v_exp_f32_e32 v97, v101
	v_pk_mul_f32 v[88:89], v[88:89], v[92:93]
	v_add_f32_e32 v97, 1.0, v97
	v_rcp_f32_e32 v101, v97
	v_cvt_pk_bf16_f32 v92, v89, s0
	v_cvt_pk_bf16_f32 v88, v88, s0
	v_pk_mul_f32 v[94:95], v[98:99], v[100:101] op_sel_hi:[0,1]
	v_pk_mul_f32 v[90:91], v[90:91], v[94:95]
	s_nop 0
	v_cvt_pk_bf16_f32 v89, v90, v91
	v_lshlrev_b32_e32 v90, 16, v92
	v_pk_mul_f32 v[92:93], v[84:85], v[96:97] op_sel_hi:[1,0]
	v_or_b32_sdwa v88, v90, v88 dst_sel:DWORD dst_unused:UNUSED_PAD src0_sel:DWORD src1_sel:WORD_0
	v_pk_mul_f32 v[90:91], v[86:87], v[96:97] op_sel_hi:[1,0]
	v_exp_f32_e32 v92, v92
	v_exp_f32_e32 v93, v93
	v_exp_f32_e32 v90, v90
	v_exp_f32_e32 v91, v91
	v_add_f32_e32 v92, 1.0, v92
	v_add_f32_e32 v93, 1.0, v93
	v_rcp_f32_e32 v92, v92
	v_rcp_f32_e32 v93, v93
	v_add_f32_e32 v90, 1.0, v90
	v_add_f32_e32 v91, 1.0, v91
	v_rcp_f32_e32 v90, v90
	v_rcp_f32_e32 v91, v91
	v_pk_mul_f32 v[84:85], v[98:99], v[92:93] op_sel_hi:[0,1]
	v_pk_mul_f32 v[80:81], v[80:81], v[84:85]
	v_pk_mul_f32 v[86:87], v[98:99], v[90:91] op_sel_hi:[0,1]
	v_pk_mul_f32 v[82:83], v[82:83], v[86:87]
	v_cvt_pk_bf16_f32 v90, v80, v81
	v_mad_i64_i32 v[80:81], s[18:19], v144, s9, v[112:113]
	v_cvt_pk_bf16_f32 v91, v82, v83
	v_lshl_add_u64 v[80:81], v[80:81], 0, v[114:115]
	global_store_dwordx4 v[80:81], v[88:91], off
	v_fmamk_f32 v80, v234, 0x3a800000, v194
	s_nop 0
	v_rsq_f32_e32 v80, v80
	s_nop 0
	v_mov_b32_e32 v81, v80
	v_mul_f32_e32 v80, 0xbfb8aa3b, v81
	v_pk_mul_f32 v[86:87], v[76:77], v[80:81] op_sel_hi:[1,0]
	v_mul_f32_e32 v82, v81, v81
	v_pk_mul_f32 v[84:85], v[78:79], v[80:81] op_sel_hi:[1,0]
	v_exp_f32_e32 v81, v86
	s_nop 0
	v_add_f32_e32 v81, 1.0, v81
	v_rcp_f32_e32 v86, v81
	v_exp_f32_e32 v81, v87
	s_nop 0
	v_add_f32_e32 v81, 1.0, v81
	v_rcp_f32_e32 v87, v81
	v_exp_f32_e32 v81, v84
	v_pk_mul_f32 v[76:77], v[82:83], v[86:87] op_sel_hi:[0,1]
	v_add_f32_e32 v81, 1.0, v81
	v_rcp_f32_e32 v84, v81
	v_exp_f32_e32 v81, v85
	v_pk_mul_f32 v[72:73], v[72:73], v[76:77]
	v_add_f32_e32 v81, 1.0, v81
	v_rcp_f32_e32 v85, v81
	v_cvt_pk_bf16_f32 v76, v73, s0
	v_cvt_pk_bf16_f32 v72, v72, s0
	v_pk_mul_f32 v[78:79], v[82:83], v[84:85] op_sel_hi:[0,1]
	v_pk_mul_f32 v[74:75], v[74:75], v[78:79]
	s_nop 0
	v_cvt_pk_bf16_f32 v73, v74, v75
	v_lshlrev_b32_e32 v74, 16, v76
	v_pk_mul_f32 v[76:77], v[68:69], v[80:81] op_sel_hi:[1,0]
	v_or_b32_sdwa v72, v74, v72 dst_sel:DWORD dst_unused:UNUSED_PAD src0_sel:DWORD src1_sel:WORD_0
	v_pk_mul_f32 v[74:75], v[70:71], v[80:81] op_sel_hi:[1,0]
	v_exp_f32_e32 v76, v76
	v_exp_f32_e32 v77, v77
	v_exp_f32_e32 v74, v74
	v_exp_f32_e32 v75, v75
	v_add_f32_e32 v76, 1.0, v76
	v_add_f32_e32 v77, 1.0, v77
	v_rcp_f32_e32 v76, v76
	v_rcp_f32_e32 v77, v77
	v_add_f32_e32 v74, 1.0, v74
	v_add_f32_e32 v75, 1.0, v75
	v_rcp_f32_e32 v74, v74
	v_rcp_f32_e32 v75, v75
	v_pk_mul_f32 v[68:69], v[82:83], v[76:77] op_sel_hi:[0,1]
	v_pk_mul_f32 v[64:65], v[64:65], v[68:69]
	v_add_u32_e32 v69, 0x90, v138
	v_pk_mul_f32 v[70:71], v[82:83], v[74:75] op_sel_hi:[0,1]
	v_pk_mul_f32 v[66:67], v[66:67], v[70:71]
	v_cvt_pk_bf16_f32 v74, v64, v65
	v_mad_i64_i32 v[64:65], s[18:19], v142, s9, v[112:113]
	v_cvt_pk_bf16_f32 v75, v66, v67
	v_lshl_add_u64 v[64:65], v[64:65], 0, v[114:115]
	global_store_dwordx4 v[64:65], v[72:75], off
	v_add_u32_e32 v67, 0x80, v138
	v_add_u32_e32 v66, 0xa0, v138
	v_add_u32_e32 v64, 0xb0, v138
	v_fmamk_f32 v68, v235, 0x3a800000, v194
	s_nop 0
	v_rsq_f32_e32 v68, v68
	s_nop 0
	v_mov_b32_e32 v70, v68
	v_mul_f32_e32 v68, 0xbfb8aa3b, v70
	v_pk_mul_f32 v[74:75], v[60:61], v[68:69] op_sel_hi:[1,0]
	v_pk_mul_f32 v[72:73], v[62:63], v[68:69] op_sel_hi:[1,0]
	v_exp_f32_e32 v74, v74
	v_exp_f32_e32 v75, v75
	v_exp_f32_e32 v72, v72
	v_exp_f32_e32 v73, v73
	v_add_f32_e32 v74, 1.0, v74
	v_add_f32_e32 v75, 1.0, v75
	v_rcp_f32_e32 v74, v74
	v_rcp_f32_e32 v75, v75
	v_add_f32_e32 v72, 1.0, v72
	v_add_f32_e32 v73, 1.0, v73
	v_rcp_f32_e32 v72, v72
	v_rcp_f32_e32 v73, v73
	v_mul_f32_e32 v70, v70, v70
	v_pk_mul_f32 v[60:61], v[70:71], v[74:75] op_sel_hi:[0,1]
	v_pk_mul_f32 v[56:57], v[56:57], v[60:61]
	v_pk_mul_f32 v[62:63], v[70:71], v[72:73] op_sel_hi:[0,1]
	v_pk_mul_f32 v[58:59], v[58:59], v[62:63]
	v_cvt_pk_bf16_f32 v60, v57, s0
	v_cvt_pk_bf16_f32 v56, v56, s0
	v_cvt_pk_bf16_f32 v57, v58, v59
	v_lshlrev_b32_e32 v58, 16, v60
	v_pk_mul_f32 v[60:61], v[52:53], v[68:69] op_sel_hi:[1,0]
	v_or_b32_sdwa v56, v58, v56 dst_sel:DWORD dst_unused:UNUSED_PAD src0_sel:DWORD src1_sel:WORD_0
	v_pk_mul_f32 v[58:59], v[54:55], v[68:69] op_sel_hi:[1,0]
	v_exp_f32_e32 v60, v60
	v_exp_f32_e32 v61, v61
	v_exp_f32_e32 v58, v58
	v_exp_f32_e32 v59, v59
	v_add_f32_e32 v60, 1.0, v60
	v_add_f32_e32 v61, 1.0, v61
	v_rcp_f32_e32 v60, v60
	v_rcp_f32_e32 v61, v61
	v_add_f32_e32 v58, 1.0, v58
	v_add_f32_e32 v59, 1.0, v59
	v_rcp_f32_e32 v58, v58
	v_rcp_f32_e32 v59, v59
	v_pk_mul_f32 v[52:53], v[70:71], v[60:61] op_sel_hi:[0,1]
	v_pk_mul_f32 v[48:49], v[48:49], v[52:53]
	v_pk_mul_f32 v[54:55], v[70:71], v[58:59] op_sel_hi:[0,1]
	v_pk_mul_f32 v[50:51], v[50:51], v[54:55]
	v_cvt_pk_bf16_f32 v58, v48, v49
	v_mad_i64_i32 v[48:49], s[18:19], v67, s9, v[112:113]
	v_cvt_pk_bf16_f32 v59, v50, v51
	v_lshl_add_u64 v[48:49], v[48:49], 0, v[114:115]
	global_store_dwordx4 v[48:49], v[56:59], off
	v_fmamk_f32 v48, v236, 0x3a800000, v194
	s_nop 0
	v_rsq_f32_e32 v48, v48
	s_nop 0
	v_mov_b32_e32 v49, v48
	v_mul_f32_e32 v48, 0xbfb8aa3b, v49
	v_pk_mul_f32 v[54:55], v[44:45], v[48:49] op_sel_hi:[1,0]
	v_mul_f32_e32 v50, v49, v49
	v_pk_mul_f32 v[52:53], v[46:47], v[48:49] op_sel_hi:[1,0]
	v_exp_f32_e32 v49, v54
	s_nop 0
	v_add_f32_e32 v49, 1.0, v49
	v_rcp_f32_e32 v54, v49
	v_exp_f32_e32 v49, v55
	s_nop 0
	v_add_f32_e32 v49, 1.0, v49
	v_rcp_f32_e32 v55, v49
	v_exp_f32_e32 v49, v52
	v_pk_mul_f32 v[44:45], v[50:51], v[54:55] op_sel_hi:[0,1]
	v_add_f32_e32 v49, 1.0, v49
	v_rcp_f32_e32 v52, v49
	v_exp_f32_e32 v49, v53
	v_pk_mul_f32 v[40:41], v[40:41], v[44:45]
	v_add_f32_e32 v49, 1.0, v49
	v_rcp_f32_e32 v53, v49
	v_cvt_pk_bf16_f32 v44, v41, s0
	v_cvt_pk_bf16_f32 v40, v40, s0
	v_pk_mul_f32 v[46:47], v[50:51], v[52:53] op_sel_hi:[0,1]
	v_pk_mul_f32 v[42:43], v[42:43], v[46:47]
	s_nop 0
	v_cvt_pk_bf16_f32 v41, v42, v43
	v_lshlrev_b32_e32 v42, 16, v44
	v_pk_mul_f32 v[44:45], v[36:37], v[48:49] op_sel_hi:[1,0]
	v_or_b32_sdwa v40, v42, v40 dst_sel:DWORD dst_unused:UNUSED_PAD src0_sel:DWORD src1_sel:WORD_0
	v_pk_mul_f32 v[42:43], v[38:39], v[48:49] op_sel_hi:[1,0]
	v_exp_f32_e32 v44, v44
	v_exp_f32_e32 v45, v45
	v_exp_f32_e32 v42, v42
	v_exp_f32_e32 v43, v43
	v_add_f32_e32 v44, 1.0, v44
	v_add_f32_e32 v45, 1.0, v45
	v_rcp_f32_e32 v44, v44
	v_rcp_f32_e32 v45, v45
	v_add_f32_e32 v42, 1.0, v42
	v_add_f32_e32 v43, 1.0, v43
	v_rcp_f32_e32 v42, v42
	v_rcp_f32_e32 v43, v43
	v_pk_mul_f32 v[36:37], v[50:51], v[44:45] op_sel_hi:[0,1]
	v_pk_mul_f32 v[32:33], v[32:33], v[36:37]
	v_pk_mul_f32 v[38:39], v[50:51], v[42:43] op_sel_hi:[0,1]
	v_pk_mul_f32 v[34:35], v[34:35], v[38:39]
	v_cvt_pk_bf16_f32 v42, v32, v33
	v_mad_i64_i32 v[32:33], s[18:19], v69, s9, v[112:113]
	v_cvt_pk_bf16_f32 v43, v34, v35
	v_lshl_add_u64 v[32:33], v[32:33], 0, v[114:115]
	global_store_dwordx4 v[32:33], v[40:43], off
	v_fmamk_f32 v32, v237, 0x3a800000, v194
	s_nop 0
	v_rsq_f32_e32 v32, v32
	s_nop 0
	v_mov_b32_e32 v33, v32
	v_mul_f32_e32 v32, 0xbfb8aa3b, v33
	v_pk_mul_f32 v[38:39], v[28:29], v[32:33] op_sel_hi:[1,0]
	v_mul_f32_e32 v34, v33, v33
	v_pk_mul_f32 v[36:37], v[30:31], v[32:33] op_sel_hi:[1,0]
	v_exp_f32_e32 v33, v38
	s_nop 0
	v_add_f32_e32 v33, 1.0, v33
	v_rcp_f32_e32 v38, v33
	v_exp_f32_e32 v33, v39
	s_nop 0
	v_add_f32_e32 v33, 1.0, v33
	v_rcp_f32_e32 v39, v33
	v_exp_f32_e32 v33, v36
	v_pk_mul_f32 v[28:29], v[34:35], v[38:39] op_sel_hi:[0,1]
	v_add_f32_e32 v33, 1.0, v33
	v_rcp_f32_e32 v36, v33
	v_exp_f32_e32 v33, v37
	v_pk_mul_f32 v[24:25], v[24:25], v[28:29]
	v_add_f32_e32 v33, 1.0, v33
	v_rcp_f32_e32 v37, v33
	v_cvt_pk_bf16_f32 v28, v25, s0
	v_cvt_pk_bf16_f32 v24, v24, s0
	v_pk_mul_f32 v[30:31], v[34:35], v[36:37] op_sel_hi:[0,1]
	v_pk_mul_f32 v[26:27], v[26:27], v[30:31]
	s_nop 0
	v_cvt_pk_bf16_f32 v25, v26, v27
	v_lshlrev_b32_e32 v26, 16, v28
	v_pk_mul_f32 v[28:29], v[20:21], v[32:33] op_sel_hi:[1,0]
	v_or_b32_sdwa v24, v26, v24 dst_sel:DWORD dst_unused:UNUSED_PAD src0_sel:DWORD src1_sel:WORD_0
	v_pk_mul_f32 v[26:27], v[22:23], v[32:33] op_sel_hi:[1,0]
	v_exp_f32_e32 v28, v28
	v_exp_f32_e32 v29, v29
	v_exp_f32_e32 v26, v26
	v_exp_f32_e32 v27, v27
	v_add_f32_e32 v28, 1.0, v28
	v_add_f32_e32 v29, 1.0, v29
	v_rcp_f32_e32 v28, v28
	v_rcp_f32_e32 v29, v29
	v_add_f32_e32 v26, 1.0, v26
	v_add_f32_e32 v27, 1.0, v27
	v_rcp_f32_e32 v26, v26
	v_rcp_f32_e32 v27, v27
	v_pk_mul_f32 v[20:21], v[34:35], v[28:29] op_sel_hi:[0,1]
	v_pk_mul_f32 v[16:17], v[16:17], v[20:21]
	v_pk_mul_f32 v[22:23], v[34:35], v[26:27] op_sel_hi:[0,1]
	v_pk_mul_f32 v[18:19], v[18:19], v[22:23]
	v_cvt_pk_bf16_f32 v26, v16, v17
	v_mad_i64_i32 v[16:17], s[18:19], v66, s9, v[112:113]
	v_cvt_pk_bf16_f32 v27, v18, v19
	v_lshl_add_u64 v[16:17], v[16:17], 0, v[114:115]
	global_store_dwordx4 v[16:17], v[24:27], off
	v_fmamk_f32 v16, v238, 0x3a800000, v194
	s_nop 0
	v_rsq_f32_e32 v16, v16
	s_nop 0
	v_mov_b32_e32 v17, v16
	v_mul_f32_e32 v16, 0xbfb8aa3b, v17
	v_pk_mul_f32 v[22:23], v[12:13], v[16:17] op_sel_hi:[1,0]
	v_mul_f32_e32 v18, v17, v17
	v_pk_mul_f32 v[20:21], v[14:15], v[16:17] op_sel_hi:[1,0]
	v_exp_f32_e32 v17, v22
	s_and_b64 vcc, exec, s[0:1]
	v_add_f32_e32 v17, 1.0, v17
	v_rcp_f32_e32 v22, v17
	v_exp_f32_e32 v17, v23
	s_nop 0
	v_add_f32_e32 v17, 1.0, v17
	v_rcp_f32_e32 v23, v17
	v_exp_f32_e32 v17, v20
	v_pk_mul_f32 v[12:13], v[18:19], v[22:23] op_sel_hi:[0,1]
	v_add_f32_e32 v17, 1.0, v17
	v_rcp_f32_e32 v20, v17
	v_exp_f32_e32 v17, v21
	v_pk_mul_f32 v[8:9], v[8:9], v[12:13]
	v_add_f32_e32 v17, 1.0, v17
	v_rcp_f32_e32 v21, v17
	v_cvt_pk_bf16_f32 v12, v9, s0
	v_cvt_pk_bf16_f32 v8, v8, s0
	v_pk_mul_f32 v[14:15], v[18:19], v[20:21] op_sel_hi:[0,1]
	v_pk_mul_f32 v[10:11], v[10:11], v[14:15]
	s_nop 0
	v_cvt_pk_bf16_f32 v9, v10, v11
	v_lshlrev_b32_e32 v10, 16, v12
	v_pk_mul_f32 v[12:13], v[4:5], v[16:17] op_sel_hi:[1,0]
	v_or_b32_sdwa v8, v10, v8 dst_sel:DWORD dst_unused:UNUSED_PAD src0_sel:DWORD src1_sel:WORD_0
	v_pk_mul_f32 v[10:11], v[6:7], v[16:17] op_sel_hi:[1,0]
	v_exp_f32_e32 v12, v12
	v_exp_f32_e32 v13, v13
	v_exp_f32_e32 v10, v10
	v_exp_f32_e32 v11, v11
	v_add_f32_e32 v12, 1.0, v12
	v_add_f32_e32 v13, 1.0, v13
	v_rcp_f32_e32 v12, v12
	v_rcp_f32_e32 v13, v13
	v_add_f32_e32 v10, 1.0, v10
	v_add_f32_e32 v11, 1.0, v11
	v_rcp_f32_e32 v10, v10
	v_rcp_f32_e32 v11, v11
	v_pk_mul_f32 v[4:5], v[18:19], v[12:13] op_sel_hi:[0,1]
	v_pk_mul_f32 v[0:1], v[0:1], v[4:5]
	v_pk_mul_f32 v[6:7], v[18:19], v[10:11] op_sel_hi:[0,1]
	v_pk_mul_f32 v[2:3], v[2:3], v[6:7]
	v_cvt_pk_bf16_f32 v10, v0, v1
	v_mad_i64_i32 v[0:1], s[18:19], v64, s9, v[112:113]
	v_cvt_pk_bf16_f32 v11, v2, v3
	v_lshl_add_u64 v[0:1], v[0:1], 0, v[114:115]
	s_mov_b64 s[18:19], s[14:15]
	global_store_dwordx4 v[0:1], v[8:11], off
	s_cbranch_vccz .LBB0_2801
	s_waitcnt vmcnt(0)
	s_cmpk_gt_u32 s25, 0xff
	s_cbranch_scc1 .LBB0_2808
	s_barrier

.LBB0_3618:
	s_add_u32 s20, s18, 0x100
	s_addc_u32 s21, s19, 0
	s_add_i32 s45, 0, 0x10000
	ds_read_b128 v[128:131], v202
	ds_read_b128 v[132:135], v202 offset:1024
	ds_read_b128 v[136:139], v202 offset:2048
	ds_read_b128 v[140:143], v202 offset:3072
	s_cmp_eq_u32 s44, 40
	s_cselect_b32 s25, s5, s21
	s_cselect_b32 s24, s4, s20
	s_cselect_b32 s23, s7, s43
	s_cselect_b32 s22, s6, s33
	s_add_i32 m0, s30, 0xc000
	ds_read_b128 v[144:147], v198
	ds_read_b128 v[148:151], v198 offset:1024
	ds_read_b128 v[152:155], v198 offset:2048
	ds_read_b128 v[156:159], v198 offset:3072
	ds_read_b128 v[160:163], v198 offset:4096
	ds_read_b128 v[164:167], v198 offset:5120
	ds_read_b128 v[168:171], v198 offset:6144
	ds_read_b128 v[172:175], v198 offset:7168
	global_load_lds_dwordx4 v214, s[18:19]
	s_add_i32 m0, s30, 0xe000
	s_nop 0
	global_load_lds_dwordx4 v212, s[18:19]
	s_waitcnt lgkmcnt(8)
	s_barrier
	s_waitcnt lgkmcnt(0)
	v_mfma_f32_16x16x32_bf16 v[124:127], v[128:131], v[144:147], v[124:127]
	v_mfma_f32_16x16x32_bf16 v[120:123], v[136:139], v[144:147], v[120:123]
	v_mfma_f32_16x16x32_bf16 v[108:111], v[128:131], v[152:155], v[108:111]
	v_mfma_f32_16x16x32_bf16 v[104:107], v[136:139], v[152:155], v[104:107]
	v_mfma_f32_16x16x32_bf16 v[92:95], v[128:131], v[160:163], v[92:95]
	v_mfma_f32_16x16x32_bf16 v[88:91], v[136:139], v[160:163], v[88:91]
	v_mfma_f32_16x16x32_bf16 v[76:79], v[128:131], v[168:171], v[76:79]
	v_mfma_f32_16x16x32_bf16 v[72:75], v[136:139], v[168:171], v[72:75]
	v_mfma_f32_16x16x32_bf16 v[124:127], v[132:135], v[148:151], v[124:127]
	v_mfma_f32_16x16x32_bf16 v[120:123], v[140:143], v[148:151], v[120:123]
	v_mfma_f32_16x16x32_bf16 v[108:111], v[132:135], v[156:159], v[108:111]
	v_mfma_f32_16x16x32_bf16 v[104:107], v[140:143], v[156:159], v[104:107]
	v_mfma_f32_16x16x32_bf16 v[92:95], v[132:135], v[164:167], v[92:95]
	v_mfma_f32_16x16x32_bf16 v[88:91], v[140:143], v[164:167], v[88:91]
	v_mfma_f32_16x16x32_bf16 v[76:79], v[132:135], v[172:175], v[76:79]
	v_mfma_f32_16x16x32_bf16 v[72:75], v[140:143], v[172:175], v[72:75]
	s_barrier
	s_add_i32 s46, 0, 0x14000
	s_add_i32 s18, s45, s29
	s_mov_b32 m0, s18
	ds_read_b128 v[176:179], v203
	ds_read_b128 v[180:183], v203 offset:1024
	ds_read_b128 v[184:187], v203 offset:2048
	ds_read_b128 v[188:191], v203 offset:3072
	global_load_lds_dwordx4 v192, s[22:23]
	s_add_i32 m0, s18, 0x2000
	s_nop 0
	global_load_lds_dwordx4 v210, s[22:23]
	s_barrier
	s_waitcnt lgkmcnt(0)
	v_mfma_f32_16x16x32_bf16 v[116:119], v[176:179], v[144:147], v[116:119]
	v_mfma_f32_16x16x32_bf16 v[112:115], v[184:187], v[144:147], v[112:115]
	v_mfma_f32_16x16x32_bf16 v[100:103], v[176:179], v[152:155], v[100:103]
	v_mfma_f32_16x16x32_bf16 v[96:99], v[184:187], v[152:155], v[96:99]
	v_mfma_f32_16x16x32_bf16 v[84:87], v[176:179], v[160:163], v[84:87]
	v_mfma_f32_16x16x32_bf16 v[80:83], v[184:187], v[160:163], v[80:83]
	v_mfma_f32_16x16x32_bf16 v[68:71], v[176:179], v[168:171], v[68:71]
	v_mfma_f32_16x16x32_bf16 v[64:67], v[184:187], v[168:171], v[64:67]
	v_mfma_f32_16x16x32_bf16 v[116:119], v[180:183], v[148:151], v[116:119]
	v_mfma_f32_16x16x32_bf16 v[112:115], v[188:191], v[148:151], v[112:115]
	v_mfma_f32_16x16x32_bf16 v[100:103], v[180:183], v[156:159], v[100:103]
	v_mfma_f32_16x16x32_bf16 v[96:99], v[188:191], v[156:159], v[96:99]
	v_mfma_f32_16x16x32_bf16 v[84:87], v[180:183], v[164:167], v[84:87]
	v_mfma_f32_16x16x32_bf16 v[80:83], v[188:191], v[164:167], v[80:83]
	v_mfma_f32_16x16x32_bf16 v[68:71], v[180:183], v[172:175], v[68:71]
	v_mfma_f32_16x16x32_bf16 v[64:67], v[188:191], v[172:175], v[64:67]
	s_mov_b32 m0, s30
	s_add_u32 vcc_lo, s24, 0x80
	s_addc_u32 vcc_hi, s25, 0
	s_barrier
	ds_read_b128 v[144:147], v198 offset:16384
	ds_read_b128 v[148:151], v198 offset:17408
	ds_read_b128 v[152:155], v198 offset:18432
	ds_read_b128 v[156:159], v198 offset:19456
	ds_read_b128 v[160:163], v198 offset:20480
	ds_read_b128 v[164:167], v198 offset:21504
	ds_read_b128 v[168:171], v198 offset:22528
	ds_read_b128 v[172:175], v198 offset:23552
	global_load_lds_dwordx4 v206, s[24:25]
	s_mov_b32 m0, s31
	s_nop 0
	global_load_lds_dwordx4 v208, s[24:25]
	s_barrier
	s_waitcnt lgkmcnt(0)
	v_mfma_f32_16x16x32_bf16 v[60:63], v[128:131], v[144:147], v[60:63]
	v_mfma_f32_16x16x32_bf16 v[56:59], v[136:139], v[144:147], v[56:59]
	v_mfma_f32_16x16x32_bf16 v[44:47], v[128:131], v[152:155], v[44:47]
	v_mfma_f32_16x16x32_bf16 v[40:43], v[136:139], v[152:155], v[40:43]
	v_mfma_f32_16x16x32_bf16 v[28:31], v[128:131], v[160:163], v[28:31]
	v_mfma_f32_16x16x32_bf16 v[24:27], v[136:139], v[160:163], v[24:27]
	v_mfma_f32_16x16x32_bf16 v[12:15], v[128:131], v[168:171], v[12:15]
	v_mfma_f32_16x16x32_bf16 v[8:11], v[136:139], v[168:171], v[8:11]
	v_mfma_f32_16x16x32_bf16 v[60:63], v[132:135], v[148:151], v[60:63]
	v_mfma_f32_16x16x32_bf16 v[56:59], v[140:143], v[148:151], v[56:59]
	v_mfma_f32_16x16x32_bf16 v[44:47], v[132:135], v[156:159], v[44:47]
	v_mfma_f32_16x16x32_bf16 v[40:43], v[140:143], v[156:159], v[40:43]
	v_mfma_f32_16x16x32_bf16 v[28:31], v[132:135], v[164:167], v[28:31]
	v_mfma_f32_16x16x32_bf16 v[24:27], v[140:143], v[164:167], v[24:27]
	v_mfma_f32_16x16x32_bf16 v[12:15], v[132:135], v[172:175], v[12:15]
	v_mfma_f32_16x16x32_bf16 v[8:11], v[140:143], v[172:175], v[8:11]
	s_barrier
	s_add_u32 s18, s22, 0xb0000
	s_addc_u32 s19, s23, 0
	s_add_i32 s45, s46, s29
	s_mov_b32 m0, s45
	s_nop 0
	global_load_lds_dwordx4 v192, s[18:19]
	s_add_i32 m0, s45, 0x2000
	s_nop 0
	global_load_lds_dwordx4 v210, s[18:19]
	s_waitcnt vmcnt(6)
	s_barrier
	v_mfma_f32_16x16x32_bf16 v[52:55], v[176:179], v[144:147], v[52:55]
	v_mfma_f32_16x16x32_bf16 v[48:51], v[184:187], v[144:147], v[48:51]
	v_mfma_f32_16x16x32_bf16 v[36:39], v[176:179], v[152:155], v[36:39]
	v_mfma_f32_16x16x32_bf16 v[32:35], v[184:187], v[152:155], v[32:35]
	v_mfma_f32_16x16x32_bf16 v[20:23], v[176:179], v[160:163], v[20:23]
	v_mfma_f32_16x16x32_bf16 v[16:19], v[184:187], v[160:163], v[16:19]
	v_mfma_f32_16x16x32_bf16 v[4:7], v[176:179], v[168:171], v[4:7]
	v_mfma_f32_16x16x32_bf16 v[0:3], v[184:187], v[168:171], v[0:3]
	v_mfma_f32_16x16x32_bf16 v[52:55], v[180:183], v[148:151], v[52:55]
	v_mfma_f32_16x16x32_bf16 v[48:51], v[188:191], v[148:151], v[48:51]
	v_mfma_f32_16x16x32_bf16 v[36:39], v[180:183], v[156:159], v[36:39]
	v_mfma_f32_16x16x32_bf16 v[32:35], v[188:191], v[156:159], v[32:35]
	v_mfma_f32_16x16x32_bf16 v[20:23], v[180:183], v[164:167], v[20:23]
	v_mfma_f32_16x16x32_bf16 v[16:19], v[188:191], v[164:167], v[16:19]
	v_mfma_f32_16x16x32_bf16 v[4:7], v[180:183], v[172:175], v[4:7]
	v_mfma_f32_16x16x32_bf16 v[0:3], v[188:191], v[172:175], v[0:3]
	s_add_i32 s45, 0, 0x18000
	s_barrier
	ds_read_b128 v[128:131], v204
	ds_read_b128 v[132:135], v204 offset:1024
	ds_read_b128 v[136:139], v204 offset:2048
	ds_read_b128 v[140:143], v204 offset:3072
	s_add_u32 s18, s24, 0xb0000
	s_addc_u32 s19, s25, 0
	s_mov_b32 m0, s34
	ds_read_b128 v[144:147], v198 offset:32768
	ds_read_b128 v[148:151], v198 offset:33792
	ds_read_b128 v[152:155], v198 offset:34816
	ds_read_b128 v[156:159], v198 offset:35840
	ds_read_b128 v[160:163], v198 offset:36864
	ds_read_b128 v[164:167], v198 offset:37888
	ds_read_b128 v[168:171], v198 offset:38912
	ds_read_b128 v[172:175], v198 offset:39936
	global_load_lds_dwordx4 v206, s[18:19]
	s_mov_b32 m0, s35
	s_nop 0
	global_load_lds_dwordx4 v208, s[18:19]
	s_waitcnt lgkmcnt(8)
	s_barrier
	s_waitcnt lgkmcnt(0)
	v_mfma_f32_16x16x32_bf16 v[124:127], v[128:131], v[144:147], v[124:127]
	v_mfma_f32_16x16x32_bf16 v[120:123], v[136:139], v[144:147], v[120:123]
	v_mfma_f32_16x16x32_bf16 v[108:111], v[128:131], v[152:155], v[108:111]
	v_mfma_f32_16x16x32_bf16 v[104:107], v[136:139], v[152:155], v[104:107]
	v_mfma_f32_16x16x32_bf16 v[92:95], v[128:131], v[160:163], v[92:95]
	v_mfma_f32_16x16x32_bf16 v[88:91], v[136:139], v[160:163], v[88:91]
	v_mfma_f32_16x16x32_bf16 v[76:79], v[128:131], v[168:171], v[76:79]
	v_mfma_f32_16x16x32_bf16 v[72:75], v[136:139], v[168:171], v[72:75]
	v_mfma_f32_16x16x32_bf16 v[124:127], v[132:135], v[148:151], v[124:127]
	v_mfma_f32_16x16x32_bf16 v[120:123], v[140:143], v[148:151], v[120:123]
	v_mfma_f32_16x16x32_bf16 v[108:111], v[132:135], v[156:159], v[108:111]
	v_mfma_f32_16x16x32_bf16 v[104:107], v[140:143], v[156:159], v[104:107]
	v_mfma_f32_16x16x32_bf16 v[92:95], v[132:135], v[164:167], v[92:95]
	v_mfma_f32_16x16x32_bf16 v[88:91], v[140:143], v[164:167], v[88:91]
	v_mfma_f32_16x16x32_bf16 v[76:79], v[132:135], v[172:175], v[76:79]
	v_mfma_f32_16x16x32_bf16 v[72:75], v[140:143], v[172:175], v[72:75]
	s_barrier
	s_add_i32 s24, 0, 0x1c000
	s_add_i32 s18, s45, s29
	s_add_u32 s100, s22, 0x80
	s_addc_u32 s101, s23, 0
	s_mov_b32 m0, s18
	ds_read_b128 v[176:179], v205
	ds_read_b128 v[180:183], v205 offset:1024
	ds_read_b128 v[184:187], v205 offset:2048
	ds_read_b128 v[188:191], v205 offset:3072
	global_load_lds_dwordx4 v192, s[100:101]
	s_add_i32 m0, s18, 0x2000
	s_nop 0
	global_load_lds_dwordx4 v210, s[100:101]
	s_barrier
	s_waitcnt lgkmcnt(0)
	v_mfma_f32_16x16x32_bf16 v[116:119], v[176:179], v[144:147], v[116:119]
	v_mfma_f32_16x16x32_bf16 v[112:115], v[184:187], v[144:147], v[112:115]
	v_mfma_f32_16x16x32_bf16 v[100:103], v[176:179], v[152:155], v[100:103]
	v_mfma_f32_16x16x32_bf16 v[96:99], v[184:187], v[152:155], v[96:99]
	v_mfma_f32_16x16x32_bf16 v[84:87], v[176:179], v[160:163], v[84:87]
	v_mfma_f32_16x16x32_bf16 v[80:83], v[184:187], v[160:163], v[80:83]
	v_mfma_f32_16x16x32_bf16 v[68:71], v[176:179], v[168:171], v[68:71]
	v_mfma_f32_16x16x32_bf16 v[64:67], v[184:187], v[168:171], v[64:67]
	v_mfma_f32_16x16x32_bf16 v[116:119], v[180:183], v[148:151], v[116:119]
	v_mfma_f32_16x16x32_bf16 v[112:115], v[188:191], v[148:151], v[112:115]
	v_mfma_f32_16x16x32_bf16 v[100:103], v[180:183], v[156:159], v[100:103]
	v_mfma_f32_16x16x32_bf16 v[96:99], v[188:191], v[156:159], v[96:99]
	v_mfma_f32_16x16x32_bf16 v[84:87], v[180:183], v[164:167], v[84:87]
	v_mfma_f32_16x16x32_bf16 v[80:83], v[188:191], v[164:167], v[80:83]
	v_mfma_f32_16x16x32_bf16 v[68:71], v[180:183], v[172:175], v[68:71]
	v_mfma_f32_16x16x32_bf16 v[64:67], v[188:191], v[172:175], v[64:67]
	s_mov_b32 m0, s36
	s_barrier
	ds_read_b128 v[144:147], v198 offset:49152
	ds_read_b128 v[148:151], v198 offset:50176
	ds_read_b128 v[152:155], v198 offset:51200
	ds_read_b128 v[156:159], v198 offset:52224
	ds_read_b128 v[160:163], v198 offset:53248
	ds_read_b128 v[164:167], v198 offset:54272
	ds_read_b128 v[168:171], v198 offset:55296
	ds_read_b128 v[172:175], v198 offset:56320
	global_load_lds_dwordx4 v206, vcc
	s_mov_b32 m0, s37
	s_nop 0
	global_load_lds_dwordx4 v208, vcc
	s_barrier
	s_waitcnt lgkmcnt(0)
	v_mfma_f32_16x16x32_bf16 v[60:63], v[128:131], v[144:147], v[60:63]
	v_mfma_f32_16x16x32_bf16 v[56:59], v[136:139], v[144:147], v[56:59]
	v_mfma_f32_16x16x32_bf16 v[44:47], v[128:131], v[152:155], v[44:47]
	v_mfma_f32_16x16x32_bf16 v[40:43], v[136:139], v[152:155], v[40:43]
	v_mfma_f32_16x16x32_bf16 v[28:31], v[128:131], v[160:163], v[28:31]
	v_mfma_f32_16x16x32_bf16 v[24:27], v[136:139], v[160:163], v[24:27]
	v_mfma_f32_16x16x32_bf16 v[12:15], v[128:131], v[168:171], v[12:15]
	v_mfma_f32_16x16x32_bf16 v[8:11], v[136:139], v[168:171], v[8:11]
	v_mfma_f32_16x16x32_bf16 v[60:63], v[132:135], v[148:151], v[60:63]
	v_mfma_f32_16x16x32_bf16 v[56:59], v[140:143], v[148:151], v[56:59]
	v_mfma_f32_16x16x32_bf16 v[44:47], v[132:135], v[156:159], v[44:47]
	v_mfma_f32_16x16x32_bf16 v[40:43], v[140:143], v[156:159], v[40:43]
	v_mfma_f32_16x16x32_bf16 v[28:31], v[132:135], v[164:167], v[28:31]
	v_mfma_f32_16x16x32_bf16 v[24:27], v[140:143], v[164:167], v[24:27]
	v_mfma_f32_16x16x32_bf16 v[12:15], v[132:135], v[172:175], v[12:15]
	v_mfma_f32_16x16x32_bf16 v[8:11], v[140:143], v[172:175], v[8:11]
	s_barrier
	s_add_u32 s18, s22, 0xb0080
	s_addc_u32 s19, s23, 0
	s_add_i32 s22, s24, s29
	s_mov_b32 m0, s22
	s_nop 0
	global_load_lds_dwordx4 v192, s[18:19]
	s_add_i32 m0, s22, 0x2000
	s_nop 0
	global_load_lds_dwordx4 v210, s[18:19]
	s_waitcnt vmcnt(6)
	s_barrier
	v_mfma_f32_16x16x32_bf16 v[52:55], v[176:179], v[144:147], v[52:55]
	v_mfma_f32_16x16x32_bf16 v[48:51], v[184:187], v[144:147], v[48:51]
	v_mfma_f32_16x16x32_bf16 v[36:39], v[176:179], v[152:155], v[36:39]
	v_mfma_f32_16x16x32_bf16 v[32:35], v[184:187], v[152:155], v[32:35]
	v_mfma_f32_16x16x32_bf16 v[20:23], v[176:179], v[160:163], v[20:23]
	v_mfma_f32_16x16x32_bf16 v[16:19], v[184:187], v[160:163], v[16:19]
	v_mfma_f32_16x16x32_bf16 v[4:7], v[176:179], v[168:171], v[4:7]
	v_mfma_f32_16x16x32_bf16 v[0:3], v[184:187], v[168:171], v[0:3]
	v_mfma_f32_16x16x32_bf16 v[52:55], v[180:183], v[148:151], v[52:55]
	v_mfma_f32_16x16x32_bf16 v[48:51], v[188:191], v[148:151], v[48:51]
	v_mfma_f32_16x16x32_bf16 v[36:39], v[180:183], v[156:159], v[36:39]
	v_mfma_f32_16x16x32_bf16 v[32:35], v[188:191], v[156:159], v[32:35]
	v_mfma_f32_16x16x32_bf16 v[20:23], v[180:183], v[164:167], v[20:23]
	v_mfma_f32_16x16x32_bf16 v[16:19], v[188:191], v[164:167], v[16:19]
	v_mfma_f32_16x16x32_bf16 v[4:7], v[180:183], v[172:175], v[4:7]
	v_mfma_f32_16x16x32_bf16 v[0:3], v[188:191], v[172:175], v[0:3]
	s_add_i32 s44, s44, 2
	s_add_u32 s33, s33, 0x100
	s_addc_u32 s43, s43, 0
	s_cmp_gt_u32 s44, 41
	s_mov_b64 s[18:19], s[20:21]
	s_barrier
	s_cbranch_scc0 .LBB0_3618
	v_mov_b32_e32 v128, v252
	s_lshl_b32 s19, s42, 8
	v_readfirstlane_b32 s18, v128
	s_ashr_i32 s20, s18, 2
	s_andn2_b32 s20, s20, 63
	s_lshr_b32 s18, s18, 1
	s_add_i32 s20, s20, s19
	s_and_b32 s18, s18, 0x60
	s_lshl_b32 s19, s41, 8
	v_and_or_b32 v218, v128, 15, s20
	v_lshrrev_b32_e32 v128, 1, v128
	s_or_b32 s18, s18, s19
	v_and_b32_e32 v129, 64, v195
	v_and_or_b32 v216, v128, 24, s18
	v_xor_b32_e32 v128, 16, v195
	v_add_u32_e32 v129, 64, v129
	v_cmp_lt_i32_e32 vcc, v128, v129
	v_ashrrev_i32_e32 v219, 31, v218
	v_ashrrev_i32_e32 v217, 31, v216
	v_cndmask_b32_e32 v128, v195, v128, vcc
	v_lshlrev_b32_e32 v200, 2, v128
	v_xor_b32_e32 v128, 32, v195
	v_cmp_lt_i32_e32 vcc, v128, v129
	v_or_b32_e32 v220, 0x80, v216
	v_ashrrev_i32_e32 v221, 31, v220
	v_cndmask_b32_e32 v128, v195, v128, vcc
	v_lshlrev_b32_e32 v199, 2, v128
	v_lshlrev_b64 v[128:129], 10, v[218:219]
	v_lshl_add_u64 v[130:131], v[128:129], 0, v[216:217]
	v_lshlrev_b64 v[130:131], 1, v[130:131]
	v_lshl_add_u64 v[246:247], s[10:11], 0, v[130:131]
	v_lshl_add_u64 v[250:251], s[12:13], 0, v[130:131]
	global_load_dwordx4 v[188:191], v[246:247], off
	global_load_dwordx4 v[180:183], v[246:247], off offset:256
	global_load_dwordx4 v[184:187], v[250:251], off
	v_or_b32_e32 v242, 16, v218
	v_lshl_add_u64 v[128:129], v[128:129], 0, v[220:221]
	v_ashrrev_i32_e32 v243, 31, v242
	v_lshl_add_u64 v[248:249], v[128:129], 1, s[12:13]
	v_lshlrev_b64 v[128:129], 10, v[242:243]
	v_or_b32_e32 v234, 32, v218
	v_lshl_add_u64 v[130:131], v[128:129], 0, v[216:217]
	v_lshl_add_u64 v[128:129], v[128:129], 0, v[220:221]
	v_ashrrev_i32_e32 v235, 31, v234
	v_lshlrev_b64 v[130:131], 1, v[130:131]
	v_lshl_add_u64 v[240:241], v[128:129], 1, s[12:13]
	v_lshlrev_b64 v[128:129], 10, v[234:235]
	v_or_b32_e32 v226, 48, v218
	v_lshl_add_u64 v[238:239], s[10:11], 0, v[130:131]
	v_lshl_add_u64 v[244:245], s[12:13], 0, v[130:131]
	v_lshl_add_u64 v[130:131], v[128:129], 0, v[216:217]
	v_lshl_add_u64 v[128:129], v[128:129], 0, v[220:221]
	v_ashrrev_i32_e32 v227, 31, v226
	v_lshlrev_b64 v[130:131], 1, v[130:131]
	v_lshl_add_u64 v[232:233], v[128:129], 1, s[12:13]
	v_lshlrev_b64 v[128:129], 10, v[226:227]
	v_lshl_add_u64 v[228:229], s[10:11], 0, v[130:131]
	v_lshl_add_u64 v[236:237], s[12:13], 0, v[130:131]
	v_lshl_add_u64 v[130:131], v[128:129], 0, v[216:217]
	v_lshlrev_b64 v[130:131], 1, v[130:131]
	v_lshl_add_u64 v[132:133], v[128:129], 0, v[220:221]
	v_lshl_add_u64 v[222:223], s[10:11], 0, v[130:131]
	v_lshl_add_u64 v[230:231], s[12:13], 0, v[130:131]
	v_lshl_add_u64 v[224:225], v[132:133], 1, s[12:13]
	global_load_dwordx4 v[176:179], v[248:249], off
	global_load_dwordx4 v[172:175], v[238:239], off
	global_load_dwordx4 v[164:167], v[238:239], off offset:256
	global_load_dwordx4 v[168:171], v[244:245], off
	global_load_dwordx4 v[160:163], v[240:241], off
	global_load_dwordx4 v[156:159], v[228:229], off
	global_load_dwordx4 v[132:135], v[224:225], off
	global_load_dwordx4 v[152:155], v[236:237], off
	global_load_dwordx4 v[144:147], v[232:233], off
	global_load_dwordx4 v[148:151], v[228:229], off offset:256
	global_load_dwordx4 v[136:139], v[230:231], off
	global_load_dwordx4 v[140:143], v[222:223], off
	global_load_dwordx4 v[128:131], v[222:223], off offset:256
	v_cmp_gt_u32_e32 vcc, 16, v195
	s_waitcnt vmcnt(0)
	v_lshlrev_b32_e32 v202, 16, v188
	v_and_b32_e32 v203, 0xffff0000, v188
	v_lshlrev_b32_e32 v204, 16, v184
	v_and_b32_e32 v205, 0xffff0000, v184
	v_lshlrev_b32_e32 v188, 16, v189
	v_and_b32_e32 v189, 0xffff0000, v189
	v_lshlrev_b32_e32 v184, 16, v185
	v_and_b32_e32 v185, 0xffff0000, v185
	v_pk_add_f32 v[202:203], v[202:203], v[204:205]
	v_pk_add_f32 v[184:185], v[188:189], v[184:185]
	v_pk_fma_f32 v[188:189], v[124:125], 0.5, v[202:203] op_sel_hi:[1,0,1]
	v_pk_fma_f32 v[184:185], v[126:127], 0.5, v[184:185] op_sel_hi:[1,0,1]
	v_lshlrev_b32_e32 v124, 16, v190
	v_and_b32_e32 v125, 0xffff0000, v190
	v_lshlrev_b32_e32 v126, 16, v186
	v_and_b32_e32 v127, 0xffff0000, v186
	v_pk_add_f32 v[124:125], v[124:125], v[126:127]
	v_lshlrev_b32_e32 v126, 16, v191
	v_and_b32_e32 v127, 0xffff0000, v191
	v_lshlrev_b32_e32 v186, 16, v187
	v_and_b32_e32 v187, 0xffff0000, v187
	v_pk_add_f32 v[126:127], v[126:127], v[186:187]
	v_pk_fma_f32 v[190:191], v[120:121], 0.5, v[124:125] op_sel_hi:[1,0,1]
	v_cvt_pk_bf16_f32 v120, v188, v189
	v_pk_fma_f32 v[186:187], v[122:123], 0.5, v[126:127] op_sel_hi:[1,0,1]
	v_and_b32_e32 v123, 0xffff0000, v120
	v_lshlrev_b32_e32 v122, 16, v120
	v_pk_add_f32 v[122:123], v[188:189], v[122:123] neg_lo:[0,1] neg_hi:[0,1]
	v_cvt_pk_bf16_f32 v121, v184, v185
	v_cvt_pk_bf16_f32 v124, v122, v123
	v_and_b32_e32 v123, 0xffff0000, v121
	v_lshlrev_b32_e32 v122, 16, v121
	v_pk_add_f32 v[122:123], v[184:185], v[122:123] neg_lo:[0,1] neg_hi:[0,1]
	s_nop 0
	v_cvt_pk_bf16_f32 v125, v122, v123
	v_cvt_pk_bf16_f32 v122, v190, v191
	v_cvt_pk_bf16_f32 v123, v186, v187
	v_and_b32_e32 v127, 0xffff0000, v122
	v_lshlrev_b32_e32 v126, 16, v122
	v_and_b32_e32 v203, 0xffff0000, v123
	v_lshlrev_b32_e32 v202, 16, v123
	v_pk_add_f32 v[126:127], v[190:191], v[126:127] neg_lo:[0,1] neg_hi:[0,1]
	v_pk_add_f32 v[202:203], v[186:187], v[202:203] neg_lo:[0,1] neg_hi:[0,1]
	v_cvt_pk_bf16_f32 v126, v126, v127
	v_cvt_pk_bf16_f32 v127, v202, v203
	global_store_dwordx4 v[246:247], v[120:123], off
	global_store_dwordx4 v[250:251], v[124:127], off
	s_nop 0
	v_pk_mul_f32 v[122:123], v[190:191], v[190:191]
	v_pk_mul_f32 v[120:121], v[186:187], v[186:187]
	v_pk_fma_f32 v[122:123], v[188:189], v[188:189], v[122:123]
	v_pk_fma_f32 v[120:121], v[184:185], v[184:185], v[120:121]
	v_add_f32_e32 v122, v122, v123
	v_add_f32_e32 v120, v120, v122
	v_add_f32_e32 v120, v121, v120
	ds_bpermute_b32 v121, v200, v120
	s_waitcnt lgkmcnt(0)
	v_add_f32_e32 v122, v120, v121
	ds_bpermute_b32 v123, v199, v122
	v_lshl_add_u64 v[120:121], v[218:219], 2, s[16:17]
	s_and_saveexec_b64 s[18:19], vcc
	s_cbranch_execz .LBB0_3621
	s_waitcnt lgkmcnt(0)
	v_add_f32_e32 v122, v122, v123
	global_atomic_add_f32 v[120:121], v122, off
